# v40 with the 68 redundant back-to-back s_setprio 0 / s_setprio 1 pairs inside the GEMM MFMA blocks removed
# speedup vs baseline: 1.0059x; 1.0049x over previous
.LBB0_145:
	s_ashr_i32 s17, s16, 31
	s_lshl_b64 s[18:19], s[16:17], 19
	s_add_u32 s18, s36, s18
	s_addc_u32 s19, s37, s19
	s_and_b64 s[20:21], s[2:3], exec
	s_cselect_b32 s17, s19, s25
	s_cselect_b32 s50, s18, s24
	s_ashr_i32 s15, s14, 31
	s_lshl_b64 s[20:21], s[14:15], 19
	s_add_u32 s20, s34, s20
	s_addc_u32 s21, s35, s21
	s_and_b64 s[28:29], s[2:3], exec
	s_cselect_b32 s15, s21, s27
	s_cselect_b32 s51, s20, s26
	s_add_u32 s24, s24, 0x40080
	s_addc_u32 s25, s25, 0
	s_add_u32 s52, s26, 0x100
	s_addc_u32 s53, s27, 0
	s_mov_b32 s54, -2
	s_add_u32 s26, s24, 0xfffc0080
	s_addc_u32 s27, s25, -1
	s_add_i32 s55, 0, 0x10000
	s_cmp_eq_u32 s54, 12
	s_cselect_b32 s29, s17, s27
	s_cselect_b32 s28, s50, s26
	v_add_u32_e32 v140, s55, v143
	s_cselect_b32 s27, s15, s53
	s_cselect_b32 s26, s51, s52
	s_add_i32 s60, 0, 0x14000
	ds_read_b128 v[150:153], v140
	ds_read_b128 v[154:157], v140 offset:1024
	ds_read_b128 v[158:161], v140 offset:2048
	ds_read_b128 v[162:165], v140 offset:3072
	v_add_u32_e32 v140, s60, v143
	ds_read_b128 v[166:169], v140
	ds_read_b128 v[170:173], v140 offset:1024
	ds_read_b128 v[174:177], v140 offset:2048
	ds_read_b128 v[178:181], v140 offset:3072
	v_lshl_add_u64 v[140:141], s[24:25], 0, v[136:137]
	s_add_i32 m0, s40, 0xc000
	ds_read_b128 v[182:185], v148
	ds_read_b128 v[186:189], v148 offset:1024
	ds_read_b128 v[190:193], v148 offset:2048
	ds_read_b128 v[202:205], v148 offset:3072
	ds_read_b128 v[206:209], v148 offset:4096
	ds_read_b128 v[210:213], v148 offset:5120
	ds_read_b128 v[214:217], v148 offset:6144
	ds_read_b128 v[218:221], v148 offset:7168
	global_load_lds_dwordx4 v[140:141], off
	v_lshl_add_u64 v[140:141], s[24:25], 0, v[138:139]
	s_add_i32 m0, s40, 0xe000
	s_nop 0
	global_load_lds_dwordx4 v[140:141], off
	s_waitcnt lgkmcnt(0)
	s_barrier
	s_setprio 1
	s_waitcnt lgkmcnt(0)
	v_mfma_f32_16x16x32_bf16 v[126:129], v[150:153], v[182:185], 0
	v_mfma_f32_16x16x32_bf16 v[118:121], v[158:161], v[182:185], 0
	v_mfma_f32_16x16x32_bf16 v[110:113], v[150:153], v[190:193], 0
	v_mfma_f32_16x16x32_bf16 v[102:105], v[158:161], v[190:193], 0
	v_mfma_f32_16x16x32_bf16 v[92:95], v[150:153], v[206:209], 0
	v_mfma_f32_16x16x32_bf16 v[84:87], v[158:161], v[206:209], 0
	v_mfma_f32_16x16x32_bf16 v[76:79], v[150:153], v[214:217], 0
	v_mfma_f32_16x16x32_bf16 v[68:71], v[158:161], v[214:217], 0
	v_mfma_f32_16x16x32_bf16 v[126:129], v[154:157], v[186:189], v[126:129]
	v_mfma_f32_16x16x32_bf16 v[118:121], v[162:165], v[186:189], v[118:121]
	v_mfma_f32_16x16x32_bf16 v[110:113], v[154:157], v[202:205], v[110:113]
	v_mfma_f32_16x16x32_bf16 v[102:105], v[162:165], v[202:205], v[102:105]
	v_mfma_f32_16x16x32_bf16 v[92:95], v[154:157], v[210:213], v[92:95]
	v_mfma_f32_16x16x32_bf16 v[84:87], v[162:165], v[210:213], v[84:87]
	v_mfma_f32_16x16x32_bf16 v[76:79], v[154:157], v[218:221], v[76:79]
	v_mfma_f32_16x16x32_bf16 v[68:71], v[162:165], v[218:221], v[68:71]
	v_mfma_f32_16x16x32_bf16 v[122:125], v[166:169], v[182:185], 0
	v_mfma_f32_16x16x32_bf16 v[114:117], v[174:177], v[182:185], 0
	v_mfma_f32_16x16x32_bf16 v[106:109], v[166:169], v[190:193], 0
	v_mfma_f32_16x16x32_bf16 v[98:101], v[174:177], v[190:193], 0
	v_mfma_f32_16x16x32_bf16 v[88:91], v[166:169], v[206:209], 0
	v_mfma_f32_16x16x32_bf16 v[80:83], v[174:177], v[206:209], 0
	v_mfma_f32_16x16x32_bf16 v[72:75], v[166:169], v[214:217], 0
	v_mfma_f32_16x16x32_bf16 v[64:67], v[174:177], v[214:217], 0
	v_mfma_f32_16x16x32_bf16 v[122:125], v[170:173], v[186:189], v[122:125]
	v_mfma_f32_16x16x32_bf16 v[114:117], v[178:181], v[186:189], v[114:117]
	v_mfma_f32_16x16x32_bf16 v[106:109], v[170:173], v[202:205], v[106:109]
	v_mfma_f32_16x16x32_bf16 v[98:101], v[178:181], v[202:205], v[98:101]
	v_mfma_f32_16x16x32_bf16 v[88:91], v[170:173], v[210:213], v[88:91]
	v_mfma_f32_16x16x32_bf16 v[80:83], v[178:181], v[210:213], v[80:83]
	v_mfma_f32_16x16x32_bf16 v[72:75], v[170:173], v[218:221], v[72:75]
	v_mfma_f32_16x16x32_bf16 v[64:67], v[178:181], v[218:221], v[64:67]
	s_setprio 0
	s_barrier
	s_add_i32 s55, s55, s39
	v_lshl_add_u64 v[140:141], s[26:27], 0, v[96:97]
	s_mov_b32 m0, s55
	ds_read_b128 v[182:185], v148 offset:16384
	ds_read_b128 v[186:189], v148 offset:17408
	ds_read_b128 v[190:193], v148 offset:18432
	ds_read_b128 v[202:205], v148 offset:19456
	ds_read_b128 v[206:209], v148 offset:20480
	ds_read_b128 v[210:213], v148 offset:21504
	ds_read_b128 v[214:217], v148 offset:22528
	ds_read_b128 v[218:221], v148 offset:23552
	global_load_lds_dwordx4 v[140:141], off
	s_add_i32 m0, s55, 0x2000
	s_add_u32 s56, s26, 0x40000
	v_lshl_add_u64 v[194:195], s[26:27], 0, v[130:131]
	s_addc_u32 s57, s27, 0
	s_add_i32 s55, s60, s39
	global_load_lds_dwordx4 v[194:195], off
	v_lshl_add_u64 v[196:197], s[56:57], 0, v[96:97]
	s_mov_b32 m0, s55
	v_lshl_add_u64 v[198:199], s[28:29], 0, v[132:133]
	global_load_lds_dwordx4 v[196:197], off
	v_lshl_add_u64 v[196:197], s[56:57], 0, v[130:131]
	s_add_i32 m0, s55, 0x2000
	s_nop 0
	global_load_lds_dwordx4 v[196:197], off
	v_lshl_add_u64 v[196:197], s[28:29], 0, v[134:135]
	s_mov_b32 m0, s40
	s_nop 0
	global_load_lds_dwordx4 v[196:197], off
	s_mov_b32 m0, s41
	s_nop 0
	global_load_lds_dwordx4 v[198:199], off
	s_waitcnt lgkmcnt(0)
	s_barrier
	s_setprio 1
	s_waitcnt lgkmcnt(0)
	v_mfma_f32_16x16x32_bf16 v[60:63], v[150:153], v[182:185], 0
	v_mfma_f32_16x16x32_bf16 v[52:55], v[158:161], v[182:185], 0
	v_mfma_f32_16x16x32_bf16 v[44:47], v[150:153], v[190:193], 0
	v_mfma_f32_16x16x32_bf16 v[36:39], v[158:161], v[190:193], 0
	v_mfma_f32_16x16x32_bf16 v[28:31], v[150:153], v[206:209], 0
	v_mfma_f32_16x16x32_bf16 v[20:23], v[158:161], v[206:209], 0
	v_mfma_f32_16x16x32_bf16 v[12:15], v[150:153], v[214:217], 0
	v_mfma_f32_16x16x32_bf16 v[4:7], v[158:161], v[214:217], 0
	v_mfma_f32_16x16x32_bf16 v[60:63], v[154:157], v[186:189], v[60:63]
	v_mfma_f32_16x16x32_bf16 v[52:55], v[162:165], v[186:189], v[52:55]
	v_mfma_f32_16x16x32_bf16 v[44:47], v[154:157], v[202:205], v[44:47]
	v_mfma_f32_16x16x32_bf16 v[36:39], v[162:165], v[202:205], v[36:39]
	v_mfma_f32_16x16x32_bf16 v[28:31], v[154:157], v[210:213], v[28:31]
	v_mfma_f32_16x16x32_bf16 v[20:23], v[162:165], v[210:213], v[20:23]
	v_mfma_f32_16x16x32_bf16 v[12:15], v[154:157], v[218:221], v[12:15]
	v_mfma_f32_16x16x32_bf16 v[4:7], v[162:165], v[218:221], v[4:7]
	v_mfma_f32_16x16x32_bf16 v[56:59], v[166:169], v[182:185], 0
	v_mfma_f32_16x16x32_bf16 v[48:51], v[174:177], v[182:185], 0
	v_mfma_f32_16x16x32_bf16 v[40:43], v[166:169], v[190:193], 0
	v_mfma_f32_16x16x32_bf16 v[32:35], v[174:177], v[190:193], 0
	v_mfma_f32_16x16x32_bf16 v[24:27], v[166:169], v[206:209], 0
	v_mfma_f32_16x16x32_bf16 v[16:19], v[174:177], v[206:209], 0
	v_mfma_f32_16x16x32_bf16 v[8:11], v[166:169], v[214:217], 0
	v_mfma_f32_16x16x32_bf16 v[0:3], v[174:177], v[214:217], 0
	v_mfma_f32_16x16x32_bf16 v[56:59], v[170:173], v[186:189], v[56:59]
	v_mfma_f32_16x16x32_bf16 v[48:51], v[178:181], v[186:189], v[48:51]
	v_mfma_f32_16x16x32_bf16 v[40:43], v[170:173], v[202:205], v[40:43]
	v_mfma_f32_16x16x32_bf16 v[32:35], v[178:181], v[202:205], v[32:35]
	v_mfma_f32_16x16x32_bf16 v[24:27], v[170:173], v[210:213], v[24:27]
	v_mfma_f32_16x16x32_bf16 v[16:19], v[178:181], v[210:213], v[16:19]
	v_mfma_f32_16x16x32_bf16 v[8:11], v[170:173], v[218:221], v[8:11]
	v_mfma_f32_16x16x32_bf16 v[0:3], v[178:181], v[218:221], v[0:3]
	s_setprio 0
	s_barrier
	s_add_i32 s55, 0, 0x18000
	v_add_u32_e32 v149, s55, v143
	s_add_i32 s56, 0, 0x1c000
	ds_read_b128 v[150:153], v149
	ds_read_b128 v[154:157], v149 offset:1024
	ds_read_b128 v[158:161], v149 offset:2048
	ds_read_b128 v[162:165], v149 offset:3072
	v_add_u32_e32 v149, s56, v143
	ds_read_b128 v[166:169], v149
	ds_read_b128 v[170:173], v149 offset:1024
	ds_read_b128 v[174:177], v149 offset:2048
	ds_read_b128 v[178:181], v149 offset:3072
	s_add_u32 s28, s28, 0x40000
	s_addc_u32 s29, s29, 0
	s_mov_b32 m0, s42
	v_lshl_add_u64 v[200:201], s[28:29], 0, v[134:135]
	ds_read_b128 v[182:185], v148 offset:32768
	ds_read_b128 v[186:189], v148 offset:33792
	ds_read_b128 v[190:193], v148 offset:34816
	ds_read_b128 v[202:205], v148 offset:35840
	ds_read_b128 v[206:209], v148 offset:36864
	ds_read_b128 v[210:213], v148 offset:37888
	ds_read_b128 v[214:217], v148 offset:38912
	ds_read_b128 v[218:221], v148 offset:39936
	global_load_lds_dwordx4 v[200:201], off
	v_lshl_add_u64 v[200:201], s[28:29], 0, v[132:133]
	s_mov_b32 m0, s43
	s_nop 0
	global_load_lds_dwordx4 v[200:201], off
	s_waitcnt vmcnt(8)
	s_waitcnt lgkmcnt(0)
	s_barrier
	s_setprio 1
	s_waitcnt lgkmcnt(0)
	v_mfma_f32_16x16x32_bf16 v[126:129], v[150:153], v[182:185], v[126:129]
	v_mfma_f32_16x16x32_bf16 v[118:121], v[158:161], v[182:185], v[118:121]
	v_mfma_f32_16x16x32_bf16 v[110:113], v[150:153], v[190:193], v[110:113]
	v_mfma_f32_16x16x32_bf16 v[102:105], v[158:161], v[190:193], v[102:105]
	v_mfma_f32_16x16x32_bf16 v[92:95], v[150:153], v[206:209], v[92:95]
	v_mfma_f32_16x16x32_bf16 v[84:87], v[158:161], v[206:209], v[84:87]
	v_mfma_f32_16x16x32_bf16 v[76:79], v[150:153], v[214:217], v[76:79]
	v_mfma_f32_16x16x32_bf16 v[68:71], v[158:161], v[214:217], v[68:71]
	v_mfma_f32_16x16x32_bf16 v[126:129], v[154:157], v[186:189], v[126:129]
	v_mfma_f32_16x16x32_bf16 v[118:121], v[162:165], v[186:189], v[118:121]
	v_mfma_f32_16x16x32_bf16 v[110:113], v[154:157], v[202:205], v[110:113]
	v_mfma_f32_16x16x32_bf16 v[102:105], v[162:165], v[202:205], v[102:105]
	v_mfma_f32_16x16x32_bf16 v[92:95], v[154:157], v[210:213], v[92:95]
	v_mfma_f32_16x16x32_bf16 v[84:87], v[162:165], v[210:213], v[84:87]
	v_mfma_f32_16x16x32_bf16 v[76:79], v[154:157], v[218:221], v[76:79]
	v_mfma_f32_16x16x32_bf16 v[68:71], v[162:165], v[218:221], v[68:71]
	v_mfma_f32_16x16x32_bf16 v[122:125], v[166:169], v[182:185], v[122:125]
	v_mfma_f32_16x16x32_bf16 v[114:117], v[174:177], v[182:185], v[114:117]
	v_mfma_f32_16x16x32_bf16 v[106:109], v[166:169], v[190:193], v[106:109]
	v_mfma_f32_16x16x32_bf16 v[98:101], v[174:177], v[190:193], v[98:101]
	v_mfma_f32_16x16x32_bf16 v[88:91], v[166:169], v[206:209], v[88:91]
	v_mfma_f32_16x16x32_bf16 v[80:83], v[174:177], v[206:209], v[80:83]
	v_mfma_f32_16x16x32_bf16 v[72:75], v[166:169], v[214:217], v[72:75]
	v_mfma_f32_16x16x32_bf16 v[64:67], v[174:177], v[214:217], v[64:67]
	v_mfma_f32_16x16x32_bf16 v[122:125], v[170:173], v[186:189], v[122:125]
	v_mfma_f32_16x16x32_bf16 v[114:117], v[178:181], v[186:189], v[114:117]
	v_mfma_f32_16x16x32_bf16 v[106:109], v[170:173], v[202:205], v[106:109]
	v_mfma_f32_16x16x32_bf16 v[98:101], v[178:181], v[202:205], v[98:101]
	v_mfma_f32_16x16x32_bf16 v[88:91], v[170:173], v[210:213], v[88:91]
	v_mfma_f32_16x16x32_bf16 v[80:83], v[178:181], v[210:213], v[80:83]
	v_mfma_f32_16x16x32_bf16 v[72:75], v[170:173], v[218:221], v[72:75]
	v_mfma_f32_16x16x32_bf16 v[64:67], v[178:181], v[218:221], v[64:67]
	s_setprio 0
	s_barrier
	s_add_i32 s28, s55, s39
	v_lshl_add_u64 v[140:141], v[140:141], 0, s[64:65]
	s_mov_b32 m0, s28
	ds_read_b128 v[182:185], v148 offset:49152
	ds_read_b128 v[186:189], v148 offset:50176
	ds_read_b128 v[190:193], v148 offset:51200
	ds_read_b128 v[202:205], v148 offset:52224
	ds_read_b128 v[206:209], v148 offset:53248
	ds_read_b128 v[210:213], v148 offset:54272
	ds_read_b128 v[214:217], v148 offset:55296
	ds_read_b128 v[218:221], v148 offset:56320
	global_load_lds_dwordx4 v[140:141], off
	s_add_i32 m0, s28, 0x2000
	s_add_u32 s26, s26, 0x40080
	v_lshl_add_u64 v[140:141], v[194:195], 0, s[64:65]
	s_addc_u32 s27, s27, 0
	s_add_i32 s28, s56, s39
	global_load_lds_dwordx4 v[140:141], off
	v_lshl_add_u64 v[140:141], s[26:27], 0, v[96:97]
	s_mov_b32 m0, s28
	s_nop 0
	global_load_lds_dwordx4 v[140:141], off
	v_lshl_add_u64 v[140:141], s[26:27], 0, v[130:131]
	s_add_i32 m0, s28, 0x2000
	s_nop 0
	global_load_lds_dwordx4 v[140:141], off
	v_lshl_add_u64 v[140:141], v[196:197], 0, s[64:65]
	s_mov_b32 m0, s44
	s_nop 0
	global_load_lds_dwordx4 v[140:141], off
	v_lshl_add_u64 v[140:141], v[198:199], 0, s[64:65]
	s_mov_b32 m0, s45
	s_nop 0
	global_load_lds_dwordx4 v[140:141], off
	s_waitcnt vmcnt(8)
	s_waitcnt lgkmcnt(0)
	s_barrier
	s_setprio 1
	s_waitcnt lgkmcnt(0)
	v_mfma_f32_16x16x32_bf16 v[60:63], v[150:153], v[182:185], v[60:63]
	v_mfma_f32_16x16x32_bf16 v[52:55], v[158:161], v[182:185], v[52:55]
	v_mfma_f32_16x16x32_bf16 v[44:47], v[150:153], v[190:193], v[44:47]
	v_mfma_f32_16x16x32_bf16 v[36:39], v[158:161], v[190:193], v[36:39]
	v_mfma_f32_16x16x32_bf16 v[28:31], v[150:153], v[206:209], v[28:31]
	v_mfma_f32_16x16x32_bf16 v[20:23], v[158:161], v[206:209], v[20:23]
	v_mfma_f32_16x16x32_bf16 v[12:15], v[150:153], v[214:217], v[12:15]
	v_mfma_f32_16x16x32_bf16 v[4:7], v[158:161], v[214:217], v[4:7]
	v_mfma_f32_16x16x32_bf16 v[60:63], v[154:157], v[186:189], v[60:63]
	v_mfma_f32_16x16x32_bf16 v[52:55], v[162:165], v[186:189], v[52:55]
	v_mfma_f32_16x16x32_bf16 v[44:47], v[154:157], v[202:205], v[44:47]
	v_mfma_f32_16x16x32_bf16 v[36:39], v[162:165], v[202:205], v[36:39]
	v_mfma_f32_16x16x32_bf16 v[28:31], v[154:157], v[210:213], v[28:31]
	v_mfma_f32_16x16x32_bf16 v[20:23], v[162:165], v[210:213], v[20:23]
	v_mfma_f32_16x16x32_bf16 v[12:15], v[154:157], v[218:221], v[12:15]
	v_mfma_f32_16x16x32_bf16 v[4:7], v[162:165], v[218:221], v[4:7]
	v_mfma_f32_16x16x32_bf16 v[56:59], v[166:169], v[182:185], v[56:59]
	v_mfma_f32_16x16x32_bf16 v[48:51], v[174:177], v[182:185], v[48:51]
	v_mfma_f32_16x16x32_bf16 v[40:43], v[166:169], v[190:193], v[40:43]
	v_mfma_f32_16x16x32_bf16 v[32:35], v[174:177], v[190:193], v[32:35]
	v_mfma_f32_16x16x32_bf16 v[24:27], v[166:169], v[206:209], v[24:27]
	v_mfma_f32_16x16x32_bf16 v[16:19], v[174:177], v[206:209], v[16:19]
	v_mfma_f32_16x16x32_bf16 v[8:11], v[166:169], v[214:217], v[8:11]
	v_mfma_f32_16x16x32_bf16 v[0:3], v[174:177], v[214:217], v[0:3]
	v_mfma_f32_16x16x32_bf16 v[56:59], v[170:173], v[186:189], v[56:59]
	v_mfma_f32_16x16x32_bf16 v[48:51], v[178:181], v[186:189], v[48:51]
	v_mfma_f32_16x16x32_bf16 v[40:43], v[170:173], v[202:205], v[40:43]
	v_mfma_f32_16x16x32_bf16 v[32:35], v[178:181], v[202:205], v[32:35]
	v_mfma_f32_16x16x32_bf16 v[24:27], v[170:173], v[210:213], v[24:27]
	v_mfma_f32_16x16x32_bf16 v[16:19], v[178:181], v[210:213], v[16:19]
	v_mfma_f32_16x16x32_bf16 v[8:11], v[170:173], v[218:221], v[8:11]
	v_mfma_f32_16x16x32_bf16 v[0:3], v[178:181], v[218:221], v[0:3]
	s_setprio 0
	s_barrier
	s_add_i32 s54, s54, 2
	s_add_u32 s24, s24, 0x100
	s_addc_u32 s25, s25, 0
	s_add_u32 s52, s52, 0x100
	s_addc_u32 s53, s53, 0
	s_cmp_gt_u32 s54, 13
	s_cbranch_scc1 .Lgu_kdone
.LBB0_146:
	s_add_u32 s26, s24, 0xfffc0080
	s_addc_u32 s27, s25, -1
	s_add_i32 s55, 0, 0x10000
	s_cmp_eq_u32 s54, 12
	s_cselect_b32 s29, s17, s27
	s_cselect_b32 s28, s50, s26
	v_add_u32_e32 v140, s55, v143
	s_cselect_b32 s27, s15, s53
	s_cselect_b32 s26, s51, s52
	s_add_i32 s60, 0, 0x14000
	ds_read_b128 v[150:153], v140
	ds_read_b128 v[154:157], v140 offset:1024
	ds_read_b128 v[158:161], v140 offset:2048
	ds_read_b128 v[162:165], v140 offset:3072
	v_add_u32_e32 v140, s60, v143
	ds_read_b128 v[166:169], v140
	ds_read_b128 v[170:173], v140 offset:1024
	ds_read_b128 v[174:177], v140 offset:2048
	ds_read_b128 v[178:181], v140 offset:3072
	v_lshl_add_u64 v[140:141], s[24:25], 0, v[136:137]
	s_add_i32 m0, s40, 0xc000
	ds_read_b128 v[182:185], v148
	ds_read_b128 v[186:189], v148 offset:1024
	ds_read_b128 v[190:193], v148 offset:2048
	ds_read_b128 v[202:205], v148 offset:3072
	ds_read_b128 v[206:209], v148 offset:4096
	ds_read_b128 v[210:213], v148 offset:5120
	ds_read_b128 v[214:217], v148 offset:6144
	ds_read_b128 v[218:221], v148 offset:7168
	global_load_lds_dwordx4 v[140:141], off
	v_lshl_add_u64 v[140:141], s[24:25], 0, v[138:139]
	s_add_i32 m0, s40, 0xe000
	s_nop 0
	global_load_lds_dwordx4 v[140:141], off
	s_waitcnt vmcnt(8)
	s_waitcnt lgkmcnt(0)
	s_barrier
	s_setprio 1
	s_waitcnt lgkmcnt(0)
	v_mfma_f32_16x16x32_bf16 v[126:129], v[150:153], v[182:185], v[126:129]
	v_mfma_f32_16x16x32_bf16 v[118:121], v[158:161], v[182:185], v[118:121]
	v_mfma_f32_16x16x32_bf16 v[110:113], v[150:153], v[190:193], v[110:113]
	v_mfma_f32_16x16x32_bf16 v[102:105], v[158:161], v[190:193], v[102:105]
	v_mfma_f32_16x16x32_bf16 v[92:95], v[150:153], v[206:209], v[92:95]
	v_mfma_f32_16x16x32_bf16 v[84:87], v[158:161], v[206:209], v[84:87]
	v_mfma_f32_16x16x32_bf16 v[76:79], v[150:153], v[214:217], v[76:79]
	v_mfma_f32_16x16x32_bf16 v[68:71], v[158:161], v[214:217], v[68:71]
	v_mfma_f32_16x16x32_bf16 v[126:129], v[154:157], v[186:189], v[126:129]
	v_mfma_f32_16x16x32_bf16 v[118:121], v[162:165], v[186:189], v[118:121]
	v_mfma_f32_16x16x32_bf16 v[110:113], v[154:157], v[202:205], v[110:113]
	v_mfma_f32_16x16x32_bf16 v[102:105], v[162:165], v[202:205], v[102:105]
	v_mfma_f32_16x16x32_bf16 v[92:95], v[154:157], v[210:213], v[92:95]
	v_mfma_f32_16x16x32_bf16 v[84:87], v[162:165], v[210:213], v[84:87]
	v_mfma_f32_16x16x32_bf16 v[76:79], v[154:157], v[218:221], v[76:79]
	v_mfma_f32_16x16x32_bf16 v[68:71], v[162:165], v[218:221], v[68:71]
	v_mfma_f32_16x16x32_bf16 v[122:125], v[166:169], v[182:185], v[122:125]
	v_mfma_f32_16x16x32_bf16 v[114:117], v[174:177], v[182:185], v[114:117]
	v_mfma_f32_16x16x32_bf16 v[106:109], v[166:169], v[190:193], v[106:109]
	v_mfma_f32_16x16x32_bf16 v[98:101], v[174:177], v[190:193], v[98:101]
	v_mfma_f32_16x16x32_bf16 v[88:91], v[166:169], v[206:209], v[88:91]
	v_mfma_f32_16x16x32_bf16 v[80:83], v[174:177], v[206:209], v[80:83]
	v_mfma_f32_16x16x32_bf16 v[72:75], v[166:169], v[214:217], v[72:75]
	v_mfma_f32_16x16x32_bf16 v[64:67], v[174:177], v[214:217], v[64:67]
	v_mfma_f32_16x16x32_bf16 v[122:125], v[170:173], v[186:189], v[122:125]
	v_mfma_f32_16x16x32_bf16 v[114:117], v[178:181], v[186:189], v[114:117]
	v_mfma_f32_16x16x32_bf16 v[106:109], v[170:173], v[202:205], v[106:109]
	v_mfma_f32_16x16x32_bf16 v[98:101], v[178:181], v[202:205], v[98:101]
	v_mfma_f32_16x16x32_bf16 v[88:91], v[170:173], v[210:213], v[88:91]
	v_mfma_f32_16x16x32_bf16 v[80:83], v[178:181], v[210:213], v[80:83]
	v_mfma_f32_16x16x32_bf16 v[72:75], v[170:173], v[218:221], v[72:75]
	v_mfma_f32_16x16x32_bf16 v[64:67], v[178:181], v[218:221], v[64:67]
	s_setprio 0
	s_barrier
	s_add_i32 s55, s55, s39
	v_lshl_add_u64 v[140:141], s[26:27], 0, v[96:97]
	s_mov_b32 m0, s55
	ds_read_b128 v[182:185], v148 offset:16384
	ds_read_b128 v[186:189], v148 offset:17408
	ds_read_b128 v[190:193], v148 offset:18432
	ds_read_b128 v[202:205], v148 offset:19456
	ds_read_b128 v[206:209], v148 offset:20480
	ds_read_b128 v[210:213], v148 offset:21504
	ds_read_b128 v[214:217], v148 offset:22528
	ds_read_b128 v[218:221], v148 offset:23552
	global_load_lds_dwordx4 v[140:141], off
	s_add_i32 m0, s55, 0x2000
	s_add_u32 s56, s26, 0x40000
	v_lshl_add_u64 v[194:195], s[26:27], 0, v[130:131]
	s_addc_u32 s57, s27, 0
	s_add_i32 s55, s60, s39
	global_load_lds_dwordx4 v[194:195], off
	v_lshl_add_u64 v[196:197], s[56:57], 0, v[96:97]
	s_mov_b32 m0, s55
	v_lshl_add_u64 v[198:199], s[28:29], 0, v[132:133]
	global_load_lds_dwordx4 v[196:197], off
	v_lshl_add_u64 v[196:197], s[56:57], 0, v[130:131]
	s_add_i32 m0, s55, 0x2000
	s_nop 0
	global_load_lds_dwordx4 v[196:197], off
	v_lshl_add_u64 v[196:197], s[28:29], 0, v[134:135]
	s_mov_b32 m0, s40
	s_nop 0
	global_load_lds_dwordx4 v[196:197], off
	s_mov_b32 m0, s41
	s_nop 0
	global_load_lds_dwordx4 v[198:199], off
	s_waitcnt vmcnt(8)
	s_waitcnt lgkmcnt(0)
	s_barrier
	s_setprio 1
	s_waitcnt lgkmcnt(0)
	v_mfma_f32_16x16x32_bf16 v[60:63], v[150:153], v[182:185], v[60:63]
	v_mfma_f32_16x16x32_bf16 v[52:55], v[158:161], v[182:185], v[52:55]
	v_mfma_f32_16x16x32_bf16 v[44:47], v[150:153], v[190:193], v[44:47]
	v_mfma_f32_16x16x32_bf16 v[36:39], v[158:161], v[190:193], v[36:39]
	v_mfma_f32_16x16x32_bf16 v[28:31], v[150:153], v[206:209], v[28:31]
	v_mfma_f32_16x16x32_bf16 v[20:23], v[158:161], v[206:209], v[20:23]
	v_mfma_f32_16x16x32_bf16 v[12:15], v[150:153], v[214:217], v[12:15]
	v_mfma_f32_16x16x32_bf16 v[4:7], v[158:161], v[214:217], v[4:7]
	v_mfma_f32_16x16x32_bf16 v[60:63], v[154:157], v[186:189], v[60:63]
	v_mfma_f32_16x16x32_bf16 v[52:55], v[162:165], v[186:189], v[52:55]
	v_mfma_f32_16x16x32_bf16 v[44:47], v[154:157], v[202:205], v[44:47]
	v_mfma_f32_16x16x32_bf16 v[36:39], v[162:165], v[202:205], v[36:39]
	v_mfma_f32_16x16x32_bf16 v[28:31], v[154:157], v[210:213], v[28:31]
	v_mfma_f32_16x16x32_bf16 v[20:23], v[162:165], v[210:213], v[20:23]
	v_mfma_f32_16x16x32_bf16 v[12:15], v[154:157], v[218:221], v[12:15]
	v_mfma_f32_16x16x32_bf16 v[4:7], v[162:165], v[218:221], v[4:7]
	v_mfma_f32_16x16x32_bf16 v[56:59], v[166:169], v[182:185], v[56:59]
	v_mfma_f32_16x16x32_bf16 v[48:51], v[174:177], v[182:185], v[48:51]
	v_mfma_f32_16x16x32_bf16 v[40:43], v[166:169], v[190:193], v[40:43]
	v_mfma_f32_16x16x32_bf16 v[32:35], v[174:177], v[190:193], v[32:35]
	v_mfma_f32_16x16x32_bf16 v[24:27], v[166:169], v[206:209], v[24:27]
	v_mfma_f32_16x16x32_bf16 v[16:19], v[174:177], v[206:209], v[16:19]
	v_mfma_f32_16x16x32_bf16 v[8:11], v[166:169], v[214:217], v[8:11]
	v_mfma_f32_16x16x32_bf16 v[0:3], v[174:177], v[214:217], v[0:3]
	v_mfma_f32_16x16x32_bf16 v[56:59], v[170:173], v[186:189], v[56:59]
	v_mfma_f32_16x16x32_bf16 v[48:51], v[178:181], v[186:189], v[48:51]
	v_mfma_f32_16x16x32_bf16 v[40:43], v[170:173], v[202:205], v[40:43]
	v_mfma_f32_16x16x32_bf16 v[32:35], v[178:181], v[202:205], v[32:35]
	v_mfma_f32_16x16x32_bf16 v[24:27], v[170:173], v[210:213], v[24:27]
	v_mfma_f32_16x16x32_bf16 v[16:19], v[178:181], v[210:213], v[16:19]
	v_mfma_f32_16x16x32_bf16 v[8:11], v[170:173], v[218:221], v[8:11]
	v_mfma_f32_16x16x32_bf16 v[0:3], v[178:181], v[218:221], v[0:3]
	s_setprio 0
	s_barrier
	s_add_i32 s55, 0, 0x18000
	v_add_u32_e32 v149, s55, v143
	s_add_i32 s56, 0, 0x1c000
	ds_read_b128 v[150:153], v149
	ds_read_b128 v[154:157], v149 offset:1024
	ds_read_b128 v[158:161], v149 offset:2048
	ds_read_b128 v[162:165], v149 offset:3072
	v_add_u32_e32 v149, s56, v143
	ds_read_b128 v[166:169], v149
	ds_read_b128 v[170:173], v149 offset:1024
	ds_read_b128 v[174:177], v149 offset:2048
	ds_read_b128 v[178:181], v149 offset:3072
	s_add_u32 s28, s28, 0x40000
	s_addc_u32 s29, s29, 0
	s_mov_b32 m0, s42
	v_lshl_add_u64 v[200:201], s[28:29], 0, v[134:135]
	ds_read_b128 v[182:185], v148 offset:32768
	ds_read_b128 v[186:189], v148 offset:33792
	ds_read_b128 v[190:193], v148 offset:34816
	ds_read_b128 v[202:205], v148 offset:35840
	ds_read_b128 v[206:209], v148 offset:36864
	ds_read_b128 v[210:213], v148 offset:37888
	ds_read_b128 v[214:217], v148 offset:38912
	ds_read_b128 v[218:221], v148 offset:39936
	global_load_lds_dwordx4 v[200:201], off
	v_lshl_add_u64 v[200:201], s[28:29], 0, v[132:133]
	s_mov_b32 m0, s43
	s_nop 0
	global_load_lds_dwordx4 v[200:201], off
	s_waitcnt vmcnt(8)
	s_waitcnt lgkmcnt(0)
	s_barrier
	s_setprio 1
	s_waitcnt lgkmcnt(0)
	v_mfma_f32_16x16x32_bf16 v[126:129], v[150:153], v[182:185], v[126:129]
	v_mfma_f32_16x16x32_bf16 v[118:121], v[158:161], v[182:185], v[118:121]
	v_mfma_f32_16x16x32_bf16 v[110:113], v[150:153], v[190:193], v[110:113]
	v_mfma_f32_16x16x32_bf16 v[102:105], v[158:161], v[190:193], v[102:105]
	v_mfma_f32_16x16x32_bf16 v[92:95], v[150:153], v[206:209], v[92:95]
	v_mfma_f32_16x16x32_bf16 v[84:87], v[158:161], v[206:209], v[84:87]
	v_mfma_f32_16x16x32_bf16 v[76:79], v[150:153], v[214:217], v[76:79]
	v_mfma_f32_16x16x32_bf16 v[68:71], v[158:161], v[214:217], v[68:71]
	v_mfma_f32_16x16x32_bf16 v[126:129], v[154:157], v[186:189], v[126:129]
	v_mfma_f32_16x16x32_bf16 v[118:121], v[162:165], v[186:189], v[118:121]
	v_mfma_f32_16x16x32_bf16 v[110:113], v[154:157], v[202:205], v[110:113]
	v_mfma_f32_16x16x32_bf16 v[102:105], v[162:165], v[202:205], v[102:105]
	v_mfma_f32_16x16x32_bf16 v[92:95], v[154:157], v[210:213], v[92:95]
	v_mfma_f32_16x16x32_bf16 v[84:87], v[162:165], v[210:213], v[84:87]
	v_mfma_f32_16x16x32_bf16 v[76:79], v[154:157], v[218:221], v[76:79]
	v_mfma_f32_16x16x32_bf16 v[68:71], v[162:165], v[218:221], v[68:71]
	v_mfma_f32_16x16x32_bf16 v[122:125], v[166:169], v[182:185], v[122:125]
	v_mfma_f32_16x16x32_bf16 v[114:117], v[174:177], v[182:185], v[114:117]
	v_mfma_f32_16x16x32_bf16 v[106:109], v[166:169], v[190:193], v[106:109]
	v_mfma_f32_16x16x32_bf16 v[98:101], v[174:177], v[190:193], v[98:101]
	v_mfma_f32_16x16x32_bf16 v[88:91], v[166:169], v[206:209], v[88:91]
	v_mfma_f32_16x16x32_bf16 v[80:83], v[174:177], v[206:209], v[80:83]
	v_mfma_f32_16x16x32_bf16 v[72:75], v[166:169], v[214:217], v[72:75]
	v_mfma_f32_16x16x32_bf16 v[64:67], v[174:177], v[214:217], v[64:67]
	v_mfma_f32_16x16x32_bf16 v[122:125], v[170:173], v[186:189], v[122:125]
	v_mfma_f32_16x16x32_bf16 v[114:117], v[178:181], v[186:189], v[114:117]
	v_mfma_f32_16x16x32_bf16 v[106:109], v[170:173], v[202:205], v[106:109]
	v_mfma_f32_16x16x32_bf16 v[98:101], v[178:181], v[202:205], v[98:101]
	v_mfma_f32_16x16x32_bf16 v[88:91], v[170:173], v[210:213], v[88:91]
	v_mfma_f32_16x16x32_bf16 v[80:83], v[178:181], v[210:213], v[80:83]
	v_mfma_f32_16x16x32_bf16 v[72:75], v[170:173], v[218:221], v[72:75]
	v_mfma_f32_16x16x32_bf16 v[64:67], v[178:181], v[218:221], v[64:67]
	s_setprio 0
	s_barrier
	s_add_i32 s28, s55, s39
	v_lshl_add_u64 v[140:141], v[140:141], 0, s[64:65]
	s_mov_b32 m0, s28
	ds_read_b128 v[182:185], v148 offset:49152
	ds_read_b128 v[186:189], v148 offset:50176
	ds_read_b128 v[190:193], v148 offset:51200
	ds_read_b128 v[202:205], v148 offset:52224
	ds_read_b128 v[206:209], v148 offset:53248
	ds_read_b128 v[210:213], v148 offset:54272
	ds_read_b128 v[214:217], v148 offset:55296
	ds_read_b128 v[218:221], v148 offset:56320
	global_load_lds_dwordx4 v[140:141], off
	s_add_i32 m0, s28, 0x2000
	s_add_u32 s26, s26, 0x40080
	v_lshl_add_u64 v[140:141], v[194:195], 0, s[64:65]
	s_addc_u32 s27, s27, 0
	s_add_i32 s28, s56, s39
	global_load_lds_dwordx4 v[140:141], off
	v_lshl_add_u64 v[140:141], s[26:27], 0, v[96:97]
	s_mov_b32 m0, s28
	s_nop 0
	global_load_lds_dwordx4 v[140:141], off
	v_lshl_add_u64 v[140:141], s[26:27], 0, v[130:131]
	s_add_i32 m0, s28, 0x2000
	s_nop 0
	global_load_lds_dwordx4 v[140:141], off
	v_lshl_add_u64 v[140:141], v[196:197], 0, s[64:65]
	s_mov_b32 m0, s44
	s_nop 0
	global_load_lds_dwordx4 v[140:141], off
	v_lshl_add_u64 v[140:141], v[198:199], 0, s[64:65]
	s_mov_b32 m0, s45
	s_nop 0
	global_load_lds_dwordx4 v[140:141], off
	s_waitcnt vmcnt(8)
	s_waitcnt lgkmcnt(0)
	s_barrier
	s_setprio 1
	s_waitcnt lgkmcnt(0)
	v_mfma_f32_16x16x32_bf16 v[60:63], v[150:153], v[182:185], v[60:63]
	v_mfma_f32_16x16x32_bf16 v[52:55], v[158:161], v[182:185], v[52:55]
	v_mfma_f32_16x16x32_bf16 v[44:47], v[150:153], v[190:193], v[44:47]
	v_mfma_f32_16x16x32_bf16 v[36:39], v[158:161], v[190:193], v[36:39]
	v_mfma_f32_16x16x32_bf16 v[28:31], v[150:153], v[206:209], v[28:31]
	v_mfma_f32_16x16x32_bf16 v[20:23], v[158:161], v[206:209], v[20:23]
	v_mfma_f32_16x16x32_bf16 v[12:15], v[150:153], v[214:217], v[12:15]
	v_mfma_f32_16x16x32_bf16 v[4:7], v[158:161], v[214:217], v[4:7]
	v_mfma_f32_16x16x32_bf16 v[60:63], v[154:157], v[186:189], v[60:63]
	v_mfma_f32_16x16x32_bf16 v[52:55], v[162:165], v[186:189], v[52:55]
	v_mfma_f32_16x16x32_bf16 v[44:47], v[154:157], v[202:205], v[44:47]
	v_mfma_f32_16x16x32_bf16 v[36:39], v[162:165], v[202:205], v[36:39]
	v_mfma_f32_16x16x32_bf16 v[28:31], v[154:157], v[210:213], v[28:31]
	v_mfma_f32_16x16x32_bf16 v[20:23], v[162:165], v[210:213], v[20:23]
	v_mfma_f32_16x16x32_bf16 v[12:15], v[154:157], v[218:221], v[12:15]
	v_mfma_f32_16x16x32_bf16 v[4:7], v[162:165], v[218:221], v[4:7]
	v_mfma_f32_16x16x32_bf16 v[56:59], v[166:169], v[182:185], v[56:59]
	v_mfma_f32_16x16x32_bf16 v[48:51], v[174:177], v[182:185], v[48:51]
	v_mfma_f32_16x16x32_bf16 v[40:43], v[166:169], v[190:193], v[40:43]
	v_mfma_f32_16x16x32_bf16 v[32:35], v[174:177], v[190:193], v[32:35]
	v_mfma_f32_16x16x32_bf16 v[24:27], v[166:169], v[206:209], v[24:27]
	v_mfma_f32_16x16x32_bf16 v[16:19], v[174:177], v[206:209], v[16:19]
	v_mfma_f32_16x16x32_bf16 v[8:11], v[166:169], v[214:217], v[8:11]
	v_mfma_f32_16x16x32_bf16 v[0:3], v[174:177], v[214:217], v[0:3]
	v_mfma_f32_16x16x32_bf16 v[56:59], v[170:173], v[186:189], v[56:59]
	v_mfma_f32_16x16x32_bf16 v[48:51], v[178:181], v[186:189], v[48:51]
	v_mfma_f32_16x16x32_bf16 v[40:43], v[170:173], v[202:205], v[40:43]
	v_mfma_f32_16x16x32_bf16 v[32:35], v[178:181], v[202:205], v[32:35]
	v_mfma_f32_16x16x32_bf16 v[24:27], v[170:173], v[210:213], v[24:27]
	v_mfma_f32_16x16x32_bf16 v[16:19], v[178:181], v[210:213], v[16:19]
	v_mfma_f32_16x16x32_bf16 v[8:11], v[170:173], v[218:221], v[8:11]
	v_mfma_f32_16x16x32_bf16 v[0:3], v[178:181], v[218:221], v[0:3]
	s_setprio 0
	s_barrier
	s_add_i32 s54, s54, 2
	s_add_u32 s24, s24, 0x100
	s_addc_u32 s25, s25, 0
	s_add_u32 s52, s52, 0x100
	s_addc_u32 s53, s53, 0
	s_cmp_gt_u32 s54, 13
	s_cbranch_scc0 .LBB0_146

.LBB0_338:
	s_add_u32 s53, s28, 0x100
	s_addc_u32 s54, s29, 0
	s_mov_b32 s55, -2
	s_add_u32 s6, s26, 0x100
	s_addc_u32 s7, s27, 0
	s_add_i32 s56, 0, 0x10000
	s_cmp_eq_u32 s55, 40
	s_cselect_b32 s31, s23, s7
	s_cselect_b32 s30, s22, s6
	s_cselect_b32 s29, s25, s54
	s_cselect_b32 s28, s24, s53
	s_add_i32 s57, 0, 0x14000
	v_add_u32_e32 v106, s56, v254
	v_add_u32_e32 v150, s57, v254
	ds_read_b128 v[72:75], v106
	ds_read_b128 v[84:87], v106 offset:1024
	ds_read_b128 v[98:101], v106 offset:2048
	ds_read_b128 v[106:109], v106 offset:3072
	ds_read_b128 v[122:125], v150
	ds_read_b128 v[126:129], v150 offset:1024
	ds_read_b128 v[142:145], v150 offset:2048
	ds_read_b128 v[150:153], v150 offset:3072
	v_lshl_add_u64 v[194:195], s[26:27], 0, v[208:209]
	s_add_i32 m0, s40, 0xc000
	ds_read_b128 v[162:165], v198
	ds_read_b128 v[166:169], v198 offset:1024
	ds_read_b128 v[170:173], v198 offset:2048
	ds_read_b128 v[174:177], v198 offset:3072
	ds_read_b128 v[178:181], v198 offset:4096
	ds_read_b128 v[182:185], v198 offset:5120
	ds_read_b128 v[186:189], v198 offset:6144
	ds_read_b128 v[190:193], v198 offset:7168
	global_load_lds_dwordx4 v[194:195], off
	v_lshl_add_u64 v[194:195], s[26:27], 0, v[210:211]
	s_add_i32 m0, s40, 0xe000
	s_nop 0
	global_load_lds_dwordx4 v[194:195], off
	s_waitcnt vmcnt(8)
	s_waitcnt lgkmcnt(0)
	s_barrier
	s_setprio 1
	s_waitcnt lgkmcnt(0)
	v_mfma_f32_16x16x32_bf16 v[158:161], v[72:75], v[162:165], 0
	v_mfma_f32_16x16x32_bf16 v[154:157], v[98:101], v[162:165], 0
	v_mfma_f32_16x16x32_bf16 v[134:137], v[72:75], v[170:173], 0
	v_mfma_f32_16x16x32_bf16 v[130:133], v[98:101], v[170:173], 0
	v_mfma_f32_16x16x32_bf16 v[110:113], v[72:75], v[178:181], 0
	v_mfma_f32_16x16x32_bf16 v[102:105], v[98:101], v[178:181], 0
	v_mfma_f32_16x16x32_bf16 v[80:83], v[72:75], v[186:189], 0
	v_mfma_f32_16x16x32_bf16 v[76:79], v[98:101], v[186:189], 0
	v_mfma_f32_16x16x32_bf16 v[158:161], v[84:87], v[166:169], v[158:161]
	v_mfma_f32_16x16x32_bf16 v[154:157], v[106:109], v[166:169], v[154:157]
	v_mfma_f32_16x16x32_bf16 v[134:137], v[84:87], v[174:177], v[134:137]
	v_mfma_f32_16x16x32_bf16 v[130:133], v[106:109], v[174:177], v[130:133]
	v_mfma_f32_16x16x32_bf16 v[110:113], v[84:87], v[182:185], v[110:113]
	v_mfma_f32_16x16x32_bf16 v[102:105], v[106:109], v[182:185], v[102:105]
	v_mfma_f32_16x16x32_bf16 v[80:83], v[84:87], v[190:193], v[80:83]
	v_mfma_f32_16x16x32_bf16 v[76:79], v[106:109], v[190:193], v[76:79]
	v_mfma_f32_16x16x32_bf16 v[146:149], v[122:125], v[162:165], 0
	v_mfma_f32_16x16x32_bf16 v[138:141], v[142:145], v[162:165], 0
	v_mfma_f32_16x16x32_bf16 v[118:121], v[122:125], v[170:173], 0
	v_mfma_f32_16x16x32_bf16 v[114:117], v[142:145], v[170:173], 0
	v_mfma_f32_16x16x32_bf16 v[92:95], v[122:125], v[178:181], 0
	v_mfma_f32_16x16x32_bf16 v[88:91], v[142:145], v[178:181], 0
	v_mfma_f32_16x16x32_bf16 v[68:71], v[122:125], v[186:189], 0
	v_mfma_f32_16x16x32_bf16 v[64:67], v[142:145], v[186:189], 0
	v_mfma_f32_16x16x32_bf16 v[146:149], v[126:129], v[166:169], v[146:149]
	v_mfma_f32_16x16x32_bf16 v[138:141], v[150:153], v[166:169], v[138:141]
	v_mfma_f32_16x16x32_bf16 v[118:121], v[126:129], v[174:177], v[118:121]
	v_mfma_f32_16x16x32_bf16 v[114:117], v[150:153], v[174:177], v[114:117]
	v_mfma_f32_16x16x32_bf16 v[92:95], v[126:129], v[182:185], v[92:95]
	v_mfma_f32_16x16x32_bf16 v[88:91], v[150:153], v[182:185], v[88:91]
	v_mfma_f32_16x16x32_bf16 v[68:71], v[126:129], v[190:193], v[68:71]
	v_mfma_f32_16x16x32_bf16 v[64:67], v[150:153], v[190:193], v[64:67]
	s_setprio 0
	s_barrier
	s_add_i32 s26, s56, s39
	v_lshl_add_u64 v[194:195], s[28:29], 0, v[96:97]
	s_mov_b32 m0, s26
	ds_read_b128 v[162:165], v198 offset:16384
	ds_read_b128 v[166:169], v198 offset:17408
	ds_read_b128 v[170:173], v198 offset:18432
	ds_read_b128 v[174:177], v198 offset:19456
	ds_read_b128 v[178:181], v198 offset:20480
	ds_read_b128 v[182:185], v198 offset:21504
	ds_read_b128 v[186:189], v198 offset:22528
	ds_read_b128 v[190:193], v198 offset:23552
	global_load_lds_dwordx4 v[194:195], off
	s_add_i32 m0, s26, 0x2000
	s_add_u32 s26, s28, 0xb0000
	v_lshl_add_u64 v[196:197], s[28:29], 0, v[206:207]
	s_addc_u32 s27, s29, 0
	s_add_i32 s56, s57, s39
	global_load_lds_dwordx4 v[196:197], off
	v_lshl_add_u64 v[200:201], s[26:27], 0, v[96:97]
	s_mov_b32 m0, s56
	v_lshl_add_u64 v[212:213], s[30:31], 0, v[204:205]
	global_load_lds_dwordx4 v[200:201], off
	v_lshl_add_u64 v[200:201], s[26:27], 0, v[206:207]
	s_add_i32 m0, s56, 0x2000
	s_nop 0
	global_load_lds_dwordx4 v[200:201], off
	v_lshl_add_u64 v[200:201], s[30:31], 0, v[202:203]
	s_mov_b32 m0, s40
	s_nop 0
	global_load_lds_dwordx4 v[200:201], off
	s_mov_b32 m0, s41
	s_nop 0
	global_load_lds_dwordx4 v[212:213], off
	s_waitcnt vmcnt(8)
	s_waitcnt lgkmcnt(0)
	s_barrier
	s_setprio 1
	s_waitcnt lgkmcnt(0)
	v_mfma_f32_16x16x32_bf16 v[60:63], v[72:75], v[162:165], 0
	v_mfma_f32_16x16x32_bf16 v[56:59], v[98:101], v[162:165], 0
	v_mfma_f32_16x16x32_bf16 v[44:47], v[72:75], v[170:173], 0
	v_mfma_f32_16x16x32_bf16 v[40:43], v[98:101], v[170:173], 0
	v_mfma_f32_16x16x32_bf16 v[28:31], v[72:75], v[178:181], 0
	v_mfma_f32_16x16x32_bf16 v[24:27], v[98:101], v[178:181], 0
	v_mfma_f32_16x16x32_bf16 v[12:15], v[72:75], v[186:189], 0
	v_mfma_f32_16x16x32_bf16 v[8:11], v[98:101], v[186:189], 0
	v_mfma_f32_16x16x32_bf16 v[60:63], v[84:87], v[166:169], v[60:63]
	v_mfma_f32_16x16x32_bf16 v[56:59], v[106:109], v[166:169], v[56:59]
	v_mfma_f32_16x16x32_bf16 v[44:47], v[84:87], v[174:177], v[44:47]
	v_mfma_f32_16x16x32_bf16 v[40:43], v[106:109], v[174:177], v[40:43]
	v_mfma_f32_16x16x32_bf16 v[28:31], v[84:87], v[182:185], v[28:31]
	v_mfma_f32_16x16x32_bf16 v[24:27], v[106:109], v[182:185], v[24:27]
	v_mfma_f32_16x16x32_bf16 v[12:15], v[84:87], v[190:193], v[12:15]
	v_mfma_f32_16x16x32_bf16 v[8:11], v[106:109], v[190:193], v[8:11]
	v_mfma_f32_16x16x32_bf16 v[52:55], v[122:125], v[162:165], 0
	v_mfma_f32_16x16x32_bf16 v[48:51], v[142:145], v[162:165], 0
	v_mfma_f32_16x16x32_bf16 v[36:39], v[122:125], v[170:173], 0
	v_mfma_f32_16x16x32_bf16 v[32:35], v[142:145], v[170:173], 0
	v_mfma_f32_16x16x32_bf16 v[20:23], v[122:125], v[178:181], 0
	v_mfma_f32_16x16x32_bf16 v[16:19], v[142:145], v[178:181], 0
	v_mfma_f32_16x16x32_bf16 v[4:7], v[122:125], v[186:189], 0
	v_mfma_f32_16x16x32_bf16 v[0:3], v[142:145], v[186:189], 0
	v_mfma_f32_16x16x32_bf16 v[52:55], v[126:129], v[166:169], v[52:55]
	v_mfma_f32_16x16x32_bf16 v[48:51], v[150:153], v[166:169], v[48:51]
	v_mfma_f32_16x16x32_bf16 v[36:39], v[126:129], v[174:177], v[36:39]
	v_mfma_f32_16x16x32_bf16 v[32:35], v[150:153], v[174:177], v[32:35]
	v_mfma_f32_16x16x32_bf16 v[20:23], v[126:129], v[182:185], v[20:23]
	v_mfma_f32_16x16x32_bf16 v[16:19], v[150:153], v[182:185], v[16:19]
	v_mfma_f32_16x16x32_bf16 v[4:7], v[126:129], v[190:193], v[4:7]
	v_mfma_f32_16x16x32_bf16 v[0:3], v[150:153], v[190:193], v[0:3]
	s_setprio 0
	s_barrier
	s_add_i32 s56, 0, 0x18000
	s_add_i32 s57, 0, 0x1c000
	v_add_u32_e32 v106, s56, v254
	v_add_u32_e32 v150, s57, v254
	ds_read_b128 v[72:75], v106
	ds_read_b128 v[84:87], v106 offset:1024
	ds_read_b128 v[98:101], v106 offset:2048
	ds_read_b128 v[106:109], v106 offset:3072
	ds_read_b128 v[122:125], v150
	ds_read_b128 v[126:129], v150 offset:1024
	ds_read_b128 v[142:145], v150 offset:2048
	ds_read_b128 v[150:153], v150 offset:3072
	s_add_u32 s26, s30, 0xb0000
	s_addc_u32 s27, s31, 0
	s_mov_b32 m0, s42
	v_lshl_add_u64 v[214:215], s[26:27], 0, v[202:203]
	ds_read_b128 v[162:165], v198 offset:32768
	ds_read_b128 v[166:169], v198 offset:33792
	ds_read_b128 v[170:173], v198 offset:34816
	ds_read_b128 v[174:177], v198 offset:35840
	ds_read_b128 v[178:181], v198 offset:36864
	ds_read_b128 v[182:185], v198 offset:37888
	ds_read_b128 v[186:189], v198 offset:38912
	ds_read_b128 v[190:193], v198 offset:39936
	global_load_lds_dwordx4 v[214:215], off
	v_lshl_add_u64 v[214:215], s[26:27], 0, v[204:205]
	s_mov_b32 m0, s43
	s_nop 0
	global_load_lds_dwordx4 v[214:215], off
	s_waitcnt vmcnt(8)
	s_waitcnt lgkmcnt(0)
	s_barrier
	s_setprio 1
	s_waitcnt lgkmcnt(0)
	v_mfma_f32_16x16x32_bf16 v[158:161], v[72:75], v[162:165], v[158:161]
	v_mfma_f32_16x16x32_bf16 v[154:157], v[98:101], v[162:165], v[154:157]
	v_mfma_f32_16x16x32_bf16 v[134:137], v[72:75], v[170:173], v[134:137]
	v_mfma_f32_16x16x32_bf16 v[130:133], v[98:101], v[170:173], v[130:133]
	v_mfma_f32_16x16x32_bf16 v[110:113], v[72:75], v[178:181], v[110:113]
	v_mfma_f32_16x16x32_bf16 v[102:105], v[98:101], v[178:181], v[102:105]
	v_mfma_f32_16x16x32_bf16 v[80:83], v[72:75], v[186:189], v[80:83]
	v_mfma_f32_16x16x32_bf16 v[76:79], v[98:101], v[186:189], v[76:79]
	v_mfma_f32_16x16x32_bf16 v[158:161], v[84:87], v[166:169], v[158:161]
	v_mfma_f32_16x16x32_bf16 v[154:157], v[106:109], v[166:169], v[154:157]
	v_mfma_f32_16x16x32_bf16 v[134:137], v[84:87], v[174:177], v[134:137]
	v_mfma_f32_16x16x32_bf16 v[130:133], v[106:109], v[174:177], v[130:133]
	v_mfma_f32_16x16x32_bf16 v[110:113], v[84:87], v[182:185], v[110:113]
	v_mfma_f32_16x16x32_bf16 v[102:105], v[106:109], v[182:185], v[102:105]
	v_mfma_f32_16x16x32_bf16 v[80:83], v[84:87], v[190:193], v[80:83]
	v_mfma_f32_16x16x32_bf16 v[76:79], v[106:109], v[190:193], v[76:79]
	v_mfma_f32_16x16x32_bf16 v[146:149], v[122:125], v[162:165], v[146:149]
	v_mfma_f32_16x16x32_bf16 v[138:141], v[142:145], v[162:165], v[138:141]
	v_mfma_f32_16x16x32_bf16 v[118:121], v[122:125], v[170:173], v[118:121]
	v_mfma_f32_16x16x32_bf16 v[114:117], v[142:145], v[170:173], v[114:117]
	v_mfma_f32_16x16x32_bf16 v[92:95], v[122:125], v[178:181], v[92:95]
	v_mfma_f32_16x16x32_bf16 v[88:91], v[142:145], v[178:181], v[88:91]
	v_mfma_f32_16x16x32_bf16 v[68:71], v[122:125], v[186:189], v[68:71]
	v_mfma_f32_16x16x32_bf16 v[64:67], v[142:145], v[186:189], v[64:67]
	v_mfma_f32_16x16x32_bf16 v[146:149], v[126:129], v[166:169], v[146:149]
	v_mfma_f32_16x16x32_bf16 v[138:141], v[150:153], v[166:169], v[138:141]
	v_mfma_f32_16x16x32_bf16 v[118:121], v[126:129], v[174:177], v[118:121]
	v_mfma_f32_16x16x32_bf16 v[114:117], v[150:153], v[174:177], v[114:117]
	v_mfma_f32_16x16x32_bf16 v[92:95], v[126:129], v[182:185], v[92:95]
	v_mfma_f32_16x16x32_bf16 v[88:91], v[150:153], v[182:185], v[88:91]
	v_mfma_f32_16x16x32_bf16 v[68:71], v[126:129], v[190:193], v[68:71]
	v_mfma_f32_16x16x32_bf16 v[64:67], v[150:153], v[190:193], v[64:67]
	s_setprio 0
	s_barrier
	s_add_i32 s26, s56, s39
	v_lshl_add_u64 v[194:195], v[194:195], 0, s[64:65]
	s_mov_b32 m0, s26
	ds_read_b128 v[162:165], v198 offset:49152
	ds_read_b128 v[166:169], v198 offset:50176
	ds_read_b128 v[170:173], v198 offset:51200
	ds_read_b128 v[174:177], v198 offset:52224
	ds_read_b128 v[178:181], v198 offset:53248
	ds_read_b128 v[182:185], v198 offset:54272
	ds_read_b128 v[186:189], v198 offset:55296
	ds_read_b128 v[190:193], v198 offset:56320
	global_load_lds_dwordx4 v[194:195], off
	s_add_i32 m0, s26, 0x2000
	s_add_u32 s26, s28, 0xb0080
	v_lshl_add_u64 v[194:195], v[196:197], 0, s[64:65]
	s_addc_u32 s27, s29, 0
	s_add_i32 s28, s57, s39
	global_load_lds_dwordx4 v[194:195], off
	v_lshl_add_u64 v[194:195], s[26:27], 0, v[96:97]
	s_mov_b32 m0, s28
	s_nop 0
	global_load_lds_dwordx4 v[194:195], off
	v_lshl_add_u64 v[194:195], s[26:27], 0, v[206:207]
	s_add_i32 m0, s28, 0x2000
	s_nop 0
	global_load_lds_dwordx4 v[194:195], off
	v_lshl_add_u64 v[194:195], v[200:201], 0, s[64:65]
	s_mov_b32 m0, s45
	s_nop 0
	global_load_lds_dwordx4 v[194:195], off
	v_lshl_add_u64 v[194:195], v[212:213], 0, s[64:65]
	s_mov_b32 m0, s46
	s_nop 0
	global_load_lds_dwordx4 v[194:195], off
	s_waitcnt vmcnt(8)
	s_waitcnt lgkmcnt(0)
	s_barrier
	s_setprio 1
	s_waitcnt lgkmcnt(0)
	v_mfma_f32_16x16x32_bf16 v[60:63], v[72:75], v[162:165], v[60:63]
	v_mfma_f32_16x16x32_bf16 v[56:59], v[98:101], v[162:165], v[56:59]
	v_mfma_f32_16x16x32_bf16 v[44:47], v[72:75], v[170:173], v[44:47]
	v_mfma_f32_16x16x32_bf16 v[40:43], v[98:101], v[170:173], v[40:43]
	v_mfma_f32_16x16x32_bf16 v[28:31], v[72:75], v[178:181], v[28:31]
	v_mfma_f32_16x16x32_bf16 v[24:27], v[98:101], v[178:181], v[24:27]
	v_mfma_f32_16x16x32_bf16 v[12:15], v[72:75], v[186:189], v[12:15]
	v_mfma_f32_16x16x32_bf16 v[8:11], v[98:101], v[186:189], v[8:11]
	v_mfma_f32_16x16x32_bf16 v[60:63], v[84:87], v[166:169], v[60:63]
	v_mfma_f32_16x16x32_bf16 v[56:59], v[106:109], v[166:169], v[56:59]
	v_mfma_f32_16x16x32_bf16 v[44:47], v[84:87], v[174:177], v[44:47]
	v_mfma_f32_16x16x32_bf16 v[40:43], v[106:109], v[174:177], v[40:43]
	v_mfma_f32_16x16x32_bf16 v[28:31], v[84:87], v[182:185], v[28:31]
	v_mfma_f32_16x16x32_bf16 v[24:27], v[106:109], v[182:185], v[24:27]
	v_mfma_f32_16x16x32_bf16 v[12:15], v[84:87], v[190:193], v[12:15]
	v_mfma_f32_16x16x32_bf16 v[8:11], v[106:109], v[190:193], v[8:11]
	v_mfma_f32_16x16x32_bf16 v[52:55], v[122:125], v[162:165], v[52:55]
	v_mfma_f32_16x16x32_bf16 v[48:51], v[142:145], v[162:165], v[48:51]
	v_mfma_f32_16x16x32_bf16 v[36:39], v[122:125], v[170:173], v[36:39]
	v_mfma_f32_16x16x32_bf16 v[32:35], v[142:145], v[170:173], v[32:35]
	v_mfma_f32_16x16x32_bf16 v[20:23], v[122:125], v[178:181], v[20:23]
	v_mfma_f32_16x16x32_bf16 v[16:19], v[142:145], v[178:181], v[16:19]
	v_mfma_f32_16x16x32_bf16 v[4:7], v[122:125], v[186:189], v[4:7]
	v_mfma_f32_16x16x32_bf16 v[0:3], v[142:145], v[186:189], v[0:3]
	v_mfma_f32_16x16x32_bf16 v[52:55], v[126:129], v[166:169], v[52:55]
	v_mfma_f32_16x16x32_bf16 v[48:51], v[150:153], v[166:169], v[48:51]
	v_mfma_f32_16x16x32_bf16 v[36:39], v[126:129], v[174:177], v[36:39]
	v_mfma_f32_16x16x32_bf16 v[32:35], v[150:153], v[174:177], v[32:35]
	v_mfma_f32_16x16x32_bf16 v[20:23], v[126:129], v[182:185], v[20:23]
	v_mfma_f32_16x16x32_bf16 v[16:19], v[150:153], v[182:185], v[16:19]
	v_mfma_f32_16x16x32_bf16 v[4:7], v[126:129], v[190:193], v[4:7]
	v_mfma_f32_16x16x32_bf16 v[0:3], v[150:153], v[190:193], v[0:3]
	s_setprio 0
	s_barrier
	s_add_i32 s55, s55, 2
	s_add_u32 s53, s53, 0x100
	s_addc_u32 s54, s54, 0
	s_cmp_gt_u32 s55, 41
	s_mov_b64 s[26:27], s[6:7]
	s_cbranch_scc1 .Lpeel_done_339
.LBB0_339:
	s_add_u32 s6, s26, 0x100
	s_addc_u32 s7, s27, 0
	s_add_i32 s56, 0, 0x10000
	s_cmp_eq_u32 s55, 40
	s_cselect_b32 s31, s23, s7
	s_cselect_b32 s30, s22, s6
	s_cselect_b32 s29, s25, s54
	s_cselect_b32 s28, s24, s53
	s_add_i32 s57, 0, 0x14000
	v_add_u32_e32 v106, s56, v254
	v_add_u32_e32 v150, s57, v254
	ds_read_b128 v[72:75], v106
	ds_read_b128 v[84:87], v106 offset:1024
	ds_read_b128 v[98:101], v106 offset:2048
	ds_read_b128 v[106:109], v106 offset:3072
	ds_read_b128 v[122:125], v150
	ds_read_b128 v[126:129], v150 offset:1024
	ds_read_b128 v[142:145], v150 offset:2048
	ds_read_b128 v[150:153], v150 offset:3072
	v_lshl_add_u64 v[194:195], s[26:27], 0, v[208:209]
	s_add_i32 m0, s40, 0xc000
	ds_read_b128 v[162:165], v198
	ds_read_b128 v[166:169], v198 offset:1024
	ds_read_b128 v[170:173], v198 offset:2048
	ds_read_b128 v[174:177], v198 offset:3072
	ds_read_b128 v[178:181], v198 offset:4096
	ds_read_b128 v[182:185], v198 offset:5120
	ds_read_b128 v[186:189], v198 offset:6144
	ds_read_b128 v[190:193], v198 offset:7168
	global_load_lds_dwordx4 v[194:195], off
	v_lshl_add_u64 v[194:195], s[26:27], 0, v[210:211]
	s_add_i32 m0, s40, 0xe000
	s_nop 0
	global_load_lds_dwordx4 v[194:195], off
	s_waitcnt vmcnt(8)
	s_waitcnt lgkmcnt(0)
	s_barrier
	s_setprio 1
	s_waitcnt lgkmcnt(0)
	v_mfma_f32_16x16x32_bf16 v[158:161], v[72:75], v[162:165], v[158:161]
	v_mfma_f32_16x16x32_bf16 v[154:157], v[98:101], v[162:165], v[154:157]
	v_mfma_f32_16x16x32_bf16 v[134:137], v[72:75], v[170:173], v[134:137]
	v_mfma_f32_16x16x32_bf16 v[130:133], v[98:101], v[170:173], v[130:133]
	v_mfma_f32_16x16x32_bf16 v[110:113], v[72:75], v[178:181], v[110:113]
	v_mfma_f32_16x16x32_bf16 v[102:105], v[98:101], v[178:181], v[102:105]
	v_mfma_f32_16x16x32_bf16 v[80:83], v[72:75], v[186:189], v[80:83]
	v_mfma_f32_16x16x32_bf16 v[76:79], v[98:101], v[186:189], v[76:79]
	v_mfma_f32_16x16x32_bf16 v[158:161], v[84:87], v[166:169], v[158:161]
	v_mfma_f32_16x16x32_bf16 v[154:157], v[106:109], v[166:169], v[154:157]
	v_mfma_f32_16x16x32_bf16 v[134:137], v[84:87], v[174:177], v[134:137]
	v_mfma_f32_16x16x32_bf16 v[130:133], v[106:109], v[174:177], v[130:133]
	v_mfma_f32_16x16x32_bf16 v[110:113], v[84:87], v[182:185], v[110:113]
	v_mfma_f32_16x16x32_bf16 v[102:105], v[106:109], v[182:185], v[102:105]
	v_mfma_f32_16x16x32_bf16 v[80:83], v[84:87], v[190:193], v[80:83]
	v_mfma_f32_16x16x32_bf16 v[76:79], v[106:109], v[190:193], v[76:79]
	v_mfma_f32_16x16x32_bf16 v[146:149], v[122:125], v[162:165], v[146:149]
	v_mfma_f32_16x16x32_bf16 v[138:141], v[142:145], v[162:165], v[138:141]
	v_mfma_f32_16x16x32_bf16 v[118:121], v[122:125], v[170:173], v[118:121]
	v_mfma_f32_16x16x32_bf16 v[114:117], v[142:145], v[170:173], v[114:117]
	v_mfma_f32_16x16x32_bf16 v[92:95], v[122:125], v[178:181], v[92:95]
	v_mfma_f32_16x16x32_bf16 v[88:91], v[142:145], v[178:181], v[88:91]
	v_mfma_f32_16x16x32_bf16 v[68:71], v[122:125], v[186:189], v[68:71]
	v_mfma_f32_16x16x32_bf16 v[64:67], v[142:145], v[186:189], v[64:67]
	v_mfma_f32_16x16x32_bf16 v[146:149], v[126:129], v[166:169], v[146:149]
	v_mfma_f32_16x16x32_bf16 v[138:141], v[150:153], v[166:169], v[138:141]
	v_mfma_f32_16x16x32_bf16 v[118:121], v[126:129], v[174:177], v[118:121]
	v_mfma_f32_16x16x32_bf16 v[114:117], v[150:153], v[174:177], v[114:117]
	v_mfma_f32_16x16x32_bf16 v[92:95], v[126:129], v[182:185], v[92:95]
	v_mfma_f32_16x16x32_bf16 v[88:91], v[150:153], v[182:185], v[88:91]
	v_mfma_f32_16x16x32_bf16 v[68:71], v[126:129], v[190:193], v[68:71]
	v_mfma_f32_16x16x32_bf16 v[64:67], v[150:153], v[190:193], v[64:67]
	s_setprio 0
	s_barrier
	s_add_i32 s26, s56, s39
	v_lshl_add_u64 v[194:195], s[28:29], 0, v[96:97]
	s_mov_b32 m0, s26
	ds_read_b128 v[162:165], v198 offset:16384
	ds_read_b128 v[166:169], v198 offset:17408
	ds_read_b128 v[170:173], v198 offset:18432
	ds_read_b128 v[174:177], v198 offset:19456
	ds_read_b128 v[178:181], v198 offset:20480
	ds_read_b128 v[182:185], v198 offset:21504
	ds_read_b128 v[186:189], v198 offset:22528
	ds_read_b128 v[190:193], v198 offset:23552
	global_load_lds_dwordx4 v[194:195], off
	s_add_i32 m0, s26, 0x2000
	s_add_u32 s26, s28, 0xb0000
	v_lshl_add_u64 v[196:197], s[28:29], 0, v[206:207]
	s_addc_u32 s27, s29, 0
	s_add_i32 s56, s57, s39
	global_load_lds_dwordx4 v[196:197], off
	v_lshl_add_u64 v[200:201], s[26:27], 0, v[96:97]
	s_mov_b32 m0, s56
	v_lshl_add_u64 v[212:213], s[30:31], 0, v[204:205]
	global_load_lds_dwordx4 v[200:201], off
	v_lshl_add_u64 v[200:201], s[26:27], 0, v[206:207]
	s_add_i32 m0, s56, 0x2000
	s_nop 0
	global_load_lds_dwordx4 v[200:201], off
	v_lshl_add_u64 v[200:201], s[30:31], 0, v[202:203]
	s_mov_b32 m0, s40
	s_nop 0
	global_load_lds_dwordx4 v[200:201], off
	s_mov_b32 m0, s41
	s_nop 0
	global_load_lds_dwordx4 v[212:213], off
	s_waitcnt vmcnt(8)
	s_waitcnt lgkmcnt(0)
	s_barrier
	s_setprio 1
	s_waitcnt lgkmcnt(0)
	v_mfma_f32_16x16x32_bf16 v[60:63], v[72:75], v[162:165], v[60:63]
	v_mfma_f32_16x16x32_bf16 v[56:59], v[98:101], v[162:165], v[56:59]
	v_mfma_f32_16x16x32_bf16 v[44:47], v[72:75], v[170:173], v[44:47]
	v_mfma_f32_16x16x32_bf16 v[40:43], v[98:101], v[170:173], v[40:43]
	v_mfma_f32_16x16x32_bf16 v[28:31], v[72:75], v[178:181], v[28:31]
	v_mfma_f32_16x16x32_bf16 v[24:27], v[98:101], v[178:181], v[24:27]
	v_mfma_f32_16x16x32_bf16 v[12:15], v[72:75], v[186:189], v[12:15]
	v_mfma_f32_16x16x32_bf16 v[8:11], v[98:101], v[186:189], v[8:11]
	v_mfma_f32_16x16x32_bf16 v[60:63], v[84:87], v[166:169], v[60:63]
	v_mfma_f32_16x16x32_bf16 v[56:59], v[106:109], v[166:169], v[56:59]
	v_mfma_f32_16x16x32_bf16 v[44:47], v[84:87], v[174:177], v[44:47]
	v_mfma_f32_16x16x32_bf16 v[40:43], v[106:109], v[174:177], v[40:43]
	v_mfma_f32_16x16x32_bf16 v[28:31], v[84:87], v[182:185], v[28:31]
	v_mfma_f32_16x16x32_bf16 v[24:27], v[106:109], v[182:185], v[24:27]
	v_mfma_f32_16x16x32_bf16 v[12:15], v[84:87], v[190:193], v[12:15]
	v_mfma_f32_16x16x32_bf16 v[8:11], v[106:109], v[190:193], v[8:11]
	v_mfma_f32_16x16x32_bf16 v[52:55], v[122:125], v[162:165], v[52:55]
	v_mfma_f32_16x16x32_bf16 v[48:51], v[142:145], v[162:165], v[48:51]
	v_mfma_f32_16x16x32_bf16 v[36:39], v[122:125], v[170:173], v[36:39]
	v_mfma_f32_16x16x32_bf16 v[32:35], v[142:145], v[170:173], v[32:35]
	v_mfma_f32_16x16x32_bf16 v[20:23], v[122:125], v[178:181], v[20:23]
	v_mfma_f32_16x16x32_bf16 v[16:19], v[142:145], v[178:181], v[16:19]
	v_mfma_f32_16x16x32_bf16 v[4:7], v[122:125], v[186:189], v[4:7]
	v_mfma_f32_16x16x32_bf16 v[0:3], v[142:145], v[186:189], v[0:3]
	v_mfma_f32_16x16x32_bf16 v[52:55], v[126:129], v[166:169], v[52:55]
	v_mfma_f32_16x16x32_bf16 v[48:51], v[150:153], v[166:169], v[48:51]
	v_mfma_f32_16x16x32_bf16 v[36:39], v[126:129], v[174:177], v[36:39]
	v_mfma_f32_16x16x32_bf16 v[32:35], v[150:153], v[174:177], v[32:35]
	v_mfma_f32_16x16x32_bf16 v[20:23], v[126:129], v[182:185], v[20:23]
	v_mfma_f32_16x16x32_bf16 v[16:19], v[150:153], v[182:185], v[16:19]
	v_mfma_f32_16x16x32_bf16 v[4:7], v[126:129], v[190:193], v[4:7]
	v_mfma_f32_16x16x32_bf16 v[0:3], v[150:153], v[190:193], v[0:3]
	s_setprio 0
	s_barrier
	s_add_i32 s56, 0, 0x18000
	s_add_i32 s57, 0, 0x1c000
	v_add_u32_e32 v106, s56, v254
	v_add_u32_e32 v150, s57, v254
	ds_read_b128 v[72:75], v106
	ds_read_b128 v[84:87], v106 offset:1024
	ds_read_b128 v[98:101], v106 offset:2048
	ds_read_b128 v[106:109], v106 offset:3072
	ds_read_b128 v[122:125], v150
	ds_read_b128 v[126:129], v150 offset:1024
	ds_read_b128 v[142:145], v150 offset:2048
	ds_read_b128 v[150:153], v150 offset:3072
	s_add_u32 s26, s30, 0xb0000
	s_addc_u32 s27, s31, 0
	s_mov_b32 m0, s42
	v_lshl_add_u64 v[214:215], s[26:27], 0, v[202:203]
	ds_read_b128 v[162:165], v198 offset:32768
	ds_read_b128 v[166:169], v198 offset:33792
	ds_read_b128 v[170:173], v198 offset:34816
	ds_read_b128 v[174:177], v198 offset:35840
	ds_read_b128 v[178:181], v198 offset:36864
	ds_read_b128 v[182:185], v198 offset:37888
	ds_read_b128 v[186:189], v198 offset:38912
	ds_read_b128 v[190:193], v198 offset:39936
	global_load_lds_dwordx4 v[214:215], off
	v_lshl_add_u64 v[214:215], s[26:27], 0, v[204:205]
	s_mov_b32 m0, s43
	s_nop 0
	global_load_lds_dwordx4 v[214:215], off
	s_waitcnt vmcnt(8)
	s_waitcnt lgkmcnt(0)
	s_barrier
	s_setprio 1
	s_waitcnt lgkmcnt(0)
	v_mfma_f32_16x16x32_bf16 v[158:161], v[72:75], v[162:165], v[158:161]
	v_mfma_f32_16x16x32_bf16 v[154:157], v[98:101], v[162:165], v[154:157]
	v_mfma_f32_16x16x32_bf16 v[134:137], v[72:75], v[170:173], v[134:137]
	v_mfma_f32_16x16x32_bf16 v[130:133], v[98:101], v[170:173], v[130:133]
	v_mfma_f32_16x16x32_bf16 v[110:113], v[72:75], v[178:181], v[110:113]
	v_mfma_f32_16x16x32_bf16 v[102:105], v[98:101], v[178:181], v[102:105]
	v_mfma_f32_16x16x32_bf16 v[80:83], v[72:75], v[186:189], v[80:83]
	v_mfma_f32_16x16x32_bf16 v[76:79], v[98:101], v[186:189], v[76:79]
	v_mfma_f32_16x16x32_bf16 v[158:161], v[84:87], v[166:169], v[158:161]
	v_mfma_f32_16x16x32_bf16 v[154:157], v[106:109], v[166:169], v[154:157]
	v_mfma_f32_16x16x32_bf16 v[134:137], v[84:87], v[174:177], v[134:137]
	v_mfma_f32_16x16x32_bf16 v[130:133], v[106:109], v[174:177], v[130:133]
	v_mfma_f32_16x16x32_bf16 v[110:113], v[84:87], v[182:185], v[110:113]
	v_mfma_f32_16x16x32_bf16 v[102:105], v[106:109], v[182:185], v[102:105]
	v_mfma_f32_16x16x32_bf16 v[80:83], v[84:87], v[190:193], v[80:83]
	v_mfma_f32_16x16x32_bf16 v[76:79], v[106:109], v[190:193], v[76:79]
	v_mfma_f32_16x16x32_bf16 v[146:149], v[122:125], v[162:165], v[146:149]
	v_mfma_f32_16x16x32_bf16 v[138:141], v[142:145], v[162:165], v[138:141]
	v_mfma_f32_16x16x32_bf16 v[118:121], v[122:125], v[170:173], v[118:121]
	v_mfma_f32_16x16x32_bf16 v[114:117], v[142:145], v[170:173], v[114:117]
	v_mfma_f32_16x16x32_bf16 v[92:95], v[122:125], v[178:181], v[92:95]
	v_mfma_f32_16x16x32_bf16 v[88:91], v[142:145], v[178:181], v[88:91]
	v_mfma_f32_16x16x32_bf16 v[68:71], v[122:125], v[186:189], v[68:71]
	v_mfma_f32_16x16x32_bf16 v[64:67], v[142:145], v[186:189], v[64:67]
	v_mfma_f32_16x16x32_bf16 v[146:149], v[126:129], v[166:169], v[146:149]
	v_mfma_f32_16x16x32_bf16 v[138:141], v[150:153], v[166:169], v[138:141]
	v_mfma_f32_16x16x32_bf16 v[118:121], v[126:129], v[174:177], v[118:121]
	v_mfma_f32_16x16x32_bf16 v[114:117], v[150:153], v[174:177], v[114:117]
	v_mfma_f32_16x16x32_bf16 v[92:95], v[126:129], v[182:185], v[92:95]
	v_mfma_f32_16x16x32_bf16 v[88:91], v[150:153], v[182:185], v[88:91]
	v_mfma_f32_16x16x32_bf16 v[68:71], v[126:129], v[190:193], v[68:71]
	v_mfma_f32_16x16x32_bf16 v[64:67], v[150:153], v[190:193], v[64:67]
	s_setprio 0
	s_barrier
	s_add_i32 s26, s56, s39
	v_lshl_add_u64 v[194:195], v[194:195], 0, s[64:65]
	s_mov_b32 m0, s26
	ds_read_b128 v[162:165], v198 offset:49152
	ds_read_b128 v[166:169], v198 offset:50176
	ds_read_b128 v[170:173], v198 offset:51200
	ds_read_b128 v[174:177], v198 offset:52224
	ds_read_b128 v[178:181], v198 offset:53248
	ds_read_b128 v[182:185], v198 offset:54272
	ds_read_b128 v[186:189], v198 offset:55296
	ds_read_b128 v[190:193], v198 offset:56320
	global_load_lds_dwordx4 v[194:195], off
	s_add_i32 m0, s26, 0x2000
	s_add_u32 s26, s28, 0xb0080
	v_lshl_add_u64 v[194:195], v[196:197], 0, s[64:65]
	s_addc_u32 s27, s29, 0
	s_add_i32 s28, s57, s39
	global_load_lds_dwordx4 v[194:195], off
	v_lshl_add_u64 v[194:195], s[26:27], 0, v[96:97]
	s_mov_b32 m0, s28
	s_nop 0
	global_load_lds_dwordx4 v[194:195], off
	v_lshl_add_u64 v[194:195], s[26:27], 0, v[206:207]
	s_add_i32 m0, s28, 0x2000
	s_nop 0
	global_load_lds_dwordx4 v[194:195], off
	v_lshl_add_u64 v[194:195], v[200:201], 0, s[64:65]
	s_mov_b32 m0, s45
	s_nop 0
	global_load_lds_dwordx4 v[194:195], off
	v_lshl_add_u64 v[194:195], v[212:213], 0, s[64:65]
	s_mov_b32 m0, s46
	s_nop 0
	global_load_lds_dwordx4 v[194:195], off
	s_waitcnt vmcnt(8)
	s_waitcnt lgkmcnt(0)
	s_barrier
	s_setprio 1
	s_waitcnt lgkmcnt(0)
	v_mfma_f32_16x16x32_bf16 v[60:63], v[72:75], v[162:165], v[60:63]
	v_mfma_f32_16x16x32_bf16 v[56:59], v[98:101], v[162:165], v[56:59]
	v_mfma_f32_16x16x32_bf16 v[44:47], v[72:75], v[170:173], v[44:47]
	v_mfma_f32_16x16x32_bf16 v[40:43], v[98:101], v[170:173], v[40:43]
	v_mfma_f32_16x16x32_bf16 v[28:31], v[72:75], v[178:181], v[28:31]
	v_mfma_f32_16x16x32_bf16 v[24:27], v[98:101], v[178:181], v[24:27]
	v_mfma_f32_16x16x32_bf16 v[12:15], v[72:75], v[186:189], v[12:15]
	v_mfma_f32_16x16x32_bf16 v[8:11], v[98:101], v[186:189], v[8:11]
	v_mfma_f32_16x16x32_bf16 v[60:63], v[84:87], v[166:169], v[60:63]
	v_mfma_f32_16x16x32_bf16 v[56:59], v[106:109], v[166:169], v[56:59]
	v_mfma_f32_16x16x32_bf16 v[44:47], v[84:87], v[174:177], v[44:47]
	v_mfma_f32_16x16x32_bf16 v[40:43], v[106:109], v[174:177], v[40:43]
	v_mfma_f32_16x16x32_bf16 v[28:31], v[84:87], v[182:185], v[28:31]
	v_mfma_f32_16x16x32_bf16 v[24:27], v[106:109], v[182:185], v[24:27]
	v_mfma_f32_16x16x32_bf16 v[12:15], v[84:87], v[190:193], v[12:15]
	v_mfma_f32_16x16x32_bf16 v[8:11], v[106:109], v[190:193], v[8:11]
	v_mfma_f32_16x16x32_bf16 v[52:55], v[122:125], v[162:165], v[52:55]
	v_mfma_f32_16x16x32_bf16 v[48:51], v[142:145], v[162:165], v[48:51]
	v_mfma_f32_16x16x32_bf16 v[36:39], v[122:125], v[170:173], v[36:39]
	v_mfma_f32_16x16x32_bf16 v[32:35], v[142:145], v[170:173], v[32:35]
	v_mfma_f32_16x16x32_bf16 v[20:23], v[122:125], v[178:181], v[20:23]
	v_mfma_f32_16x16x32_bf16 v[16:19], v[142:145], v[178:181], v[16:19]
	v_mfma_f32_16x16x32_bf16 v[4:7], v[122:125], v[186:189], v[4:7]
	v_mfma_f32_16x16x32_bf16 v[0:3], v[142:145], v[186:189], v[0:3]
	v_mfma_f32_16x16x32_bf16 v[52:55], v[126:129], v[166:169], v[52:55]
	v_mfma_f32_16x16x32_bf16 v[48:51], v[150:153], v[166:169], v[48:51]
	v_mfma_f32_16x16x32_bf16 v[36:39], v[126:129], v[174:177], v[36:39]
	v_mfma_f32_16x16x32_bf16 v[32:35], v[150:153], v[174:177], v[32:35]
	v_mfma_f32_16x16x32_bf16 v[20:23], v[126:129], v[182:185], v[20:23]
	v_mfma_f32_16x16x32_bf16 v[16:19], v[150:153], v[182:185], v[16:19]
	v_mfma_f32_16x16x32_bf16 v[4:7], v[126:129], v[190:193], v[4:7]
	v_mfma_f32_16x16x32_bf16 v[0:3], v[150:153], v[190:193], v[0:3]
	s_setprio 0
	s_barrier
	s_add_i32 s55, s55, 2
	s_add_u32 s53, s53, 0x100
	s_addc_u32 s54, s54, 0
	s_cmp_gt_u32 s55, 41
	s_mov_b64 s[26:27], s[6:7]
	s_cbranch_scc0 .LBB0_339

.LBB0_460:
	s_ashr_i32 s21, s20, 31
	s_lshl_b64 s[22:23], s[20:21], 19
	s_add_u32 s22, s40, s22
	s_addc_u32 s23, s41, s23
	s_and_b64 s[24:25], s[2:3], exec
	s_cselect_b32 s21, s23, s29
	s_cselect_b32 s51, s22, s28
	s_ashr_i32 s19, s18, 31
	s_lshl_b64 s[24:25], s[18:19], 19
	s_add_u32 s24, s38, s24
	s_addc_u32 s25, s39, s25
	s_and_b64 s[34:35], s[2:3], exec
	s_cselect_b32 s19, s25, s31
	s_cselect_b32 s52, s24, s30
	s_add_u32 s28, s28, 0x40080
	s_addc_u32 s29, s29, 0
	s_add_u32 s53, s30, 0x100
	s_addc_u32 s54, s31, 0
	s_mov_b32 s55, -2
	s_add_u32 s30, s28, 0xfffc0080
	s_addc_u32 s31, s29, -1
	s_add_i32 s56, 0, 0x10000
	s_cmp_eq_u32 s55, 12
	s_cselect_b32 s35, s21, s31
	s_cselect_b32 s34, s51, s30
	v_add_u32_e32 v96, s56, v148
	s_cselect_b32 s31, s19, s54
	s_cselect_b32 s30, s52, s53
	s_add_i32 s60, 0, 0x14000
	ds_read_b128 v[144:147], v96
	ds_read_b128 v[154:157], v96 offset:1024
	ds_read_b128 v[158:161], v96 offset:2048
	ds_read_b128 v[162:165], v96 offset:3072
	v_add_u32_e32 v96, s60, v148
	ds_read_b128 v[166:169], v96
	ds_read_b128 v[170:173], v96 offset:1024
	ds_read_b128 v[174:177], v96 offset:2048
	ds_read_b128 v[178:181], v96 offset:3072
	v_lshl_add_u64 v[214:215], s[28:29], 0, v[140:141]
	s_add_i32 m0, s43, 0xc000
	ds_read_b128 v[182:185], v152
	ds_read_b128 v[186:189], v152 offset:1024
	ds_read_b128 v[190:193], v152 offset:2048
	ds_read_b128 v[194:197], v152 offset:3072
	ds_read_b128 v[198:201], v152 offset:4096
	ds_read_b128 v[202:205], v152 offset:5120
	ds_read_b128 v[206:209], v152 offset:6144
	ds_read_b128 v[210:213], v152 offset:7168
	global_load_lds_dwordx4 v[214:215], off
	v_lshl_add_u64 v[214:215], s[28:29], 0, v[142:143]
	s_add_i32 m0, s43, 0xe000
	s_nop 0
	global_load_lds_dwordx4 v[214:215], off
	s_waitcnt vmcnt(8)
	s_waitcnt lgkmcnt(0)
	s_barrier
	s_setprio 1
	s_waitcnt lgkmcnt(0)
	v_mfma_f32_16x16x32_bf16 v[122:125], v[144:147], v[182:185], 0
	v_mfma_f32_16x16x32_bf16 v[126:129], v[158:161], v[182:185], 0
	v_mfma_f32_16x16x32_bf16 v[106:109], v[144:147], v[190:193], 0
	v_mfma_f32_16x16x32_bf16 v[110:113], v[158:161], v[190:193], 0
	v_mfma_f32_16x16x32_bf16 v[88:91], v[144:147], v[198:201], 0
	v_mfma_f32_16x16x32_bf16 v[92:95], v[158:161], v[198:201], 0
	v_mfma_f32_16x16x32_bf16 v[72:75], v[144:147], v[206:209], 0
	v_mfma_f32_16x16x32_bf16 v[76:79], v[158:161], v[206:209], 0
	v_mfma_f32_16x16x32_bf16 v[122:125], v[154:157], v[186:189], v[122:125]
	v_mfma_f32_16x16x32_bf16 v[126:129], v[162:165], v[186:189], v[126:129]
	v_mfma_f32_16x16x32_bf16 v[106:109], v[154:157], v[194:197], v[106:109]
	v_mfma_f32_16x16x32_bf16 v[110:113], v[162:165], v[194:197], v[110:113]
	v_mfma_f32_16x16x32_bf16 v[88:91], v[154:157], v[202:205], v[88:91]
	v_mfma_f32_16x16x32_bf16 v[92:95], v[162:165], v[202:205], v[92:95]
	v_mfma_f32_16x16x32_bf16 v[72:75], v[154:157], v[210:213], v[72:75]
	v_mfma_f32_16x16x32_bf16 v[76:79], v[162:165], v[210:213], v[76:79]
	v_mfma_f32_16x16x32_bf16 v[118:121], v[166:169], v[182:185], 0
	v_mfma_f32_16x16x32_bf16 v[114:117], v[174:177], v[182:185], 0
	v_mfma_f32_16x16x32_bf16 v[102:105], v[166:169], v[190:193], 0
	v_mfma_f32_16x16x32_bf16 v[98:101], v[174:177], v[190:193], 0
	v_mfma_f32_16x16x32_bf16 v[84:87], v[166:169], v[198:201], 0
	v_mfma_f32_16x16x32_bf16 v[80:83], v[174:177], v[198:201], 0
	v_mfma_f32_16x16x32_bf16 v[68:71], v[166:169], v[206:209], 0
	v_mfma_f32_16x16x32_bf16 v[64:67], v[174:177], v[206:209], 0
	v_mfma_f32_16x16x32_bf16 v[118:121], v[170:173], v[186:189], v[118:121]
	v_mfma_f32_16x16x32_bf16 v[114:117], v[178:181], v[186:189], v[114:117]
	v_mfma_f32_16x16x32_bf16 v[102:105], v[170:173], v[194:197], v[102:105]
	v_mfma_f32_16x16x32_bf16 v[98:101], v[178:181], v[194:197], v[98:101]
	v_mfma_f32_16x16x32_bf16 v[84:87], v[170:173], v[202:205], v[84:87]
	v_mfma_f32_16x16x32_bf16 v[80:83], v[178:181], v[202:205], v[80:83]
	v_mfma_f32_16x16x32_bf16 v[68:71], v[170:173], v[210:213], v[68:71]
	v_mfma_f32_16x16x32_bf16 v[64:67], v[178:181], v[210:213], v[64:67]
	s_setprio 0
	s_barrier
	s_add_i32 s56, s56, s42
	v_lshl_add_u64 v[214:215], s[30:31], 0, v[132:133]
	s_mov_b32 m0, s56
	ds_read_b128 v[182:185], v152 offset:16384
	ds_read_b128 v[186:189], v152 offset:17408
	ds_read_b128 v[190:193], v152 offset:18432
	ds_read_b128 v[194:197], v152 offset:19456
	ds_read_b128 v[198:201], v152 offset:20480
	ds_read_b128 v[202:205], v152 offset:21504
	ds_read_b128 v[206:209], v152 offset:22528
	ds_read_b128 v[210:213], v152 offset:23552
	global_load_lds_dwordx4 v[214:215], off
	s_add_i32 m0, s56, 0x2000
	s_add_u32 s56, s30, 0x40000
	v_lshl_add_u64 v[216:217], s[30:31], 0, v[136:137]
	s_addc_u32 s57, s31, 0
	s_add_i32 s60, s60, s42
	global_load_lds_dwordx4 v[216:217], off
	v_lshl_add_u64 v[218:219], s[56:57], 0, v[132:133]
	s_mov_b32 m0, s60
	v_lshl_add_u64 v[220:221], s[34:35], 0, v[134:135]
	global_load_lds_dwordx4 v[218:219], off
	v_lshl_add_u64 v[218:219], s[56:57], 0, v[136:137]
	s_add_i32 m0, s60, 0x2000
	s_nop 0
	global_load_lds_dwordx4 v[218:219], off
	v_lshl_add_u64 v[218:219], s[34:35], 0, v[130:131]
	s_mov_b32 m0, s43
	s_nop 0
	global_load_lds_dwordx4 v[218:219], off
	s_mov_b32 m0, s44
	s_nop 0
	global_load_lds_dwordx4 v[220:221], off
	s_waitcnt vmcnt(8)
	s_waitcnt lgkmcnt(0)
	s_barrier
	s_setprio 1
	s_waitcnt lgkmcnt(0)
	v_mfma_f32_16x16x32_bf16 v[56:59], v[144:147], v[182:185], 0
	v_mfma_f32_16x16x32_bf16 v[60:63], v[158:161], v[182:185], 0
	v_mfma_f32_16x16x32_bf16 v[40:43], v[144:147], v[190:193], 0
	v_mfma_f32_16x16x32_bf16 v[44:47], v[158:161], v[190:193], 0
	v_mfma_f32_16x16x32_bf16 v[24:27], v[144:147], v[198:201], 0
	v_mfma_f32_16x16x32_bf16 v[28:31], v[158:161], v[198:201], 0
	v_mfma_f32_16x16x32_bf16 v[8:11], v[144:147], v[206:209], 0
	v_mfma_f32_16x16x32_bf16 v[12:15], v[158:161], v[206:209], 0
	v_mfma_f32_16x16x32_bf16 v[56:59], v[154:157], v[186:189], v[56:59]
	v_mfma_f32_16x16x32_bf16 v[60:63], v[162:165], v[186:189], v[60:63]
	v_mfma_f32_16x16x32_bf16 v[40:43], v[154:157], v[194:197], v[40:43]
	v_mfma_f32_16x16x32_bf16 v[44:47], v[162:165], v[194:197], v[44:47]
	v_mfma_f32_16x16x32_bf16 v[24:27], v[154:157], v[202:205], v[24:27]
	v_mfma_f32_16x16x32_bf16 v[28:31], v[162:165], v[202:205], v[28:31]
	v_mfma_f32_16x16x32_bf16 v[8:11], v[154:157], v[210:213], v[8:11]
	v_mfma_f32_16x16x32_bf16 v[12:15], v[162:165], v[210:213], v[12:15]
	v_mfma_f32_16x16x32_bf16 v[52:55], v[166:169], v[182:185], 0
	v_mfma_f32_16x16x32_bf16 v[48:51], v[174:177], v[182:185], 0
	v_mfma_f32_16x16x32_bf16 v[36:39], v[166:169], v[190:193], 0
	v_mfma_f32_16x16x32_bf16 v[32:35], v[174:177], v[190:193], 0
	v_mfma_f32_16x16x32_bf16 v[20:23], v[166:169], v[198:201], 0
	v_mfma_f32_16x16x32_bf16 v[16:19], v[174:177], v[198:201], 0
	v_mfma_f32_16x16x32_bf16 v[4:7], v[166:169], v[206:209], 0
	v_mfma_f32_16x16x32_bf16 v[0:3], v[174:177], v[206:209], 0
	v_mfma_f32_16x16x32_bf16 v[52:55], v[170:173], v[186:189], v[52:55]
	v_mfma_f32_16x16x32_bf16 v[48:51], v[178:181], v[186:189], v[48:51]
	v_mfma_f32_16x16x32_bf16 v[36:39], v[170:173], v[194:197], v[36:39]
	v_mfma_f32_16x16x32_bf16 v[32:35], v[178:181], v[194:197], v[32:35]
	v_mfma_f32_16x16x32_bf16 v[20:23], v[170:173], v[202:205], v[20:23]
	v_mfma_f32_16x16x32_bf16 v[16:19], v[178:181], v[202:205], v[16:19]
	v_mfma_f32_16x16x32_bf16 v[4:7], v[170:173], v[210:213], v[4:7]
	v_mfma_f32_16x16x32_bf16 v[0:3], v[178:181], v[210:213], v[0:3]
	s_setprio 0
	s_barrier
	s_add_i32 s56, 0, 0x18000
	v_add_u32_e32 v96, s56, v148
	s_add_i32 s57, 0, 0x1c000
	ds_read_b128 v[144:147], v96
	ds_read_b128 v[154:157], v96 offset:1024
	ds_read_b128 v[158:161], v96 offset:2048
	ds_read_b128 v[162:165], v96 offset:3072
	v_add_u32_e32 v96, s57, v148
	ds_read_b128 v[166:169], v96
	ds_read_b128 v[170:173], v96 offset:1024
	ds_read_b128 v[174:177], v96 offset:2048
	ds_read_b128 v[178:181], v96 offset:3072
	s_add_u32 s34, s34, 0x40000
	s_addc_u32 s35, s35, 0
	s_mov_b32 m0, s45
	v_lshl_add_u64 v[222:223], s[34:35], 0, v[130:131]
	ds_read_b128 v[182:185], v152 offset:32768
	ds_read_b128 v[186:189], v152 offset:33792
	ds_read_b128 v[190:193], v152 offset:34816
	ds_read_b128 v[194:197], v152 offset:35840
	ds_read_b128 v[198:201], v152 offset:36864
	ds_read_b128 v[202:205], v152 offset:37888
	ds_read_b128 v[206:209], v152 offset:38912
	ds_read_b128 v[210:213], v152 offset:39936
	global_load_lds_dwordx4 v[222:223], off
	v_lshl_add_u64 v[222:223], s[34:35], 0, v[134:135]
	s_mov_b32 m0, s46
	s_nop 0
	global_load_lds_dwordx4 v[222:223], off
	s_waitcnt vmcnt(8)
	s_waitcnt lgkmcnt(0)
	s_barrier
	s_setprio 1
	s_waitcnt lgkmcnt(0)
	v_mfma_f32_16x16x32_bf16 v[122:125], v[144:147], v[182:185], v[122:125]
	v_mfma_f32_16x16x32_bf16 v[126:129], v[158:161], v[182:185], v[126:129]
	v_mfma_f32_16x16x32_bf16 v[106:109], v[144:147], v[190:193], v[106:109]
	v_mfma_f32_16x16x32_bf16 v[110:113], v[158:161], v[190:193], v[110:113]
	v_mfma_f32_16x16x32_bf16 v[88:91], v[144:147], v[198:201], v[88:91]
	v_mfma_f32_16x16x32_bf16 v[92:95], v[158:161], v[198:201], v[92:95]
	v_mfma_f32_16x16x32_bf16 v[72:75], v[144:147], v[206:209], v[72:75]
	v_mfma_f32_16x16x32_bf16 v[76:79], v[158:161], v[206:209], v[76:79]
	v_mfma_f32_16x16x32_bf16 v[122:125], v[154:157], v[186:189], v[122:125]
	v_mfma_f32_16x16x32_bf16 v[126:129], v[162:165], v[186:189], v[126:129]
	v_mfma_f32_16x16x32_bf16 v[106:109], v[154:157], v[194:197], v[106:109]
	v_mfma_f32_16x16x32_bf16 v[110:113], v[162:165], v[194:197], v[110:113]
	v_mfma_f32_16x16x32_bf16 v[88:91], v[154:157], v[202:205], v[88:91]
	v_mfma_f32_16x16x32_bf16 v[92:95], v[162:165], v[202:205], v[92:95]
	v_mfma_f32_16x16x32_bf16 v[72:75], v[154:157], v[210:213], v[72:75]
	v_mfma_f32_16x16x32_bf16 v[76:79], v[162:165], v[210:213], v[76:79]
	v_mfma_f32_16x16x32_bf16 v[118:121], v[166:169], v[182:185], v[118:121]
	v_mfma_f32_16x16x32_bf16 v[114:117], v[174:177], v[182:185], v[114:117]
	v_mfma_f32_16x16x32_bf16 v[102:105], v[166:169], v[190:193], v[102:105]
	v_mfma_f32_16x16x32_bf16 v[98:101], v[174:177], v[190:193], v[98:101]
	v_mfma_f32_16x16x32_bf16 v[84:87], v[166:169], v[198:201], v[84:87]
	v_mfma_f32_16x16x32_bf16 v[80:83], v[174:177], v[198:201], v[80:83]
	v_mfma_f32_16x16x32_bf16 v[68:71], v[166:169], v[206:209], v[68:71]
	v_mfma_f32_16x16x32_bf16 v[64:67], v[174:177], v[206:209], v[64:67]
	v_mfma_f32_16x16x32_bf16 v[118:121], v[170:173], v[186:189], v[118:121]
	v_mfma_f32_16x16x32_bf16 v[114:117], v[178:181], v[186:189], v[114:117]
	v_mfma_f32_16x16x32_bf16 v[102:105], v[170:173], v[194:197], v[102:105]
	v_mfma_f32_16x16x32_bf16 v[98:101], v[178:181], v[194:197], v[98:101]
	v_mfma_f32_16x16x32_bf16 v[84:87], v[170:173], v[202:205], v[84:87]
	v_mfma_f32_16x16x32_bf16 v[80:83], v[178:181], v[202:205], v[80:83]
	v_mfma_f32_16x16x32_bf16 v[68:71], v[170:173], v[210:213], v[68:71]
	v_mfma_f32_16x16x32_bf16 v[64:67], v[178:181], v[210:213], v[64:67]
	s_setprio 0
	s_barrier
	s_add_i32 s34, s56, s42
	v_lshl_add_u64 v[214:215], v[214:215], 0, s[64:65]
	s_mov_b32 m0, s34
	ds_read_b128 v[182:185], v152 offset:49152
	ds_read_b128 v[186:189], v152 offset:50176
	ds_read_b128 v[190:193], v152 offset:51200
	ds_read_b128 v[194:197], v152 offset:52224
	ds_read_b128 v[198:201], v152 offset:53248
	ds_read_b128 v[202:205], v152 offset:54272
	ds_read_b128 v[206:209], v152 offset:55296
	ds_read_b128 v[210:213], v152 offset:56320
	global_load_lds_dwordx4 v[214:215], off
	s_add_i32 m0, s34, 0x2000
	s_add_u32 s30, s30, 0x40080
	v_lshl_add_u64 v[214:215], v[216:217], 0, s[64:65]
	s_addc_u32 s31, s31, 0
	s_add_i32 s34, s57, s42
	global_load_lds_dwordx4 v[214:215], off
	v_lshl_add_u64 v[214:215], s[30:31], 0, v[132:133]
	s_mov_b32 m0, s34
	s_nop 0
	global_load_lds_dwordx4 v[214:215], off
	v_lshl_add_u64 v[214:215], s[30:31], 0, v[136:137]
	s_add_i32 m0, s34, 0x2000
	s_nop 0
	global_load_lds_dwordx4 v[214:215], off
	v_lshl_add_u64 v[214:215], v[218:219], 0, s[64:65]
	s_mov_b32 m0, s48
	s_nop 0
	global_load_lds_dwordx4 v[214:215], off
	v_lshl_add_u64 v[214:215], v[220:221], 0, s[64:65]
	s_mov_b32 m0, s49
	s_nop 0
	global_load_lds_dwordx4 v[214:215], off
	s_waitcnt vmcnt(8)
	s_waitcnt lgkmcnt(0)
	s_barrier
	s_setprio 1
	s_waitcnt lgkmcnt(0)
	v_mfma_f32_16x16x32_bf16 v[56:59], v[144:147], v[182:185], v[56:59]
	v_mfma_f32_16x16x32_bf16 v[60:63], v[158:161], v[182:185], v[60:63]
	v_mfma_f32_16x16x32_bf16 v[40:43], v[144:147], v[190:193], v[40:43]
	v_mfma_f32_16x16x32_bf16 v[44:47], v[158:161], v[190:193], v[44:47]
	v_mfma_f32_16x16x32_bf16 v[24:27], v[144:147], v[198:201], v[24:27]
	v_mfma_f32_16x16x32_bf16 v[28:31], v[158:161], v[198:201], v[28:31]
	v_mfma_f32_16x16x32_bf16 v[8:11], v[144:147], v[206:209], v[8:11]
	v_mfma_f32_16x16x32_bf16 v[12:15], v[158:161], v[206:209], v[12:15]
	v_mfma_f32_16x16x32_bf16 v[56:59], v[154:157], v[186:189], v[56:59]
	v_mfma_f32_16x16x32_bf16 v[60:63], v[162:165], v[186:189], v[60:63]
	v_mfma_f32_16x16x32_bf16 v[40:43], v[154:157], v[194:197], v[40:43]
	v_mfma_f32_16x16x32_bf16 v[44:47], v[162:165], v[194:197], v[44:47]
	v_mfma_f32_16x16x32_bf16 v[24:27], v[154:157], v[202:205], v[24:27]
	v_mfma_f32_16x16x32_bf16 v[28:31], v[162:165], v[202:205], v[28:31]
	v_mfma_f32_16x16x32_bf16 v[8:11], v[154:157], v[210:213], v[8:11]
	v_mfma_f32_16x16x32_bf16 v[12:15], v[162:165], v[210:213], v[12:15]
	v_mfma_f32_16x16x32_bf16 v[52:55], v[166:169], v[182:185], v[52:55]
	v_mfma_f32_16x16x32_bf16 v[48:51], v[174:177], v[182:185], v[48:51]
	v_mfma_f32_16x16x32_bf16 v[36:39], v[166:169], v[190:193], v[36:39]
	v_mfma_f32_16x16x32_bf16 v[32:35], v[174:177], v[190:193], v[32:35]
	v_mfma_f32_16x16x32_bf16 v[20:23], v[166:169], v[198:201], v[20:23]
	v_mfma_f32_16x16x32_bf16 v[16:19], v[174:177], v[198:201], v[16:19]
	v_mfma_f32_16x16x32_bf16 v[4:7], v[166:169], v[206:209], v[4:7]
	v_mfma_f32_16x16x32_bf16 v[0:3], v[174:177], v[206:209], v[0:3]
	v_mfma_f32_16x16x32_bf16 v[52:55], v[170:173], v[186:189], v[52:55]
	v_mfma_f32_16x16x32_bf16 v[48:51], v[178:181], v[186:189], v[48:51]
	v_mfma_f32_16x16x32_bf16 v[36:39], v[170:173], v[194:197], v[36:39]
	v_mfma_f32_16x16x32_bf16 v[32:35], v[178:181], v[194:197], v[32:35]
	v_mfma_f32_16x16x32_bf16 v[20:23], v[170:173], v[202:205], v[20:23]
	v_mfma_f32_16x16x32_bf16 v[16:19], v[178:181], v[202:205], v[16:19]
	v_mfma_f32_16x16x32_bf16 v[4:7], v[170:173], v[210:213], v[4:7]
	v_mfma_f32_16x16x32_bf16 v[0:3], v[178:181], v[210:213], v[0:3]
	s_setprio 0
	s_barrier
	s_add_i32 s55, s55, 2
	s_add_u32 s28, s28, 0x100
	s_addc_u32 s29, s29, 0
	s_add_u32 s53, s53, 0x100
	s_addc_u32 s54, s54, 0
	s_cmp_gt_u32 s55, 13
	s_cbranch_scc1 .Lpeel_done_461
.LBB0_461:
	s_add_u32 s30, s28, 0xfffc0080
	s_addc_u32 s31, s29, -1
	s_add_i32 s56, 0, 0x10000
	s_cmp_eq_u32 s55, 12
	s_cselect_b32 s35, s21, s31
	s_cselect_b32 s34, s51, s30
	v_add_u32_e32 v96, s56, v148
	s_cselect_b32 s31, s19, s54
	s_cselect_b32 s30, s52, s53
	s_add_i32 s60, 0, 0x14000
	ds_read_b128 v[144:147], v96
	ds_read_b128 v[154:157], v96 offset:1024
	ds_read_b128 v[158:161], v96 offset:2048
	ds_read_b128 v[162:165], v96 offset:3072
	v_add_u32_e32 v96, s60, v148
	ds_read_b128 v[166:169], v96
	ds_read_b128 v[170:173], v96 offset:1024
	ds_read_b128 v[174:177], v96 offset:2048
	ds_read_b128 v[178:181], v96 offset:3072
	v_lshl_add_u64 v[214:215], s[28:29], 0, v[140:141]
	s_add_i32 m0, s43, 0xc000
	ds_read_b128 v[182:185], v152
	ds_read_b128 v[186:189], v152 offset:1024
	ds_read_b128 v[190:193], v152 offset:2048
	ds_read_b128 v[194:197], v152 offset:3072
	ds_read_b128 v[198:201], v152 offset:4096
	ds_read_b128 v[202:205], v152 offset:5120
	ds_read_b128 v[206:209], v152 offset:6144
	ds_read_b128 v[210:213], v152 offset:7168
	global_load_lds_dwordx4 v[214:215], off
	v_lshl_add_u64 v[214:215], s[28:29], 0, v[142:143]
	s_add_i32 m0, s43, 0xe000
	s_nop 0
	global_load_lds_dwordx4 v[214:215], off
	s_waitcnt vmcnt(8)
	s_waitcnt lgkmcnt(0)
	s_barrier
	s_setprio 1
	s_waitcnt lgkmcnt(0)
	v_mfma_f32_16x16x32_bf16 v[122:125], v[144:147], v[182:185], v[122:125]
	v_mfma_f32_16x16x32_bf16 v[126:129], v[158:161], v[182:185], v[126:129]
	v_mfma_f32_16x16x32_bf16 v[106:109], v[144:147], v[190:193], v[106:109]
	v_mfma_f32_16x16x32_bf16 v[110:113], v[158:161], v[190:193], v[110:113]
	v_mfma_f32_16x16x32_bf16 v[88:91], v[144:147], v[198:201], v[88:91]
	v_mfma_f32_16x16x32_bf16 v[92:95], v[158:161], v[198:201], v[92:95]
	v_mfma_f32_16x16x32_bf16 v[72:75], v[144:147], v[206:209], v[72:75]
	v_mfma_f32_16x16x32_bf16 v[76:79], v[158:161], v[206:209], v[76:79]
	v_mfma_f32_16x16x32_bf16 v[122:125], v[154:157], v[186:189], v[122:125]
	v_mfma_f32_16x16x32_bf16 v[126:129], v[162:165], v[186:189], v[126:129]
	v_mfma_f32_16x16x32_bf16 v[106:109], v[154:157], v[194:197], v[106:109]
	v_mfma_f32_16x16x32_bf16 v[110:113], v[162:165], v[194:197], v[110:113]
	v_mfma_f32_16x16x32_bf16 v[88:91], v[154:157], v[202:205], v[88:91]
	v_mfma_f32_16x16x32_bf16 v[92:95], v[162:165], v[202:205], v[92:95]
	v_mfma_f32_16x16x32_bf16 v[72:75], v[154:157], v[210:213], v[72:75]
	v_mfma_f32_16x16x32_bf16 v[76:79], v[162:165], v[210:213], v[76:79]
	v_mfma_f32_16x16x32_bf16 v[118:121], v[166:169], v[182:185], v[118:121]
	v_mfma_f32_16x16x32_bf16 v[114:117], v[174:177], v[182:185], v[114:117]
	v_mfma_f32_16x16x32_bf16 v[102:105], v[166:169], v[190:193], v[102:105]
	v_mfma_f32_16x16x32_bf16 v[98:101], v[174:177], v[190:193], v[98:101]
	v_mfma_f32_16x16x32_bf16 v[84:87], v[166:169], v[198:201], v[84:87]
	v_mfma_f32_16x16x32_bf16 v[80:83], v[174:177], v[198:201], v[80:83]
	v_mfma_f32_16x16x32_bf16 v[68:71], v[166:169], v[206:209], v[68:71]
	v_mfma_f32_16x16x32_bf16 v[64:67], v[174:177], v[206:209], v[64:67]
	v_mfma_f32_16x16x32_bf16 v[118:121], v[170:173], v[186:189], v[118:121]
	v_mfma_f32_16x16x32_bf16 v[114:117], v[178:181], v[186:189], v[114:117]
	v_mfma_f32_16x16x32_bf16 v[102:105], v[170:173], v[194:197], v[102:105]
	v_mfma_f32_16x16x32_bf16 v[98:101], v[178:181], v[194:197], v[98:101]
	v_mfma_f32_16x16x32_bf16 v[84:87], v[170:173], v[202:205], v[84:87]
	v_mfma_f32_16x16x32_bf16 v[80:83], v[178:181], v[202:205], v[80:83]
	v_mfma_f32_16x16x32_bf16 v[68:71], v[170:173], v[210:213], v[68:71]
	v_mfma_f32_16x16x32_bf16 v[64:67], v[178:181], v[210:213], v[64:67]
	s_setprio 0
	s_barrier
	s_add_i32 s56, s56, s42
	v_lshl_add_u64 v[214:215], s[30:31], 0, v[132:133]
	s_mov_b32 m0, s56
	ds_read_b128 v[182:185], v152 offset:16384
	ds_read_b128 v[186:189], v152 offset:17408
	ds_read_b128 v[190:193], v152 offset:18432
	ds_read_b128 v[194:197], v152 offset:19456
	ds_read_b128 v[198:201], v152 offset:20480
	ds_read_b128 v[202:205], v152 offset:21504
	ds_read_b128 v[206:209], v152 offset:22528
	ds_read_b128 v[210:213], v152 offset:23552
	global_load_lds_dwordx4 v[214:215], off
	s_add_i32 m0, s56, 0x2000
	s_add_u32 s56, s30, 0x40000
	v_lshl_add_u64 v[216:217], s[30:31], 0, v[136:137]
	s_addc_u32 s57, s31, 0
	s_add_i32 s60, s60, s42
	global_load_lds_dwordx4 v[216:217], off
	v_lshl_add_u64 v[218:219], s[56:57], 0, v[132:133]
	s_mov_b32 m0, s60
	v_lshl_add_u64 v[220:221], s[34:35], 0, v[134:135]
	global_load_lds_dwordx4 v[218:219], off
	v_lshl_add_u64 v[218:219], s[56:57], 0, v[136:137]
	s_add_i32 m0, s60, 0x2000
	s_nop 0
	global_load_lds_dwordx4 v[218:219], off
	v_lshl_add_u64 v[218:219], s[34:35], 0, v[130:131]
	s_mov_b32 m0, s43
	s_nop 0
	global_load_lds_dwordx4 v[218:219], off
	s_mov_b32 m0, s44
	s_nop 0
	global_load_lds_dwordx4 v[220:221], off
	s_waitcnt vmcnt(8)
	s_waitcnt lgkmcnt(0)
	s_barrier
	s_setprio 1
	s_waitcnt lgkmcnt(0)
	v_mfma_f32_16x16x32_bf16 v[56:59], v[144:147], v[182:185], v[56:59]
	v_mfma_f32_16x16x32_bf16 v[60:63], v[158:161], v[182:185], v[60:63]
	v_mfma_f32_16x16x32_bf16 v[40:43], v[144:147], v[190:193], v[40:43]
	v_mfma_f32_16x16x32_bf16 v[44:47], v[158:161], v[190:193], v[44:47]
	v_mfma_f32_16x16x32_bf16 v[24:27], v[144:147], v[198:201], v[24:27]
	v_mfma_f32_16x16x32_bf16 v[28:31], v[158:161], v[198:201], v[28:31]
	v_mfma_f32_16x16x32_bf16 v[8:11], v[144:147], v[206:209], v[8:11]
	v_mfma_f32_16x16x32_bf16 v[12:15], v[158:161], v[206:209], v[12:15]
	v_mfma_f32_16x16x32_bf16 v[56:59], v[154:157], v[186:189], v[56:59]
	v_mfma_f32_16x16x32_bf16 v[60:63], v[162:165], v[186:189], v[60:63]
	v_mfma_f32_16x16x32_bf16 v[40:43], v[154:157], v[194:197], v[40:43]
	v_mfma_f32_16x16x32_bf16 v[44:47], v[162:165], v[194:197], v[44:47]
	v_mfma_f32_16x16x32_bf16 v[24:27], v[154:157], v[202:205], v[24:27]
	v_mfma_f32_16x16x32_bf16 v[28:31], v[162:165], v[202:205], v[28:31]
	v_mfma_f32_16x16x32_bf16 v[8:11], v[154:157], v[210:213], v[8:11]
	v_mfma_f32_16x16x32_bf16 v[12:15], v[162:165], v[210:213], v[12:15]
	v_mfma_f32_16x16x32_bf16 v[52:55], v[166:169], v[182:185], v[52:55]
	v_mfma_f32_16x16x32_bf16 v[48:51], v[174:177], v[182:185], v[48:51]
	v_mfma_f32_16x16x32_bf16 v[36:39], v[166:169], v[190:193], v[36:39]
	v_mfma_f32_16x16x32_bf16 v[32:35], v[174:177], v[190:193], v[32:35]
	v_mfma_f32_16x16x32_bf16 v[20:23], v[166:169], v[198:201], v[20:23]
	v_mfma_f32_16x16x32_bf16 v[16:19], v[174:177], v[198:201], v[16:19]
	v_mfma_f32_16x16x32_bf16 v[4:7], v[166:169], v[206:209], v[4:7]
	v_mfma_f32_16x16x32_bf16 v[0:3], v[174:177], v[206:209], v[0:3]
	v_mfma_f32_16x16x32_bf16 v[52:55], v[170:173], v[186:189], v[52:55]
	v_mfma_f32_16x16x32_bf16 v[48:51], v[178:181], v[186:189], v[48:51]
	v_mfma_f32_16x16x32_bf16 v[36:39], v[170:173], v[194:197], v[36:39]
	v_mfma_f32_16x16x32_bf16 v[32:35], v[178:181], v[194:197], v[32:35]
	v_mfma_f32_16x16x32_bf16 v[20:23], v[170:173], v[202:205], v[20:23]
	v_mfma_f32_16x16x32_bf16 v[16:19], v[178:181], v[202:205], v[16:19]
	v_mfma_f32_16x16x32_bf16 v[4:7], v[170:173], v[210:213], v[4:7]
	v_mfma_f32_16x16x32_bf16 v[0:3], v[178:181], v[210:213], v[0:3]
	s_setprio 0
	s_barrier
	s_add_i32 s56, 0, 0x18000
	v_add_u32_e32 v96, s56, v148
	s_add_i32 s57, 0, 0x1c000
	ds_read_b128 v[144:147], v96
	ds_read_b128 v[154:157], v96 offset:1024
	ds_read_b128 v[158:161], v96 offset:2048
	ds_read_b128 v[162:165], v96 offset:3072
	v_add_u32_e32 v96, s57, v148
	ds_read_b128 v[166:169], v96
	ds_read_b128 v[170:173], v96 offset:1024
	ds_read_b128 v[174:177], v96 offset:2048
	ds_read_b128 v[178:181], v96 offset:3072
	s_add_u32 s34, s34, 0x40000
	s_addc_u32 s35, s35, 0
	s_mov_b32 m0, s45
	v_lshl_add_u64 v[222:223], s[34:35], 0, v[130:131]
	ds_read_b128 v[182:185], v152 offset:32768
	ds_read_b128 v[186:189], v152 offset:33792
	ds_read_b128 v[190:193], v152 offset:34816
	ds_read_b128 v[194:197], v152 offset:35840
	ds_read_b128 v[198:201], v152 offset:36864
	ds_read_b128 v[202:205], v152 offset:37888
	ds_read_b128 v[206:209], v152 offset:38912
	ds_read_b128 v[210:213], v152 offset:39936
	global_load_lds_dwordx4 v[222:223], off
	v_lshl_add_u64 v[222:223], s[34:35], 0, v[134:135]
	s_mov_b32 m0, s46
	s_nop 0
	global_load_lds_dwordx4 v[222:223], off
	s_waitcnt vmcnt(8)
	s_waitcnt lgkmcnt(0)
	s_barrier
	s_setprio 1
	s_waitcnt lgkmcnt(0)
	v_mfma_f32_16x16x32_bf16 v[122:125], v[144:147], v[182:185], v[122:125]
	v_mfma_f32_16x16x32_bf16 v[126:129], v[158:161], v[182:185], v[126:129]
	v_mfma_f32_16x16x32_bf16 v[106:109], v[144:147], v[190:193], v[106:109]
	v_mfma_f32_16x16x32_bf16 v[110:113], v[158:161], v[190:193], v[110:113]
	v_mfma_f32_16x16x32_bf16 v[88:91], v[144:147], v[198:201], v[88:91]
	v_mfma_f32_16x16x32_bf16 v[92:95], v[158:161], v[198:201], v[92:95]
	v_mfma_f32_16x16x32_bf16 v[72:75], v[144:147], v[206:209], v[72:75]
	v_mfma_f32_16x16x32_bf16 v[76:79], v[158:161], v[206:209], v[76:79]
	v_mfma_f32_16x16x32_bf16 v[122:125], v[154:157], v[186:189], v[122:125]
	v_mfma_f32_16x16x32_bf16 v[126:129], v[162:165], v[186:189], v[126:129]
	v_mfma_f32_16x16x32_bf16 v[106:109], v[154:157], v[194:197], v[106:109]
	v_mfma_f32_16x16x32_bf16 v[110:113], v[162:165], v[194:197], v[110:113]
	v_mfma_f32_16x16x32_bf16 v[88:91], v[154:157], v[202:205], v[88:91]
	v_mfma_f32_16x16x32_bf16 v[92:95], v[162:165], v[202:205], v[92:95]
	v_mfma_f32_16x16x32_bf16 v[72:75], v[154:157], v[210:213], v[72:75]
	v_mfma_f32_16x16x32_bf16 v[76:79], v[162:165], v[210:213], v[76:79]
	v_mfma_f32_16x16x32_bf16 v[118:121], v[166:169], v[182:185], v[118:121]
	v_mfma_f32_16x16x32_bf16 v[114:117], v[174:177], v[182:185], v[114:117]
	v_mfma_f32_16x16x32_bf16 v[102:105], v[166:169], v[190:193], v[102:105]
	v_mfma_f32_16x16x32_bf16 v[98:101], v[174:177], v[190:193], v[98:101]
	v_mfma_f32_16x16x32_bf16 v[84:87], v[166:169], v[198:201], v[84:87]
	v_mfma_f32_16x16x32_bf16 v[80:83], v[174:177], v[198:201], v[80:83]
	v_mfma_f32_16x16x32_bf16 v[68:71], v[166:169], v[206:209], v[68:71]
	v_mfma_f32_16x16x32_bf16 v[64:67], v[174:177], v[206:209], v[64:67]
	v_mfma_f32_16x16x32_bf16 v[118:121], v[170:173], v[186:189], v[118:121]
	v_mfma_f32_16x16x32_bf16 v[114:117], v[178:181], v[186:189], v[114:117]
	v_mfma_f32_16x16x32_bf16 v[102:105], v[170:173], v[194:197], v[102:105]
	v_mfma_f32_16x16x32_bf16 v[98:101], v[178:181], v[194:197], v[98:101]
	v_mfma_f32_16x16x32_bf16 v[84:87], v[170:173], v[202:205], v[84:87]
	v_mfma_f32_16x16x32_bf16 v[80:83], v[178:181], v[202:205], v[80:83]
	v_mfma_f32_16x16x32_bf16 v[68:71], v[170:173], v[210:213], v[68:71]
	v_mfma_f32_16x16x32_bf16 v[64:67], v[178:181], v[210:213], v[64:67]
	s_setprio 0
	s_barrier
	s_add_i32 s34, s56, s42
	v_lshl_add_u64 v[214:215], v[214:215], 0, s[64:65]
	s_mov_b32 m0, s34
	ds_read_b128 v[182:185], v152 offset:49152
	ds_read_b128 v[186:189], v152 offset:50176
	ds_read_b128 v[190:193], v152 offset:51200
	ds_read_b128 v[194:197], v152 offset:52224
	ds_read_b128 v[198:201], v152 offset:53248
	ds_read_b128 v[202:205], v152 offset:54272
	ds_read_b128 v[206:209], v152 offset:55296
	ds_read_b128 v[210:213], v152 offset:56320
	global_load_lds_dwordx4 v[214:215], off
	s_add_i32 m0, s34, 0x2000
	s_add_u32 s30, s30, 0x40080
	v_lshl_add_u64 v[214:215], v[216:217], 0, s[64:65]
	s_addc_u32 s31, s31, 0
	s_add_i32 s34, s57, s42
	global_load_lds_dwordx4 v[214:215], off
	v_lshl_add_u64 v[214:215], s[30:31], 0, v[132:133]
	s_mov_b32 m0, s34
	s_nop 0
	global_load_lds_dwordx4 v[214:215], off
	v_lshl_add_u64 v[214:215], s[30:31], 0, v[136:137]
	s_add_i32 m0, s34, 0x2000
	s_nop 0
	global_load_lds_dwordx4 v[214:215], off
	v_lshl_add_u64 v[214:215], v[218:219], 0, s[64:65]
	s_mov_b32 m0, s48
	s_nop 0
	global_load_lds_dwordx4 v[214:215], off
	v_lshl_add_u64 v[214:215], v[220:221], 0, s[64:65]
	s_mov_b32 m0, s49
	s_nop 0
	global_load_lds_dwordx4 v[214:215], off
	s_waitcnt vmcnt(8)
	s_waitcnt lgkmcnt(0)
	s_barrier
	s_setprio 1
	s_waitcnt lgkmcnt(0)
	v_mfma_f32_16x16x32_bf16 v[56:59], v[144:147], v[182:185], v[56:59]
	v_mfma_f32_16x16x32_bf16 v[60:63], v[158:161], v[182:185], v[60:63]
	v_mfma_f32_16x16x32_bf16 v[40:43], v[144:147], v[190:193], v[40:43]
	v_mfma_f32_16x16x32_bf16 v[44:47], v[158:161], v[190:193], v[44:47]
	v_mfma_f32_16x16x32_bf16 v[24:27], v[144:147], v[198:201], v[24:27]
	v_mfma_f32_16x16x32_bf16 v[28:31], v[158:161], v[198:201], v[28:31]
	v_mfma_f32_16x16x32_bf16 v[8:11], v[144:147], v[206:209], v[8:11]
	v_mfma_f32_16x16x32_bf16 v[12:15], v[158:161], v[206:209], v[12:15]
	v_mfma_f32_16x16x32_bf16 v[56:59], v[154:157], v[186:189], v[56:59]
	v_mfma_f32_16x16x32_bf16 v[60:63], v[162:165], v[186:189], v[60:63]
	v_mfma_f32_16x16x32_bf16 v[40:43], v[154:157], v[194:197], v[40:43]
	v_mfma_f32_16x16x32_bf16 v[44:47], v[162:165], v[194:197], v[44:47]
	v_mfma_f32_16x16x32_bf16 v[24:27], v[154:157], v[202:205], v[24:27]
	v_mfma_f32_16x16x32_bf16 v[28:31], v[162:165], v[202:205], v[28:31]
	v_mfma_f32_16x16x32_bf16 v[8:11], v[154:157], v[210:213], v[8:11]
	v_mfma_f32_16x16x32_bf16 v[12:15], v[162:165], v[210:213], v[12:15]
	v_mfma_f32_16x16x32_bf16 v[52:55], v[166:169], v[182:185], v[52:55]
	v_mfma_f32_16x16x32_bf16 v[48:51], v[174:177], v[182:185], v[48:51]
	v_mfma_f32_16x16x32_bf16 v[36:39], v[166:169], v[190:193], v[36:39]
	v_mfma_f32_16x16x32_bf16 v[32:35], v[174:177], v[190:193], v[32:35]
	v_mfma_f32_16x16x32_bf16 v[20:23], v[166:169], v[198:201], v[20:23]
	v_mfma_f32_16x16x32_bf16 v[16:19], v[174:177], v[198:201], v[16:19]
	v_mfma_f32_16x16x32_bf16 v[4:7], v[166:169], v[206:209], v[4:7]
	v_mfma_f32_16x16x32_bf16 v[0:3], v[174:177], v[206:209], v[0:3]
	v_mfma_f32_16x16x32_bf16 v[52:55], v[170:173], v[186:189], v[52:55]
	v_mfma_f32_16x16x32_bf16 v[48:51], v[178:181], v[186:189], v[48:51]
	v_mfma_f32_16x16x32_bf16 v[36:39], v[170:173], v[194:197], v[36:39]
	v_mfma_f32_16x16x32_bf16 v[32:35], v[178:181], v[194:197], v[32:35]
	v_mfma_f32_16x16x32_bf16 v[20:23], v[170:173], v[202:205], v[20:23]
	v_mfma_f32_16x16x32_bf16 v[16:19], v[178:181], v[202:205], v[16:19]
	v_mfma_f32_16x16x32_bf16 v[4:7], v[170:173], v[210:213], v[4:7]
	v_mfma_f32_16x16x32_bf16 v[0:3], v[178:181], v[210:213], v[0:3]
	s_setprio 0
	s_barrier
	s_add_i32 s55, s55, 2
	s_add_u32 s28, s28, 0x100
	s_addc_u32 s29, s29, 0
	s_add_u32 s53, s53, 0x100
	s_addc_u32 s54, s54, 0
	s_cmp_gt_u32 s55, 13
	s_cbranch_scc0 .LBB0_461

.LBB0_633:
	s_ashr_i32 s17, s16, 31
	s_lshl_b64 s[18:19], s[16:17], 19
	s_add_u32 s18, s35, s18
	s_addc_u32 s19, s36, s19
	s_and_b64 s[20:21], s[4:5], exec
	s_cselect_b32 s17, s19, s27
	s_cselect_b32 s23, s18, s26
	s_ashr_i32 s15, s14, 31
	s_lshl_b64 s[20:21], s[14:15], 19
	s_add_u32 s20, s37, s20
	s_addc_u32 s21, s38, s21
	s_and_b64 s[30:31], s[4:5], exec
	s_cselect_b32 s15, s21, s29
	s_cselect_b32 s25, s20, s28
	s_add_u32 s26, s26, 0x40080
	s_addc_u32 s27, s27, 0
	s_add_u32 s49, s28, 0x100
	s_addc_u32 s50, s29, 0
	s_mov_b32 s51, -2
	s_add_u32 s28, s26, 0xfffc0080
	s_addc_u32 s29, s27, -1
	s_add_i32 s52, 0, 0x10000
	s_cmp_eq_u32 s51, 12
	s_cselect_b32 s31, s17, s29
	s_cselect_b32 s30, s23, s28
	s_cselect_b32 s29, s15, s50
	s_cselect_b32 s28, s25, s49
	s_add_i32 s54, 0, 0x14000
	v_add_u32_e32 v134, s52, v245
	v_add_u32_e32 v150, s54, v245
	ds_read_b128 v[122:125], v134
	ds_read_b128 v[126:129], v134 offset:1024
	ds_read_b128 v[130:133], v134 offset:2048
	ds_read_b128 v[134:137], v134 offset:3072
	ds_read_b128 v[138:141], v150
	ds_read_b128 v[142:145], v150 offset:1024
	ds_read_b128 v[146:149], v150 offset:2048
	ds_read_b128 v[150:153], v150 offset:3072
	v_lshl_add_u64 v[200:201], s[26:27], 0, v[204:205]
	s_add_i32 m0, s40, 0xc000
	ds_read_b128 v[162:165], v199
	ds_read_b128 v[166:169], v199 offset:1024
	ds_read_b128 v[170:173], v199 offset:2048
	ds_read_b128 v[174:177], v199 offset:3072
	ds_read_b128 v[178:181], v199 offset:4096
	ds_read_b128 v[182:185], v199 offset:5120
	ds_read_b128 v[186:189], v199 offset:6144
	ds_read_b128 v[194:197], v199 offset:7168
	global_load_lds_dwordx4 v[200:201], off
	v_lshl_add_u64 v[200:201], s[26:27], 0, v[206:207]
	s_add_i32 m0, s40, 0xe000
	s_nop 0
	global_load_lds_dwordx4 v[200:201], off
	s_waitcnt vmcnt(8)
	s_waitcnt lgkmcnt(0)
	s_barrier
	s_setprio 1
	s_waitcnt lgkmcnt(0)
	v_mfma_f32_16x16x32_bf16 v[158:161], v[122:125], v[162:165], 0
	v_mfma_f32_16x16x32_bf16 v[154:157], v[130:133], v[162:165], 0
	v_mfma_f32_16x16x32_bf16 v[110:113], v[122:125], v[170:173], 0
	v_mfma_f32_16x16x32_bf16 v[106:109], v[130:133], v[170:173], 0
	v_mfma_f32_16x16x32_bf16 v[92:95], v[122:125], v[178:181], 0
	v_mfma_f32_16x16x32_bf16 v[88:91], v[130:133], v[178:181], 0
	v_mfma_f32_16x16x32_bf16 v[76:79], v[122:125], v[186:189], 0
	v_mfma_f32_16x16x32_bf16 v[72:75], v[130:133], v[186:189], 0
	v_mfma_f32_16x16x32_bf16 v[158:161], v[126:129], v[166:169], v[158:161]
	v_mfma_f32_16x16x32_bf16 v[154:157], v[134:137], v[166:169], v[154:157]
	v_mfma_f32_16x16x32_bf16 v[110:113], v[126:129], v[174:177], v[110:113]
	v_mfma_f32_16x16x32_bf16 v[106:109], v[134:137], v[174:177], v[106:109]
	v_mfma_f32_16x16x32_bf16 v[92:95], v[126:129], v[182:185], v[92:95]
	v_mfma_f32_16x16x32_bf16 v[88:91], v[134:137], v[182:185], v[88:91]
	v_mfma_f32_16x16x32_bf16 v[76:79], v[126:129], v[194:197], v[76:79]
	v_mfma_f32_16x16x32_bf16 v[72:75], v[134:137], v[194:197], v[72:75]
	v_mfma_f32_16x16x32_bf16 v[118:121], v[138:141], v[162:165], 0
	v_mfma_f32_16x16x32_bf16 v[114:117], v[146:149], v[162:165], 0
	v_mfma_f32_16x16x32_bf16 v[102:105], v[138:141], v[170:173], 0
	v_mfma_f32_16x16x32_bf16 v[98:101], v[146:149], v[170:173], 0
	v_mfma_f32_16x16x32_bf16 v[84:87], v[138:141], v[178:181], 0
	v_mfma_f32_16x16x32_bf16 v[80:83], v[146:149], v[178:181], 0
	v_mfma_f32_16x16x32_bf16 v[68:71], v[138:141], v[186:189], 0
	v_mfma_f32_16x16x32_bf16 v[64:67], v[146:149], v[186:189], 0
	v_mfma_f32_16x16x32_bf16 v[118:121], v[142:145], v[166:169], v[118:121]
	v_mfma_f32_16x16x32_bf16 v[114:117], v[150:153], v[166:169], v[114:117]
	v_mfma_f32_16x16x32_bf16 v[102:105], v[142:145], v[174:177], v[102:105]
	v_mfma_f32_16x16x32_bf16 v[98:101], v[150:153], v[174:177], v[98:101]
	v_mfma_f32_16x16x32_bf16 v[84:87], v[142:145], v[182:185], v[84:87]
	v_mfma_f32_16x16x32_bf16 v[80:83], v[150:153], v[182:185], v[80:83]
	v_mfma_f32_16x16x32_bf16 v[68:71], v[142:145], v[194:197], v[68:71]
	v_mfma_f32_16x16x32_bf16 v[64:67], v[150:153], v[194:197], v[64:67]
	s_setprio 0
	s_barrier
	s_add_i32 s52, s52, s39
	v_lshl_add_u64 v[200:201], s[28:29], 0, v[96:97]
	s_mov_b32 m0, s52
	ds_read_b128 v[162:165], v199 offset:16384
	ds_read_b128 v[166:169], v199 offset:17408
	ds_read_b128 v[170:173], v199 offset:18432
	ds_read_b128 v[174:177], v199 offset:19456
	ds_read_b128 v[178:181], v199 offset:20480
	ds_read_b128 v[182:185], v199 offset:21504
	ds_read_b128 v[186:189], v199 offset:22528
	ds_read_b128 v[194:197], v199 offset:23552
	global_load_lds_dwordx4 v[200:201], off
	s_add_i32 m0, s52, 0x2000
	s_add_u32 s52, s28, 0x40000
	v_lshl_add_u64 v[208:209], s[28:29], 0, v[202:203]
	s_addc_u32 s53, s29, 0
	s_add_i32 s54, s54, s39
	global_load_lds_dwordx4 v[208:209], off
	v_lshl_add_u64 v[210:211], s[52:53], 0, v[96:97]
	s_mov_b32 m0, s54
	v_lshl_add_u64 v[212:213], s[30:31], 0, v[192:193]
	global_load_lds_dwordx4 v[210:211], off
	v_lshl_add_u64 v[210:211], s[52:53], 0, v[202:203]
	s_add_i32 m0, s54, 0x2000
	s_nop 0
	global_load_lds_dwordx4 v[210:211], off
	v_lshl_add_u64 v[210:211], s[30:31], 0, v[190:191]
	s_mov_b32 m0, s40
	s_nop 0
	global_load_lds_dwordx4 v[210:211], off
	s_mov_b32 m0, s41
	s_nop 0
	global_load_lds_dwordx4 v[212:213], off
	s_waitcnt vmcnt(8)
	s_waitcnt lgkmcnt(0)
	s_barrier
	s_setprio 1
	s_waitcnt lgkmcnt(0)
	v_mfma_f32_16x16x32_bf16 v[60:63], v[122:125], v[162:165], 0
	v_mfma_f32_16x16x32_bf16 v[56:59], v[130:133], v[162:165], 0
	v_mfma_f32_16x16x32_bf16 v[44:47], v[122:125], v[170:173], 0
	v_mfma_f32_16x16x32_bf16 v[40:43], v[130:133], v[170:173], 0
	v_mfma_f32_16x16x32_bf16 v[28:31], v[122:125], v[178:181], 0
	v_mfma_f32_16x16x32_bf16 v[24:27], v[130:133], v[178:181], 0
	v_mfma_f32_16x16x32_bf16 v[12:15], v[122:125], v[186:189], 0
	v_mfma_f32_16x16x32_bf16 v[8:11], v[130:133], v[186:189], 0
	v_mfma_f32_16x16x32_bf16 v[60:63], v[126:129], v[166:169], v[60:63]
	v_mfma_f32_16x16x32_bf16 v[56:59], v[134:137], v[166:169], v[56:59]
	v_mfma_f32_16x16x32_bf16 v[44:47], v[126:129], v[174:177], v[44:47]
	v_mfma_f32_16x16x32_bf16 v[40:43], v[134:137], v[174:177], v[40:43]
	v_mfma_f32_16x16x32_bf16 v[28:31], v[126:129], v[182:185], v[28:31]
	v_mfma_f32_16x16x32_bf16 v[24:27], v[134:137], v[182:185], v[24:27]
	v_mfma_f32_16x16x32_bf16 v[12:15], v[126:129], v[194:197], v[12:15]
	v_mfma_f32_16x16x32_bf16 v[8:11], v[134:137], v[194:197], v[8:11]
	v_mfma_f32_16x16x32_bf16 v[52:55], v[138:141], v[162:165], 0
	v_mfma_f32_16x16x32_bf16 v[48:51], v[146:149], v[162:165], 0
	v_mfma_f32_16x16x32_bf16 v[36:39], v[138:141], v[170:173], 0
	v_mfma_f32_16x16x32_bf16 v[32:35], v[146:149], v[170:173], 0
	v_mfma_f32_16x16x32_bf16 v[20:23], v[138:141], v[178:181], 0
	v_mfma_f32_16x16x32_bf16 v[16:19], v[146:149], v[178:181], 0
	v_mfma_f32_16x16x32_bf16 v[4:7], v[138:141], v[186:189], 0
	v_mfma_f32_16x16x32_bf16 v[0:3], v[146:149], v[186:189], 0
	v_mfma_f32_16x16x32_bf16 v[52:55], v[142:145], v[166:169], v[52:55]
	v_mfma_f32_16x16x32_bf16 v[48:51], v[150:153], v[166:169], v[48:51]
	v_mfma_f32_16x16x32_bf16 v[36:39], v[142:145], v[174:177], v[36:39]
	v_mfma_f32_16x16x32_bf16 v[32:35], v[150:153], v[174:177], v[32:35]
	v_mfma_f32_16x16x32_bf16 v[20:23], v[142:145], v[182:185], v[20:23]
	v_mfma_f32_16x16x32_bf16 v[16:19], v[150:153], v[182:185], v[16:19]
	v_mfma_f32_16x16x32_bf16 v[4:7], v[142:145], v[194:197], v[4:7]
	v_mfma_f32_16x16x32_bf16 v[0:3], v[150:153], v[194:197], v[0:3]
	s_setprio 0
	s_barrier
	s_add_i32 s52, 0, 0x18000
	s_add_i32 s53, 0, 0x1c000
	v_add_u32_e32 v134, s52, v245
	v_add_u32_e32 v150, s53, v245
	ds_read_b128 v[122:125], v134
	ds_read_b128 v[126:129], v134 offset:1024
	ds_read_b128 v[130:133], v134 offset:2048
	ds_read_b128 v[134:137], v134 offset:3072
	ds_read_b128 v[138:141], v150
	ds_read_b128 v[142:145], v150 offset:1024
	ds_read_b128 v[146:149], v150 offset:2048
	ds_read_b128 v[150:153], v150 offset:3072
	s_add_u32 s30, s30, 0x40000
	s_addc_u32 s31, s31, 0
	s_mov_b32 m0, s42
	v_lshl_add_u64 v[214:215], s[30:31], 0, v[190:191]
	ds_read_b128 v[162:165], v199 offset:32768
	ds_read_b128 v[166:169], v199 offset:33792
	ds_read_b128 v[170:173], v199 offset:34816
	ds_read_b128 v[174:177], v199 offset:35840
	ds_read_b128 v[178:181], v199 offset:36864
	ds_read_b128 v[182:185], v199 offset:37888
	ds_read_b128 v[186:189], v199 offset:38912
	ds_read_b128 v[194:197], v199 offset:39936
	global_load_lds_dwordx4 v[214:215], off
	v_lshl_add_u64 v[214:215], s[30:31], 0, v[192:193]
	s_mov_b32 m0, s43
	s_nop 0
	global_load_lds_dwordx4 v[214:215], off
	s_waitcnt vmcnt(8)
	s_waitcnt lgkmcnt(0)
	s_barrier
	s_setprio 1
	s_waitcnt lgkmcnt(0)
	v_mfma_f32_16x16x32_bf16 v[158:161], v[122:125], v[162:165], v[158:161]
	v_mfma_f32_16x16x32_bf16 v[154:157], v[130:133], v[162:165], v[154:157]
	v_mfma_f32_16x16x32_bf16 v[110:113], v[122:125], v[170:173], v[110:113]
	v_mfma_f32_16x16x32_bf16 v[106:109], v[130:133], v[170:173], v[106:109]
	v_mfma_f32_16x16x32_bf16 v[92:95], v[122:125], v[178:181], v[92:95]
	v_mfma_f32_16x16x32_bf16 v[88:91], v[130:133], v[178:181], v[88:91]
	v_mfma_f32_16x16x32_bf16 v[76:79], v[122:125], v[186:189], v[76:79]
	v_mfma_f32_16x16x32_bf16 v[72:75], v[130:133], v[186:189], v[72:75]
	v_mfma_f32_16x16x32_bf16 v[158:161], v[126:129], v[166:169], v[158:161]
	v_mfma_f32_16x16x32_bf16 v[154:157], v[134:137], v[166:169], v[154:157]
	v_mfma_f32_16x16x32_bf16 v[110:113], v[126:129], v[174:177], v[110:113]
	v_mfma_f32_16x16x32_bf16 v[106:109], v[134:137], v[174:177], v[106:109]
	v_mfma_f32_16x16x32_bf16 v[92:95], v[126:129], v[182:185], v[92:95]
	v_mfma_f32_16x16x32_bf16 v[88:91], v[134:137], v[182:185], v[88:91]
	v_mfma_f32_16x16x32_bf16 v[76:79], v[126:129], v[194:197], v[76:79]
	v_mfma_f32_16x16x32_bf16 v[72:75], v[134:137], v[194:197], v[72:75]
	v_mfma_f32_16x16x32_bf16 v[118:121], v[138:141], v[162:165], v[118:121]
	v_mfma_f32_16x16x32_bf16 v[114:117], v[146:149], v[162:165], v[114:117]
	v_mfma_f32_16x16x32_bf16 v[102:105], v[138:141], v[170:173], v[102:105]
	v_mfma_f32_16x16x32_bf16 v[98:101], v[146:149], v[170:173], v[98:101]
	v_mfma_f32_16x16x32_bf16 v[84:87], v[138:141], v[178:181], v[84:87]
	v_mfma_f32_16x16x32_bf16 v[80:83], v[146:149], v[178:181], v[80:83]
	v_mfma_f32_16x16x32_bf16 v[68:71], v[138:141], v[186:189], v[68:71]
	v_mfma_f32_16x16x32_bf16 v[64:67], v[146:149], v[186:189], v[64:67]
	v_mfma_f32_16x16x32_bf16 v[118:121], v[142:145], v[166:169], v[118:121]
	v_mfma_f32_16x16x32_bf16 v[114:117], v[150:153], v[166:169], v[114:117]
	v_mfma_f32_16x16x32_bf16 v[102:105], v[142:145], v[174:177], v[102:105]
	v_mfma_f32_16x16x32_bf16 v[98:101], v[150:153], v[174:177], v[98:101]
	v_mfma_f32_16x16x32_bf16 v[84:87], v[142:145], v[182:185], v[84:87]
	v_mfma_f32_16x16x32_bf16 v[80:83], v[150:153], v[182:185], v[80:83]
	v_mfma_f32_16x16x32_bf16 v[68:71], v[142:145], v[194:197], v[68:71]
	v_mfma_f32_16x16x32_bf16 v[64:67], v[150:153], v[194:197], v[64:67]
	s_setprio 0
	s_barrier
	s_add_i32 s30, s52, s39
	v_lshl_add_u64 v[200:201], v[200:201], 0, s[64:65]
	s_mov_b32 m0, s30
	ds_read_b128 v[162:165], v199 offset:49152
	ds_read_b128 v[166:169], v199 offset:50176
	ds_read_b128 v[170:173], v199 offset:51200
	ds_read_b128 v[174:177], v199 offset:52224
	ds_read_b128 v[178:181], v199 offset:53248
	ds_read_b128 v[182:185], v199 offset:54272
	ds_read_b128 v[186:189], v199 offset:55296
	ds_read_b128 v[194:197], v199 offset:56320
	global_load_lds_dwordx4 v[200:201], off
	s_add_i32 m0, s30, 0x2000
	s_add_u32 s28, s28, 0x40080
	v_lshl_add_u64 v[200:201], v[208:209], 0, s[64:65]
	s_addc_u32 s29, s29, 0
	s_add_i32 s30, s53, s39
	global_load_lds_dwordx4 v[200:201], off
	v_lshl_add_u64 v[200:201], s[28:29], 0, v[96:97]
	s_mov_b32 m0, s30
	s_nop 0
	global_load_lds_dwordx4 v[200:201], off
	v_lshl_add_u64 v[200:201], s[28:29], 0, v[202:203]
	s_add_i32 m0, s30, 0x2000
	s_nop 0
	global_load_lds_dwordx4 v[200:201], off
	v_lshl_add_u64 v[200:201], v[210:211], 0, s[64:65]
	s_mov_b32 m0, s45
	s_nop 0
	global_load_lds_dwordx4 v[200:201], off
	v_lshl_add_u64 v[200:201], v[212:213], 0, s[64:65]
	s_mov_b32 m0, s46
	s_nop 0
	global_load_lds_dwordx4 v[200:201], off
	s_waitcnt vmcnt(8)
	s_waitcnt lgkmcnt(0)
	s_barrier
	s_setprio 1
	s_waitcnt lgkmcnt(0)
	v_mfma_f32_16x16x32_bf16 v[60:63], v[122:125], v[162:165], v[60:63]
	v_mfma_f32_16x16x32_bf16 v[56:59], v[130:133], v[162:165], v[56:59]
	v_mfma_f32_16x16x32_bf16 v[44:47], v[122:125], v[170:173], v[44:47]
	v_mfma_f32_16x16x32_bf16 v[40:43], v[130:133], v[170:173], v[40:43]
	v_mfma_f32_16x16x32_bf16 v[28:31], v[122:125], v[178:181], v[28:31]
	v_mfma_f32_16x16x32_bf16 v[24:27], v[130:133], v[178:181], v[24:27]
	v_mfma_f32_16x16x32_bf16 v[12:15], v[122:125], v[186:189], v[12:15]
	v_mfma_f32_16x16x32_bf16 v[8:11], v[130:133], v[186:189], v[8:11]
	v_mfma_f32_16x16x32_bf16 v[60:63], v[126:129], v[166:169], v[60:63]
	v_mfma_f32_16x16x32_bf16 v[56:59], v[134:137], v[166:169], v[56:59]
	v_mfma_f32_16x16x32_bf16 v[44:47], v[126:129], v[174:177], v[44:47]
	v_mfma_f32_16x16x32_bf16 v[40:43], v[134:137], v[174:177], v[40:43]
	v_mfma_f32_16x16x32_bf16 v[28:31], v[126:129], v[182:185], v[28:31]
	v_mfma_f32_16x16x32_bf16 v[24:27], v[134:137], v[182:185], v[24:27]
	v_mfma_f32_16x16x32_bf16 v[12:15], v[126:129], v[194:197], v[12:15]
	v_mfma_f32_16x16x32_bf16 v[8:11], v[134:137], v[194:197], v[8:11]
	v_mfma_f32_16x16x32_bf16 v[52:55], v[138:141], v[162:165], v[52:55]
	v_mfma_f32_16x16x32_bf16 v[48:51], v[146:149], v[162:165], v[48:51]
	v_mfma_f32_16x16x32_bf16 v[36:39], v[138:141], v[170:173], v[36:39]
	v_mfma_f32_16x16x32_bf16 v[32:35], v[146:149], v[170:173], v[32:35]
	v_mfma_f32_16x16x32_bf16 v[20:23], v[138:141], v[178:181], v[20:23]
	v_mfma_f32_16x16x32_bf16 v[16:19], v[146:149], v[178:181], v[16:19]
	v_mfma_f32_16x16x32_bf16 v[4:7], v[138:141], v[186:189], v[4:7]
	v_mfma_f32_16x16x32_bf16 v[0:3], v[146:149], v[186:189], v[0:3]
	v_mfma_f32_16x16x32_bf16 v[52:55], v[142:145], v[166:169], v[52:55]
	v_mfma_f32_16x16x32_bf16 v[48:51], v[150:153], v[166:169], v[48:51]
	v_mfma_f32_16x16x32_bf16 v[36:39], v[142:145], v[174:177], v[36:39]
	v_mfma_f32_16x16x32_bf16 v[32:35], v[150:153], v[174:177], v[32:35]
	v_mfma_f32_16x16x32_bf16 v[20:23], v[142:145], v[182:185], v[20:23]
	v_mfma_f32_16x16x32_bf16 v[16:19], v[150:153], v[182:185], v[16:19]
	v_mfma_f32_16x16x32_bf16 v[4:7], v[142:145], v[194:197], v[4:7]
	v_mfma_f32_16x16x32_bf16 v[0:3], v[150:153], v[194:197], v[0:3]
	s_setprio 0
	s_barrier
	s_add_i32 s51, s51, 2
	s_add_u32 s26, s26, 0x100
	s_addc_u32 s27, s27, 0
	s_add_u32 s49, s49, 0x100
	s_addc_u32 s50, s50, 0
	s_cmp_gt_u32 s51, 13
	s_cbranch_scc1 .Lpeel_done_634
.LBB0_634:
	s_add_u32 s28, s26, 0xfffc0080
	s_addc_u32 s29, s27, -1
	s_add_i32 s52, 0, 0x10000
	s_cmp_eq_u32 s51, 12
	s_cselect_b32 s31, s17, s29
	s_cselect_b32 s30, s23, s28
	s_cselect_b32 s29, s15, s50
	s_cselect_b32 s28, s25, s49
	s_add_i32 s54, 0, 0x14000
	v_add_u32_e32 v134, s52, v245
	v_add_u32_e32 v150, s54, v245
	ds_read_b128 v[122:125], v134
	ds_read_b128 v[126:129], v134 offset:1024
	ds_read_b128 v[130:133], v134 offset:2048
	ds_read_b128 v[134:137], v134 offset:3072
	ds_read_b128 v[138:141], v150
	ds_read_b128 v[142:145], v150 offset:1024
	ds_read_b128 v[146:149], v150 offset:2048
	ds_read_b128 v[150:153], v150 offset:3072
	v_lshl_add_u64 v[200:201], s[26:27], 0, v[204:205]
	s_add_i32 m0, s40, 0xc000
	ds_read_b128 v[162:165], v199
	ds_read_b128 v[166:169], v199 offset:1024
	ds_read_b128 v[170:173], v199 offset:2048
	ds_read_b128 v[174:177], v199 offset:3072
	ds_read_b128 v[178:181], v199 offset:4096
	ds_read_b128 v[182:185], v199 offset:5120
	ds_read_b128 v[186:189], v199 offset:6144
	ds_read_b128 v[194:197], v199 offset:7168
	global_load_lds_dwordx4 v[200:201], off
	v_lshl_add_u64 v[200:201], s[26:27], 0, v[206:207]
	s_add_i32 m0, s40, 0xe000
	s_nop 0
	global_load_lds_dwordx4 v[200:201], off
	s_waitcnt vmcnt(8)
	s_waitcnt lgkmcnt(0)
	s_barrier
	s_setprio 1
	s_waitcnt lgkmcnt(0)
	v_mfma_f32_16x16x32_bf16 v[158:161], v[122:125], v[162:165], v[158:161]
	v_mfma_f32_16x16x32_bf16 v[154:157], v[130:133], v[162:165], v[154:157]
	v_mfma_f32_16x16x32_bf16 v[110:113], v[122:125], v[170:173], v[110:113]
	v_mfma_f32_16x16x32_bf16 v[106:109], v[130:133], v[170:173], v[106:109]
	v_mfma_f32_16x16x32_bf16 v[92:95], v[122:125], v[178:181], v[92:95]
	v_mfma_f32_16x16x32_bf16 v[88:91], v[130:133], v[178:181], v[88:91]
	v_mfma_f32_16x16x32_bf16 v[76:79], v[122:125], v[186:189], v[76:79]
	v_mfma_f32_16x16x32_bf16 v[72:75], v[130:133], v[186:189], v[72:75]
	v_mfma_f32_16x16x32_bf16 v[158:161], v[126:129], v[166:169], v[158:161]
	v_mfma_f32_16x16x32_bf16 v[154:157], v[134:137], v[166:169], v[154:157]
	v_mfma_f32_16x16x32_bf16 v[110:113], v[126:129], v[174:177], v[110:113]
	v_mfma_f32_16x16x32_bf16 v[106:109], v[134:137], v[174:177], v[106:109]
	v_mfma_f32_16x16x32_bf16 v[92:95], v[126:129], v[182:185], v[92:95]
	v_mfma_f32_16x16x32_bf16 v[88:91], v[134:137], v[182:185], v[88:91]
	v_mfma_f32_16x16x32_bf16 v[76:79], v[126:129], v[194:197], v[76:79]
	v_mfma_f32_16x16x32_bf16 v[72:75], v[134:137], v[194:197], v[72:75]
	v_mfma_f32_16x16x32_bf16 v[118:121], v[138:141], v[162:165], v[118:121]
	v_mfma_f32_16x16x32_bf16 v[114:117], v[146:149], v[162:165], v[114:117]
	v_mfma_f32_16x16x32_bf16 v[102:105], v[138:141], v[170:173], v[102:105]
	v_mfma_f32_16x16x32_bf16 v[98:101], v[146:149], v[170:173], v[98:101]
	v_mfma_f32_16x16x32_bf16 v[84:87], v[138:141], v[178:181], v[84:87]
	v_mfma_f32_16x16x32_bf16 v[80:83], v[146:149], v[178:181], v[80:83]
	v_mfma_f32_16x16x32_bf16 v[68:71], v[138:141], v[186:189], v[68:71]
	v_mfma_f32_16x16x32_bf16 v[64:67], v[146:149], v[186:189], v[64:67]
	v_mfma_f32_16x16x32_bf16 v[118:121], v[142:145], v[166:169], v[118:121]
	v_mfma_f32_16x16x32_bf16 v[114:117], v[150:153], v[166:169], v[114:117]
	v_mfma_f32_16x16x32_bf16 v[102:105], v[142:145], v[174:177], v[102:105]
	v_mfma_f32_16x16x32_bf16 v[98:101], v[150:153], v[174:177], v[98:101]
	v_mfma_f32_16x16x32_bf16 v[84:87], v[142:145], v[182:185], v[84:87]
	v_mfma_f32_16x16x32_bf16 v[80:83], v[150:153], v[182:185], v[80:83]
	v_mfma_f32_16x16x32_bf16 v[68:71], v[142:145], v[194:197], v[68:71]
	v_mfma_f32_16x16x32_bf16 v[64:67], v[150:153], v[194:197], v[64:67]
	s_setprio 0
	s_barrier
	s_add_i32 s52, s52, s39
	v_lshl_add_u64 v[200:201], s[28:29], 0, v[96:97]
	s_mov_b32 m0, s52
	ds_read_b128 v[162:165], v199 offset:16384
	ds_read_b128 v[166:169], v199 offset:17408
	ds_read_b128 v[170:173], v199 offset:18432
	ds_read_b128 v[174:177], v199 offset:19456
	ds_read_b128 v[178:181], v199 offset:20480
	ds_read_b128 v[182:185], v199 offset:21504
	ds_read_b128 v[186:189], v199 offset:22528
	ds_read_b128 v[194:197], v199 offset:23552
	global_load_lds_dwordx4 v[200:201], off
	s_add_i32 m0, s52, 0x2000
	s_add_u32 s52, s28, 0x40000
	v_lshl_add_u64 v[208:209], s[28:29], 0, v[202:203]
	s_addc_u32 s53, s29, 0
	s_add_i32 s54, s54, s39
	global_load_lds_dwordx4 v[208:209], off
	v_lshl_add_u64 v[210:211], s[52:53], 0, v[96:97]
	s_mov_b32 m0, s54
	v_lshl_add_u64 v[212:213], s[30:31], 0, v[192:193]
	global_load_lds_dwordx4 v[210:211], off
	v_lshl_add_u64 v[210:211], s[52:53], 0, v[202:203]
	s_add_i32 m0, s54, 0x2000
	s_nop 0
	global_load_lds_dwordx4 v[210:211], off
	v_lshl_add_u64 v[210:211], s[30:31], 0, v[190:191]
	s_mov_b32 m0, s40
	s_nop 0
	global_load_lds_dwordx4 v[210:211], off
	s_mov_b32 m0, s41
	s_nop 0
	global_load_lds_dwordx4 v[212:213], off
	s_waitcnt vmcnt(8)
	s_waitcnt lgkmcnt(0)
	s_barrier
	s_setprio 1
	s_waitcnt lgkmcnt(0)
	v_mfma_f32_16x16x32_bf16 v[60:63], v[122:125], v[162:165], v[60:63]
	v_mfma_f32_16x16x32_bf16 v[56:59], v[130:133], v[162:165], v[56:59]
	v_mfma_f32_16x16x32_bf16 v[44:47], v[122:125], v[170:173], v[44:47]
	v_mfma_f32_16x16x32_bf16 v[40:43], v[130:133], v[170:173], v[40:43]
	v_mfma_f32_16x16x32_bf16 v[28:31], v[122:125], v[178:181], v[28:31]
	v_mfma_f32_16x16x32_bf16 v[24:27], v[130:133], v[178:181], v[24:27]
	v_mfma_f32_16x16x32_bf16 v[12:15], v[122:125], v[186:189], v[12:15]
	v_mfma_f32_16x16x32_bf16 v[8:11], v[130:133], v[186:189], v[8:11]
	v_mfma_f32_16x16x32_bf16 v[60:63], v[126:129], v[166:169], v[60:63]
	v_mfma_f32_16x16x32_bf16 v[56:59], v[134:137], v[166:169], v[56:59]
	v_mfma_f32_16x16x32_bf16 v[44:47], v[126:129], v[174:177], v[44:47]
	v_mfma_f32_16x16x32_bf16 v[40:43], v[134:137], v[174:177], v[40:43]
	v_mfma_f32_16x16x32_bf16 v[28:31], v[126:129], v[182:185], v[28:31]
	v_mfma_f32_16x16x32_bf16 v[24:27], v[134:137], v[182:185], v[24:27]
	v_mfma_f32_16x16x32_bf16 v[12:15], v[126:129], v[194:197], v[12:15]
	v_mfma_f32_16x16x32_bf16 v[8:11], v[134:137], v[194:197], v[8:11]
	v_mfma_f32_16x16x32_bf16 v[52:55], v[138:141], v[162:165], v[52:55]
	v_mfma_f32_16x16x32_bf16 v[48:51], v[146:149], v[162:165], v[48:51]
	v_mfma_f32_16x16x32_bf16 v[36:39], v[138:141], v[170:173], v[36:39]
	v_mfma_f32_16x16x32_bf16 v[32:35], v[146:149], v[170:173], v[32:35]
	v_mfma_f32_16x16x32_bf16 v[20:23], v[138:141], v[178:181], v[20:23]
	v_mfma_f32_16x16x32_bf16 v[16:19], v[146:149], v[178:181], v[16:19]
	v_mfma_f32_16x16x32_bf16 v[4:7], v[138:141], v[186:189], v[4:7]
	v_mfma_f32_16x16x32_bf16 v[0:3], v[146:149], v[186:189], v[0:3]
	v_mfma_f32_16x16x32_bf16 v[52:55], v[142:145], v[166:169], v[52:55]
	v_mfma_f32_16x16x32_bf16 v[48:51], v[150:153], v[166:169], v[48:51]
	v_mfma_f32_16x16x32_bf16 v[36:39], v[142:145], v[174:177], v[36:39]
	v_mfma_f32_16x16x32_bf16 v[32:35], v[150:153], v[174:177], v[32:35]
	v_mfma_f32_16x16x32_bf16 v[20:23], v[142:145], v[182:185], v[20:23]
	v_mfma_f32_16x16x32_bf16 v[16:19], v[150:153], v[182:185], v[16:19]
	v_mfma_f32_16x16x32_bf16 v[4:7], v[142:145], v[194:197], v[4:7]
	v_mfma_f32_16x16x32_bf16 v[0:3], v[150:153], v[194:197], v[0:3]
	s_setprio 0
	s_barrier
	s_add_i32 s52, 0, 0x18000
	s_add_i32 s53, 0, 0x1c000
	v_add_u32_e32 v134, s52, v245
	v_add_u32_e32 v150, s53, v245
	ds_read_b128 v[122:125], v134
	ds_read_b128 v[126:129], v134 offset:1024
	ds_read_b128 v[130:133], v134 offset:2048
	ds_read_b128 v[134:137], v134 offset:3072
	ds_read_b128 v[138:141], v150
	ds_read_b128 v[142:145], v150 offset:1024
	ds_read_b128 v[146:149], v150 offset:2048
	ds_read_b128 v[150:153], v150 offset:3072
	s_add_u32 s30, s30, 0x40000
	s_addc_u32 s31, s31, 0
	s_mov_b32 m0, s42
	v_lshl_add_u64 v[214:215], s[30:31], 0, v[190:191]
	ds_read_b128 v[162:165], v199 offset:32768
	ds_read_b128 v[166:169], v199 offset:33792
	ds_read_b128 v[170:173], v199 offset:34816
	ds_read_b128 v[174:177], v199 offset:35840
	ds_read_b128 v[178:181], v199 offset:36864
	ds_read_b128 v[182:185], v199 offset:37888
	ds_read_b128 v[186:189], v199 offset:38912
	ds_read_b128 v[194:197], v199 offset:39936
	global_load_lds_dwordx4 v[214:215], off
	v_lshl_add_u64 v[214:215], s[30:31], 0, v[192:193]
	s_mov_b32 m0, s43
	s_nop 0
	global_load_lds_dwordx4 v[214:215], off
	s_waitcnt vmcnt(8)
	s_waitcnt lgkmcnt(0)
	s_barrier
	s_setprio 1
	s_waitcnt lgkmcnt(0)
	v_mfma_f32_16x16x32_bf16 v[158:161], v[122:125], v[162:165], v[158:161]
	v_mfma_f32_16x16x32_bf16 v[154:157], v[130:133], v[162:165], v[154:157]
	v_mfma_f32_16x16x32_bf16 v[110:113], v[122:125], v[170:173], v[110:113]
	v_mfma_f32_16x16x32_bf16 v[106:109], v[130:133], v[170:173], v[106:109]
	v_mfma_f32_16x16x32_bf16 v[92:95], v[122:125], v[178:181], v[92:95]
	v_mfma_f32_16x16x32_bf16 v[88:91], v[130:133], v[178:181], v[88:91]
	v_mfma_f32_16x16x32_bf16 v[76:79], v[122:125], v[186:189], v[76:79]
	v_mfma_f32_16x16x32_bf16 v[72:75], v[130:133], v[186:189], v[72:75]
	v_mfma_f32_16x16x32_bf16 v[158:161], v[126:129], v[166:169], v[158:161]
	v_mfma_f32_16x16x32_bf16 v[154:157], v[134:137], v[166:169], v[154:157]
	v_mfma_f32_16x16x32_bf16 v[110:113], v[126:129], v[174:177], v[110:113]
	v_mfma_f32_16x16x32_bf16 v[106:109], v[134:137], v[174:177], v[106:109]
	v_mfma_f32_16x16x32_bf16 v[92:95], v[126:129], v[182:185], v[92:95]
	v_mfma_f32_16x16x32_bf16 v[88:91], v[134:137], v[182:185], v[88:91]
	v_mfma_f32_16x16x32_bf16 v[76:79], v[126:129], v[194:197], v[76:79]
	v_mfma_f32_16x16x32_bf16 v[72:75], v[134:137], v[194:197], v[72:75]
	v_mfma_f32_16x16x32_bf16 v[118:121], v[138:141], v[162:165], v[118:121]
	v_mfma_f32_16x16x32_bf16 v[114:117], v[146:149], v[162:165], v[114:117]
	v_mfma_f32_16x16x32_bf16 v[102:105], v[138:141], v[170:173], v[102:105]
	v_mfma_f32_16x16x32_bf16 v[98:101], v[146:149], v[170:173], v[98:101]
	v_mfma_f32_16x16x32_bf16 v[84:87], v[138:141], v[178:181], v[84:87]
	v_mfma_f32_16x16x32_bf16 v[80:83], v[146:149], v[178:181], v[80:83]
	v_mfma_f32_16x16x32_bf16 v[68:71], v[138:141], v[186:189], v[68:71]
	v_mfma_f32_16x16x32_bf16 v[64:67], v[146:149], v[186:189], v[64:67]
	v_mfma_f32_16x16x32_bf16 v[118:121], v[142:145], v[166:169], v[118:121]
	v_mfma_f32_16x16x32_bf16 v[114:117], v[150:153], v[166:169], v[114:117]
	v_mfma_f32_16x16x32_bf16 v[102:105], v[142:145], v[174:177], v[102:105]
	v_mfma_f32_16x16x32_bf16 v[98:101], v[150:153], v[174:177], v[98:101]
	v_mfma_f32_16x16x32_bf16 v[84:87], v[142:145], v[182:185], v[84:87]
	v_mfma_f32_16x16x32_bf16 v[80:83], v[150:153], v[182:185], v[80:83]
	v_mfma_f32_16x16x32_bf16 v[68:71], v[142:145], v[194:197], v[68:71]
	v_mfma_f32_16x16x32_bf16 v[64:67], v[150:153], v[194:197], v[64:67]
	s_setprio 0
	s_barrier
	s_add_i32 s30, s52, s39
	v_lshl_add_u64 v[200:201], v[200:201], 0, s[64:65]
	s_mov_b32 m0, s30
	ds_read_b128 v[162:165], v199 offset:49152
	ds_read_b128 v[166:169], v199 offset:50176
	ds_read_b128 v[170:173], v199 offset:51200
	ds_read_b128 v[174:177], v199 offset:52224
	ds_read_b128 v[178:181], v199 offset:53248
	ds_read_b128 v[182:185], v199 offset:54272
	ds_read_b128 v[186:189], v199 offset:55296
	ds_read_b128 v[194:197], v199 offset:56320
	global_load_lds_dwordx4 v[200:201], off
	s_add_i32 m0, s30, 0x2000
	s_add_u32 s28, s28, 0x40080
	v_lshl_add_u64 v[200:201], v[208:209], 0, s[64:65]
	s_addc_u32 s29, s29, 0
	s_add_i32 s30, s53, s39
	global_load_lds_dwordx4 v[200:201], off
	v_lshl_add_u64 v[200:201], s[28:29], 0, v[96:97]
	s_mov_b32 m0, s30
	s_nop 0
	global_load_lds_dwordx4 v[200:201], off
	v_lshl_add_u64 v[200:201], s[28:29], 0, v[202:203]
	s_add_i32 m0, s30, 0x2000
	s_nop 0
	global_load_lds_dwordx4 v[200:201], off
	v_lshl_add_u64 v[200:201], v[210:211], 0, s[64:65]
	s_mov_b32 m0, s45
	s_nop 0
	global_load_lds_dwordx4 v[200:201], off
	v_lshl_add_u64 v[200:201], v[212:213], 0, s[64:65]
	s_mov_b32 m0, s46
	s_nop 0
	global_load_lds_dwordx4 v[200:201], off
	s_waitcnt vmcnt(8)
	s_waitcnt lgkmcnt(0)
	s_barrier
	s_setprio 1
	s_waitcnt lgkmcnt(0)
	v_mfma_f32_16x16x32_bf16 v[60:63], v[122:125], v[162:165], v[60:63]
	v_mfma_f32_16x16x32_bf16 v[56:59], v[130:133], v[162:165], v[56:59]
	v_mfma_f32_16x16x32_bf16 v[44:47], v[122:125], v[170:173], v[44:47]
	v_mfma_f32_16x16x32_bf16 v[40:43], v[130:133], v[170:173], v[40:43]
	v_mfma_f32_16x16x32_bf16 v[28:31], v[122:125], v[178:181], v[28:31]
	v_mfma_f32_16x16x32_bf16 v[24:27], v[130:133], v[178:181], v[24:27]
	v_mfma_f32_16x16x32_bf16 v[12:15], v[122:125], v[186:189], v[12:15]
	v_mfma_f32_16x16x32_bf16 v[8:11], v[130:133], v[186:189], v[8:11]
	v_mfma_f32_16x16x32_bf16 v[60:63], v[126:129], v[166:169], v[60:63]
	v_mfma_f32_16x16x32_bf16 v[56:59], v[134:137], v[166:169], v[56:59]
	v_mfma_f32_16x16x32_bf16 v[44:47], v[126:129], v[174:177], v[44:47]
	v_mfma_f32_16x16x32_bf16 v[40:43], v[134:137], v[174:177], v[40:43]
	v_mfma_f32_16x16x32_bf16 v[28:31], v[126:129], v[182:185], v[28:31]
	v_mfma_f32_16x16x32_bf16 v[24:27], v[134:137], v[182:185], v[24:27]
	v_mfma_f32_16x16x32_bf16 v[12:15], v[126:129], v[194:197], v[12:15]
	v_mfma_f32_16x16x32_bf16 v[8:11], v[134:137], v[194:197], v[8:11]
	v_mfma_f32_16x16x32_bf16 v[52:55], v[138:141], v[162:165], v[52:55]
	v_mfma_f32_16x16x32_bf16 v[48:51], v[146:149], v[162:165], v[48:51]
	v_mfma_f32_16x16x32_bf16 v[36:39], v[138:141], v[170:173], v[36:39]
	v_mfma_f32_16x16x32_bf16 v[32:35], v[146:149], v[170:173], v[32:35]
	v_mfma_f32_16x16x32_bf16 v[20:23], v[138:141], v[178:181], v[20:23]
	v_mfma_f32_16x16x32_bf16 v[16:19], v[146:149], v[178:181], v[16:19]
	v_mfma_f32_16x16x32_bf16 v[4:7], v[138:141], v[186:189], v[4:7]
	v_mfma_f32_16x16x32_bf16 v[0:3], v[146:149], v[186:189], v[0:3]
	v_mfma_f32_16x16x32_bf16 v[52:55], v[142:145], v[166:169], v[52:55]
	v_mfma_f32_16x16x32_bf16 v[48:51], v[150:153], v[166:169], v[48:51]
	v_mfma_f32_16x16x32_bf16 v[36:39], v[142:145], v[174:177], v[36:39]
	v_mfma_f32_16x16x32_bf16 v[32:35], v[150:153], v[174:177], v[32:35]
	v_mfma_f32_16x16x32_bf16 v[20:23], v[142:145], v[182:185], v[20:23]
	v_mfma_f32_16x16x32_bf16 v[16:19], v[150:153], v[182:185], v[16:19]
	v_mfma_f32_16x16x32_bf16 v[4:7], v[142:145], v[194:197], v[4:7]
	v_mfma_f32_16x16x32_bf16 v[0:3], v[150:153], v[194:197], v[0:3]
	s_setprio 0
	s_barrier
	s_add_i32 s51, s51, 2
	s_add_u32 s26, s26, 0x100
	s_addc_u32 s27, s27, 0
	s_add_u32 s49, s49, 0x100
	s_addc_u32 s50, s50, 0
	s_cmp_gt_u32 s51, 13
	s_cbranch_scc0 .LBB0_634

.LBB0_721:
	s_ashr_i32 s17, s16, 31
	s_lshl_b64 s[18:19], s[16:17], 19
	s_add_u32 s18, s35, s18
	s_addc_u32 s19, s36, s19
	s_and_b64 s[20:21], s[2:3], exec
	s_cselect_b32 s17, s19, s25
	s_cselect_b32 s48, s18, s24
	s_ashr_i32 s15, s14, 31
	s_lshl_b64 s[20:21], s[14:15], 19
	s_add_u32 s20, s31, s20
	s_addc_u32 s21, s34, s21
	s_and_b64 s[28:29], s[2:3], exec
	s_cselect_b32 s15, s21, s27
	s_cselect_b32 s49, s20, s26
	s_add_u32 s24, s24, 0x40080
	s_addc_u32 s25, s25, 0
	s_add_u32 s50, s26, 0x100
	s_addc_u32 s51, s27, 0
	s_mov_b32 s52, -2
	s_add_u32 s26, s24, 0xfffc0080
	s_addc_u32 s27, s25, -1
	s_add_i32 s53, 0, 0x10000
	s_cmp_eq_u32 s52, 12
	s_cselect_b32 s29, s17, s27
	s_cselect_b32 s28, s48, s26
	v_add_u32_e32 v147, s53, v141
	s_cselect_b32 s27, s15, s51
	s_cselect_b32 s26, s49, s50
	s_add_i32 s56, 0, 0x14000
	ds_read_b128 v[148:151], v147
	ds_read_b128 v[152:155], v147 offset:1024
	ds_read_b128 v[156:159], v147 offset:2048
	ds_read_b128 v[160:163], v147 offset:3072
	v_add_u32_e32 v147, s56, v141
	ds_read_b128 v[164:167], v147
	ds_read_b128 v[168:171], v147 offset:1024
	ds_read_b128 v[172:175], v147 offset:2048
	ds_read_b128 v[176:179], v147 offset:3072
	v_lshl_add_u64 v[192:193], s[24:25], 0, v[136:137]
	s_add_i32 m0, s23, 0xc000
	ds_read_b128 v[180:183], v146
	ds_read_b128 v[184:187], v146 offset:1024
	ds_read_b128 v[188:191], v146 offset:2048
	ds_read_b128 v[202:205], v146 offset:3072
	ds_read_b128 v[206:209], v146 offset:4096
	ds_read_b128 v[210:213], v146 offset:5120
	ds_read_b128 v[214:217], v146 offset:6144
	ds_read_b128 v[218:221], v146 offset:7168
	global_load_lds_dwordx4 v[192:193], off
	v_lshl_add_u64 v[192:193], s[24:25], 0, v[138:139]
	s_add_i32 m0, s23, 0xe000
	s_nop 0
	global_load_lds_dwordx4 v[192:193], off
	s_waitcnt vmcnt(8)
	s_waitcnt lgkmcnt(0)
	s_barrier
	s_setprio 1
	s_waitcnt lgkmcnt(0)
	v_mfma_f32_16x16x32_bf16 v[126:129], v[148:151], v[180:183], 0
	v_mfma_f32_16x16x32_bf16 v[122:125], v[156:159], v[180:183], 0
	v_mfma_f32_16x16x32_bf16 v[114:117], v[148:151], v[188:191], 0
	v_mfma_f32_16x16x32_bf16 v[106:109], v[156:159], v[188:191], 0
	v_mfma_f32_16x16x32_bf16 v[98:101], v[148:151], v[206:209], 0
	v_mfma_f32_16x16x32_bf16 v[88:91], v[156:159], v[206:209], 0
	v_mfma_f32_16x16x32_bf16 v[80:83], v[148:151], v[214:217], 0
	v_mfma_f32_16x16x32_bf16 v[72:75], v[156:159], v[214:217], 0
	v_mfma_f32_16x16x32_bf16 v[126:129], v[152:155], v[184:187], v[126:129]
	v_mfma_f32_16x16x32_bf16 v[122:125], v[160:163], v[184:187], v[122:125]
	v_mfma_f32_16x16x32_bf16 v[114:117], v[152:155], v[202:205], v[114:117]
	v_mfma_f32_16x16x32_bf16 v[106:109], v[160:163], v[202:205], v[106:109]
	v_mfma_f32_16x16x32_bf16 v[98:101], v[152:155], v[210:213], v[98:101]
	v_mfma_f32_16x16x32_bf16 v[88:91], v[160:163], v[210:213], v[88:91]
	v_mfma_f32_16x16x32_bf16 v[80:83], v[152:155], v[218:221], v[80:83]
	v_mfma_f32_16x16x32_bf16 v[72:75], v[160:163], v[218:221], v[72:75]
	v_mfma_f32_16x16x32_bf16 v[118:121], v[164:167], v[180:183], 0
	v_mfma_f32_16x16x32_bf16 v[110:113], v[172:175], v[180:183], 0
	v_mfma_f32_16x16x32_bf16 v[102:105], v[164:167], v[188:191], 0
	v_mfma_f32_16x16x32_bf16 v[92:95], v[172:175], v[188:191], 0
	v_mfma_f32_16x16x32_bf16 v[84:87], v[164:167], v[206:209], 0
	v_mfma_f32_16x16x32_bf16 v[76:79], v[172:175], v[206:209], 0
	v_mfma_f32_16x16x32_bf16 v[68:71], v[164:167], v[214:217], 0
	v_mfma_f32_16x16x32_bf16 v[64:67], v[172:175], v[214:217], 0
	v_mfma_f32_16x16x32_bf16 v[118:121], v[168:171], v[184:187], v[118:121]
	v_mfma_f32_16x16x32_bf16 v[110:113], v[176:179], v[184:187], v[110:113]
	v_mfma_f32_16x16x32_bf16 v[102:105], v[168:171], v[202:205], v[102:105]
	v_mfma_f32_16x16x32_bf16 v[92:95], v[176:179], v[202:205], v[92:95]
	v_mfma_f32_16x16x32_bf16 v[84:87], v[168:171], v[210:213], v[84:87]
	v_mfma_f32_16x16x32_bf16 v[76:79], v[176:179], v[210:213], v[76:79]
	v_mfma_f32_16x16x32_bf16 v[68:71], v[168:171], v[218:221], v[68:71]
	v_mfma_f32_16x16x32_bf16 v[64:67], v[176:179], v[218:221], v[64:67]
	s_setprio 0
	s_barrier
	s_add_i32 s53, s53, s38
	v_lshl_add_u64 v[192:193], s[26:27], 0, v[96:97]
	s_mov_b32 m0, s53
	ds_read_b128 v[180:183], v146 offset:16384
	ds_read_b128 v[184:187], v146 offset:17408
	ds_read_b128 v[188:191], v146 offset:18432
	ds_read_b128 v[202:205], v146 offset:19456
	ds_read_b128 v[206:209], v146 offset:20480
	ds_read_b128 v[210:213], v146 offset:21504
	ds_read_b128 v[214:217], v146 offset:22528
	ds_read_b128 v[218:221], v146 offset:23552
	global_load_lds_dwordx4 v[192:193], off
	s_add_i32 m0, s53, 0x2000
	s_add_u32 s54, s26, 0x40000
	v_lshl_add_u64 v[194:195], s[26:27], 0, v[130:131]
	s_addc_u32 s55, s27, 0
	s_add_i32 s53, s56, s38
	global_load_lds_dwordx4 v[194:195], off
	v_lshl_add_u64 v[196:197], s[54:55], 0, v[96:97]
	s_mov_b32 m0, s53
	v_lshl_add_u64 v[198:199], s[28:29], 0, v[132:133]
	global_load_lds_dwordx4 v[196:197], off
	v_lshl_add_u64 v[196:197], s[54:55], 0, v[130:131]
	s_add_i32 m0, s53, 0x2000
	s_nop 0
	global_load_lds_dwordx4 v[196:197], off
	v_lshl_add_u64 v[196:197], s[28:29], 0, v[134:135]
	s_mov_b32 m0, s23
	s_nop 0
	global_load_lds_dwordx4 v[196:197], off
	s_mov_b32 m0, s39
	s_nop 0
	global_load_lds_dwordx4 v[198:199], off
	s_waitcnt vmcnt(8)
	s_waitcnt lgkmcnt(0)
	s_barrier
	s_setprio 1
	s_waitcnt lgkmcnt(0)
	v_mfma_f32_16x16x32_bf16 v[60:63], v[148:151], v[180:183], 0
	v_mfma_f32_16x16x32_bf16 v[56:59], v[156:159], v[180:183], 0
	v_mfma_f32_16x16x32_bf16 v[48:51], v[148:151], v[188:191], 0
	v_mfma_f32_16x16x32_bf16 v[40:43], v[156:159], v[188:191], 0
	v_mfma_f32_16x16x32_bf16 v[32:35], v[148:151], v[206:209], 0
	v_mfma_f32_16x16x32_bf16 v[24:27], v[156:159], v[206:209], 0
	v_mfma_f32_16x16x32_bf16 v[16:19], v[148:151], v[214:217], 0
	v_mfma_f32_16x16x32_bf16 v[8:11], v[156:159], v[214:217], 0
	v_mfma_f32_16x16x32_bf16 v[60:63], v[152:155], v[184:187], v[60:63]
	v_mfma_f32_16x16x32_bf16 v[56:59], v[160:163], v[184:187], v[56:59]
	v_mfma_f32_16x16x32_bf16 v[48:51], v[152:155], v[202:205], v[48:51]
	v_mfma_f32_16x16x32_bf16 v[40:43], v[160:163], v[202:205], v[40:43]
	v_mfma_f32_16x16x32_bf16 v[32:35], v[152:155], v[210:213], v[32:35]
	v_mfma_f32_16x16x32_bf16 v[24:27], v[160:163], v[210:213], v[24:27]
	v_mfma_f32_16x16x32_bf16 v[16:19], v[152:155], v[218:221], v[16:19]
	v_mfma_f32_16x16x32_bf16 v[8:11], v[160:163], v[218:221], v[8:11]
	v_mfma_f32_16x16x32_bf16 v[52:55], v[164:167], v[180:183], 0
	v_mfma_f32_16x16x32_bf16 v[44:47], v[172:175], v[180:183], 0
	v_mfma_f32_16x16x32_bf16 v[36:39], v[164:167], v[188:191], 0
	v_mfma_f32_16x16x32_bf16 v[28:31], v[172:175], v[188:191], 0
	v_mfma_f32_16x16x32_bf16 v[20:23], v[164:167], v[206:209], 0
	v_mfma_f32_16x16x32_bf16 v[12:15], v[172:175], v[206:209], 0
	v_mfma_f32_16x16x32_bf16 v[4:7], v[164:167], v[214:217], 0
	v_mfma_f32_16x16x32_bf16 v[0:3], v[172:175], v[214:217], 0
	v_mfma_f32_16x16x32_bf16 v[52:55], v[168:171], v[184:187], v[52:55]
	v_mfma_f32_16x16x32_bf16 v[44:47], v[176:179], v[184:187], v[44:47]
	v_mfma_f32_16x16x32_bf16 v[36:39], v[168:171], v[202:205], v[36:39]
	v_mfma_f32_16x16x32_bf16 v[28:31], v[176:179], v[202:205], v[28:31]
	v_mfma_f32_16x16x32_bf16 v[20:23], v[168:171], v[210:213], v[20:23]
	v_mfma_f32_16x16x32_bf16 v[12:15], v[176:179], v[210:213], v[12:15]
	v_mfma_f32_16x16x32_bf16 v[4:7], v[168:171], v[218:221], v[4:7]
	v_mfma_f32_16x16x32_bf16 v[0:3], v[176:179], v[218:221], v[0:3]
	s_setprio 0
	s_barrier
	s_add_i32 s53, 0, 0x18000
	v_add_u32_e32 v147, s53, v141
	s_add_i32 s54, 0, 0x1c000
	ds_read_b128 v[148:151], v147
	ds_read_b128 v[152:155], v147 offset:1024
	ds_read_b128 v[156:159], v147 offset:2048
	ds_read_b128 v[160:163], v147 offset:3072
	v_add_u32_e32 v147, s54, v141
	ds_read_b128 v[164:167], v147
	ds_read_b128 v[168:171], v147 offset:1024
	ds_read_b128 v[172:175], v147 offset:2048
	ds_read_b128 v[176:179], v147 offset:3072
	s_add_u32 s28, s28, 0x40000
	s_addc_u32 s29, s29, 0
	s_mov_b32 m0, s40
	v_lshl_add_u64 v[200:201], s[28:29], 0, v[134:135]
	ds_read_b128 v[180:183], v146 offset:32768
	ds_read_b128 v[184:187], v146 offset:33792
	ds_read_b128 v[188:191], v146 offset:34816
	ds_read_b128 v[202:205], v146 offset:35840
	ds_read_b128 v[206:209], v146 offset:36864
	ds_read_b128 v[210:213], v146 offset:37888
	ds_read_b128 v[214:217], v146 offset:38912
	ds_read_b128 v[218:221], v146 offset:39936
	global_load_lds_dwordx4 v[200:201], off
	v_lshl_add_u64 v[200:201], s[28:29], 0, v[132:133]
	s_mov_b32 m0, s41
	s_nop 0
	global_load_lds_dwordx4 v[200:201], off
	s_waitcnt vmcnt(8)
	s_waitcnt lgkmcnt(0)
	s_barrier
	s_setprio 1
	s_waitcnt lgkmcnt(0)
	v_mfma_f32_16x16x32_bf16 v[126:129], v[148:151], v[180:183], v[126:129]
	v_mfma_f32_16x16x32_bf16 v[122:125], v[156:159], v[180:183], v[122:125]
	v_mfma_f32_16x16x32_bf16 v[114:117], v[148:151], v[188:191], v[114:117]
	v_mfma_f32_16x16x32_bf16 v[106:109], v[156:159], v[188:191], v[106:109]
	v_mfma_f32_16x16x32_bf16 v[98:101], v[148:151], v[206:209], v[98:101]
	v_mfma_f32_16x16x32_bf16 v[88:91], v[156:159], v[206:209], v[88:91]
	v_mfma_f32_16x16x32_bf16 v[80:83], v[148:151], v[214:217], v[80:83]
	v_mfma_f32_16x16x32_bf16 v[72:75], v[156:159], v[214:217], v[72:75]
	v_mfma_f32_16x16x32_bf16 v[126:129], v[152:155], v[184:187], v[126:129]
	v_mfma_f32_16x16x32_bf16 v[122:125], v[160:163], v[184:187], v[122:125]
	v_mfma_f32_16x16x32_bf16 v[114:117], v[152:155], v[202:205], v[114:117]
	v_mfma_f32_16x16x32_bf16 v[106:109], v[160:163], v[202:205], v[106:109]
	v_mfma_f32_16x16x32_bf16 v[98:101], v[152:155], v[210:213], v[98:101]
	v_mfma_f32_16x16x32_bf16 v[88:91], v[160:163], v[210:213], v[88:91]
	v_mfma_f32_16x16x32_bf16 v[80:83], v[152:155], v[218:221], v[80:83]
	v_mfma_f32_16x16x32_bf16 v[72:75], v[160:163], v[218:221], v[72:75]
	v_mfma_f32_16x16x32_bf16 v[118:121], v[164:167], v[180:183], v[118:121]
	v_mfma_f32_16x16x32_bf16 v[110:113], v[172:175], v[180:183], v[110:113]
	v_mfma_f32_16x16x32_bf16 v[102:105], v[164:167], v[188:191], v[102:105]
	v_mfma_f32_16x16x32_bf16 v[92:95], v[172:175], v[188:191], v[92:95]
	v_mfma_f32_16x16x32_bf16 v[84:87], v[164:167], v[206:209], v[84:87]
	v_mfma_f32_16x16x32_bf16 v[76:79], v[172:175], v[206:209], v[76:79]
	v_mfma_f32_16x16x32_bf16 v[68:71], v[164:167], v[214:217], v[68:71]
	v_mfma_f32_16x16x32_bf16 v[64:67], v[172:175], v[214:217], v[64:67]
	v_mfma_f32_16x16x32_bf16 v[118:121], v[168:171], v[184:187], v[118:121]
	v_mfma_f32_16x16x32_bf16 v[110:113], v[176:179], v[184:187], v[110:113]
	v_mfma_f32_16x16x32_bf16 v[102:105], v[168:171], v[202:205], v[102:105]
	v_mfma_f32_16x16x32_bf16 v[92:95], v[176:179], v[202:205], v[92:95]
	v_mfma_f32_16x16x32_bf16 v[84:87], v[168:171], v[210:213], v[84:87]
	v_mfma_f32_16x16x32_bf16 v[76:79], v[176:179], v[210:213], v[76:79]
	v_mfma_f32_16x16x32_bf16 v[68:71], v[168:171], v[218:221], v[68:71]
	v_mfma_f32_16x16x32_bf16 v[64:67], v[176:179], v[218:221], v[64:67]
	s_setprio 0
	s_barrier
	s_add_i32 s28, s53, s38
	v_lshl_add_u64 v[192:193], v[192:193], 0, s[64:65]
	s_mov_b32 m0, s28
	ds_read_b128 v[180:183], v146 offset:49152
	ds_read_b128 v[184:187], v146 offset:50176
	ds_read_b128 v[188:191], v146 offset:51200
	ds_read_b128 v[202:205], v146 offset:52224
	ds_read_b128 v[206:209], v146 offset:53248
	ds_read_b128 v[210:213], v146 offset:54272
	ds_read_b128 v[214:217], v146 offset:55296
	ds_read_b128 v[218:221], v146 offset:56320
	global_load_lds_dwordx4 v[192:193], off
	s_add_i32 m0, s28, 0x2000
	s_add_u32 s26, s26, 0x40080
	v_lshl_add_u64 v[192:193], v[194:195], 0, s[64:65]
	s_addc_u32 s27, s27, 0
	s_add_i32 s28, s54, s38
	global_load_lds_dwordx4 v[192:193], off
	v_lshl_add_u64 v[192:193], s[26:27], 0, v[96:97]
	s_mov_b32 m0, s28
	s_nop 0
	global_load_lds_dwordx4 v[192:193], off
	v_lshl_add_u64 v[192:193], s[26:27], 0, v[130:131]
	s_add_i32 m0, s28, 0x2000
	s_nop 0
	global_load_lds_dwordx4 v[192:193], off
	v_lshl_add_u64 v[192:193], v[196:197], 0, s[64:65]
	s_mov_b32 m0, s42
	s_nop 0
	global_load_lds_dwordx4 v[192:193], off
	v_lshl_add_u64 v[192:193], v[198:199], 0, s[64:65]
	s_mov_b32 m0, s43
	s_nop 0
	global_load_lds_dwordx4 v[192:193], off
	s_waitcnt vmcnt(8)
	s_waitcnt lgkmcnt(0)
	s_barrier
	s_setprio 1
	s_waitcnt lgkmcnt(0)
	v_mfma_f32_16x16x32_bf16 v[60:63], v[148:151], v[180:183], v[60:63]
	v_mfma_f32_16x16x32_bf16 v[56:59], v[156:159], v[180:183], v[56:59]
	v_mfma_f32_16x16x32_bf16 v[48:51], v[148:151], v[188:191], v[48:51]
	v_mfma_f32_16x16x32_bf16 v[40:43], v[156:159], v[188:191], v[40:43]
	v_mfma_f32_16x16x32_bf16 v[32:35], v[148:151], v[206:209], v[32:35]
	v_mfma_f32_16x16x32_bf16 v[24:27], v[156:159], v[206:209], v[24:27]
	v_mfma_f32_16x16x32_bf16 v[16:19], v[148:151], v[214:217], v[16:19]
	v_mfma_f32_16x16x32_bf16 v[8:11], v[156:159], v[214:217], v[8:11]
	v_mfma_f32_16x16x32_bf16 v[60:63], v[152:155], v[184:187], v[60:63]
	v_mfma_f32_16x16x32_bf16 v[56:59], v[160:163], v[184:187], v[56:59]
	v_mfma_f32_16x16x32_bf16 v[48:51], v[152:155], v[202:205], v[48:51]
	v_mfma_f32_16x16x32_bf16 v[40:43], v[160:163], v[202:205], v[40:43]
	v_mfma_f32_16x16x32_bf16 v[32:35], v[152:155], v[210:213], v[32:35]
	v_mfma_f32_16x16x32_bf16 v[24:27], v[160:163], v[210:213], v[24:27]
	v_mfma_f32_16x16x32_bf16 v[16:19], v[152:155], v[218:221], v[16:19]
	v_mfma_f32_16x16x32_bf16 v[8:11], v[160:163], v[218:221], v[8:11]
	v_mfma_f32_16x16x32_bf16 v[52:55], v[164:167], v[180:183], v[52:55]
	v_mfma_f32_16x16x32_bf16 v[44:47], v[172:175], v[180:183], v[44:47]
	v_mfma_f32_16x16x32_bf16 v[36:39], v[164:167], v[188:191], v[36:39]
	v_mfma_f32_16x16x32_bf16 v[28:31], v[172:175], v[188:191], v[28:31]
	v_mfma_f32_16x16x32_bf16 v[20:23], v[164:167], v[206:209], v[20:23]
	v_mfma_f32_16x16x32_bf16 v[12:15], v[172:175], v[206:209], v[12:15]
	v_mfma_f32_16x16x32_bf16 v[4:7], v[164:167], v[214:217], v[4:7]
	v_mfma_f32_16x16x32_bf16 v[0:3], v[172:175], v[214:217], v[0:3]
	v_mfma_f32_16x16x32_bf16 v[52:55], v[168:171], v[184:187], v[52:55]
	v_mfma_f32_16x16x32_bf16 v[44:47], v[176:179], v[184:187], v[44:47]
	v_mfma_f32_16x16x32_bf16 v[36:39], v[168:171], v[202:205], v[36:39]
	v_mfma_f32_16x16x32_bf16 v[28:31], v[176:179], v[202:205], v[28:31]
	v_mfma_f32_16x16x32_bf16 v[20:23], v[168:171], v[210:213], v[20:23]
	v_mfma_f32_16x16x32_bf16 v[12:15], v[176:179], v[210:213], v[12:15]
	v_mfma_f32_16x16x32_bf16 v[4:7], v[168:171], v[218:221], v[4:7]
	v_mfma_f32_16x16x32_bf16 v[0:3], v[176:179], v[218:221], v[0:3]
	s_setprio 0
	s_barrier
	s_add_i32 s52, s52, 2
	s_add_u32 s24, s24, 0x100
	s_addc_u32 s25, s25, 0
	s_add_u32 s50, s50, 0x100
	s_addc_u32 s51, s51, 0
	s_cmp_gt_u32 s52, 13
	s_cbranch_scc1 .Lpeel_done_722
.LBB0_722:
	s_add_u32 s26, s24, 0xfffc0080
	s_addc_u32 s27, s25, -1
	s_add_i32 s53, 0, 0x10000
	s_cmp_eq_u32 s52, 12
	s_cselect_b32 s29, s17, s27
	s_cselect_b32 s28, s48, s26
	v_add_u32_e32 v147, s53, v141
	s_cselect_b32 s27, s15, s51
	s_cselect_b32 s26, s49, s50
	s_add_i32 s56, 0, 0x14000
	ds_read_b128 v[148:151], v147
	ds_read_b128 v[152:155], v147 offset:1024
	ds_read_b128 v[156:159], v147 offset:2048
	ds_read_b128 v[160:163], v147 offset:3072
	v_add_u32_e32 v147, s56, v141
	ds_read_b128 v[164:167], v147
	ds_read_b128 v[168:171], v147 offset:1024
	ds_read_b128 v[172:175], v147 offset:2048
	ds_read_b128 v[176:179], v147 offset:3072
	v_lshl_add_u64 v[192:193], s[24:25], 0, v[136:137]
	s_add_i32 m0, s23, 0xc000
	ds_read_b128 v[180:183], v146
	ds_read_b128 v[184:187], v146 offset:1024
	ds_read_b128 v[188:191], v146 offset:2048
	ds_read_b128 v[202:205], v146 offset:3072
	ds_read_b128 v[206:209], v146 offset:4096
	ds_read_b128 v[210:213], v146 offset:5120
	ds_read_b128 v[214:217], v146 offset:6144
	ds_read_b128 v[218:221], v146 offset:7168
	global_load_lds_dwordx4 v[192:193], off
	v_lshl_add_u64 v[192:193], s[24:25], 0, v[138:139]
	s_add_i32 m0, s23, 0xe000
	s_nop 0
	global_load_lds_dwordx4 v[192:193], off
	s_waitcnt vmcnt(8)
	s_waitcnt lgkmcnt(0)
	s_barrier
	s_setprio 1
	s_waitcnt lgkmcnt(0)
	v_mfma_f32_16x16x32_bf16 v[126:129], v[148:151], v[180:183], v[126:129]
	v_mfma_f32_16x16x32_bf16 v[122:125], v[156:159], v[180:183], v[122:125]
	v_mfma_f32_16x16x32_bf16 v[114:117], v[148:151], v[188:191], v[114:117]
	v_mfma_f32_16x16x32_bf16 v[106:109], v[156:159], v[188:191], v[106:109]
	v_mfma_f32_16x16x32_bf16 v[98:101], v[148:151], v[206:209], v[98:101]
	v_mfma_f32_16x16x32_bf16 v[88:91], v[156:159], v[206:209], v[88:91]
	v_mfma_f32_16x16x32_bf16 v[80:83], v[148:151], v[214:217], v[80:83]
	v_mfma_f32_16x16x32_bf16 v[72:75], v[156:159], v[214:217], v[72:75]
	v_mfma_f32_16x16x32_bf16 v[126:129], v[152:155], v[184:187], v[126:129]
	v_mfma_f32_16x16x32_bf16 v[122:125], v[160:163], v[184:187], v[122:125]
	v_mfma_f32_16x16x32_bf16 v[114:117], v[152:155], v[202:205], v[114:117]
	v_mfma_f32_16x16x32_bf16 v[106:109], v[160:163], v[202:205], v[106:109]
	v_mfma_f32_16x16x32_bf16 v[98:101], v[152:155], v[210:213], v[98:101]
	v_mfma_f32_16x16x32_bf16 v[88:91], v[160:163], v[210:213], v[88:91]
	v_mfma_f32_16x16x32_bf16 v[80:83], v[152:155], v[218:221], v[80:83]
	v_mfma_f32_16x16x32_bf16 v[72:75], v[160:163], v[218:221], v[72:75]
	v_mfma_f32_16x16x32_bf16 v[118:121], v[164:167], v[180:183], v[118:121]
	v_mfma_f32_16x16x32_bf16 v[110:113], v[172:175], v[180:183], v[110:113]
	v_mfma_f32_16x16x32_bf16 v[102:105], v[164:167], v[188:191], v[102:105]
	v_mfma_f32_16x16x32_bf16 v[92:95], v[172:175], v[188:191], v[92:95]
	v_mfma_f32_16x16x32_bf16 v[84:87], v[164:167], v[206:209], v[84:87]
	v_mfma_f32_16x16x32_bf16 v[76:79], v[172:175], v[206:209], v[76:79]
	v_mfma_f32_16x16x32_bf16 v[68:71], v[164:167], v[214:217], v[68:71]
	v_mfma_f32_16x16x32_bf16 v[64:67], v[172:175], v[214:217], v[64:67]
	v_mfma_f32_16x16x32_bf16 v[118:121], v[168:171], v[184:187], v[118:121]
	v_mfma_f32_16x16x32_bf16 v[110:113], v[176:179], v[184:187], v[110:113]
	v_mfma_f32_16x16x32_bf16 v[102:105], v[168:171], v[202:205], v[102:105]
	v_mfma_f32_16x16x32_bf16 v[92:95], v[176:179], v[202:205], v[92:95]
	v_mfma_f32_16x16x32_bf16 v[84:87], v[168:171], v[210:213], v[84:87]
	v_mfma_f32_16x16x32_bf16 v[76:79], v[176:179], v[210:213], v[76:79]
	v_mfma_f32_16x16x32_bf16 v[68:71], v[168:171], v[218:221], v[68:71]
	v_mfma_f32_16x16x32_bf16 v[64:67], v[176:179], v[218:221], v[64:67]
	s_setprio 0
	s_barrier
	s_add_i32 s53, s53, s38
	v_lshl_add_u64 v[192:193], s[26:27], 0, v[96:97]
	s_mov_b32 m0, s53
	ds_read_b128 v[180:183], v146 offset:16384
	ds_read_b128 v[184:187], v146 offset:17408
	ds_read_b128 v[188:191], v146 offset:18432
	ds_read_b128 v[202:205], v146 offset:19456
	ds_read_b128 v[206:209], v146 offset:20480
	ds_read_b128 v[210:213], v146 offset:21504
	ds_read_b128 v[214:217], v146 offset:22528
	ds_read_b128 v[218:221], v146 offset:23552
	global_load_lds_dwordx4 v[192:193], off
	s_add_i32 m0, s53, 0x2000
	s_add_u32 s54, s26, 0x40000
	v_lshl_add_u64 v[194:195], s[26:27], 0, v[130:131]
	s_addc_u32 s55, s27, 0
	s_add_i32 s53, s56, s38
	global_load_lds_dwordx4 v[194:195], off
	v_lshl_add_u64 v[196:197], s[54:55], 0, v[96:97]
	s_mov_b32 m0, s53
	v_lshl_add_u64 v[198:199], s[28:29], 0, v[132:133]
	global_load_lds_dwordx4 v[196:197], off
	v_lshl_add_u64 v[196:197], s[54:55], 0, v[130:131]
	s_add_i32 m0, s53, 0x2000
	s_nop 0
	global_load_lds_dwordx4 v[196:197], off
	v_lshl_add_u64 v[196:197], s[28:29], 0, v[134:135]
	s_mov_b32 m0, s23
	s_nop 0
	global_load_lds_dwordx4 v[196:197], off
	s_mov_b32 m0, s39
	s_nop 0
	global_load_lds_dwordx4 v[198:199], off
	s_waitcnt vmcnt(8)
	s_waitcnt lgkmcnt(0)
	s_barrier
	s_setprio 1
	s_waitcnt lgkmcnt(0)
	v_mfma_f32_16x16x32_bf16 v[60:63], v[148:151], v[180:183], v[60:63]
	v_mfma_f32_16x16x32_bf16 v[56:59], v[156:159], v[180:183], v[56:59]
	v_mfma_f32_16x16x32_bf16 v[48:51], v[148:151], v[188:191], v[48:51]
	v_mfma_f32_16x16x32_bf16 v[40:43], v[156:159], v[188:191], v[40:43]
	v_mfma_f32_16x16x32_bf16 v[32:35], v[148:151], v[206:209], v[32:35]
	v_mfma_f32_16x16x32_bf16 v[24:27], v[156:159], v[206:209], v[24:27]
	v_mfma_f32_16x16x32_bf16 v[16:19], v[148:151], v[214:217], v[16:19]
	v_mfma_f32_16x16x32_bf16 v[8:11], v[156:159], v[214:217], v[8:11]
	v_mfma_f32_16x16x32_bf16 v[60:63], v[152:155], v[184:187], v[60:63]
	v_mfma_f32_16x16x32_bf16 v[56:59], v[160:163], v[184:187], v[56:59]
	v_mfma_f32_16x16x32_bf16 v[48:51], v[152:155], v[202:205], v[48:51]
	v_mfma_f32_16x16x32_bf16 v[40:43], v[160:163], v[202:205], v[40:43]
	v_mfma_f32_16x16x32_bf16 v[32:35], v[152:155], v[210:213], v[32:35]
	v_mfma_f32_16x16x32_bf16 v[24:27], v[160:163], v[210:213], v[24:27]
	v_mfma_f32_16x16x32_bf16 v[16:19], v[152:155], v[218:221], v[16:19]
	v_mfma_f32_16x16x32_bf16 v[8:11], v[160:163], v[218:221], v[8:11]
	v_mfma_f32_16x16x32_bf16 v[52:55], v[164:167], v[180:183], v[52:55]
	v_mfma_f32_16x16x32_bf16 v[44:47], v[172:175], v[180:183], v[44:47]
	v_mfma_f32_16x16x32_bf16 v[36:39], v[164:167], v[188:191], v[36:39]
	v_mfma_f32_16x16x32_bf16 v[28:31], v[172:175], v[188:191], v[28:31]
	v_mfma_f32_16x16x32_bf16 v[20:23], v[164:167], v[206:209], v[20:23]
	v_mfma_f32_16x16x32_bf16 v[12:15], v[172:175], v[206:209], v[12:15]
	v_mfma_f32_16x16x32_bf16 v[4:7], v[164:167], v[214:217], v[4:7]
	v_mfma_f32_16x16x32_bf16 v[0:3], v[172:175], v[214:217], v[0:3]
	v_mfma_f32_16x16x32_bf16 v[52:55], v[168:171], v[184:187], v[52:55]
	v_mfma_f32_16x16x32_bf16 v[44:47], v[176:179], v[184:187], v[44:47]
	v_mfma_f32_16x16x32_bf16 v[36:39], v[168:171], v[202:205], v[36:39]
	v_mfma_f32_16x16x32_bf16 v[28:31], v[176:179], v[202:205], v[28:31]
	v_mfma_f32_16x16x32_bf16 v[20:23], v[168:171], v[210:213], v[20:23]
	v_mfma_f32_16x16x32_bf16 v[12:15], v[176:179], v[210:213], v[12:15]
	v_mfma_f32_16x16x32_bf16 v[4:7], v[168:171], v[218:221], v[4:7]
	v_mfma_f32_16x16x32_bf16 v[0:3], v[176:179], v[218:221], v[0:3]
	s_setprio 0
	s_barrier
	s_add_i32 s53, 0, 0x18000
	v_add_u32_e32 v147, s53, v141
	s_add_i32 s54, 0, 0x1c000
	ds_read_b128 v[148:151], v147
	ds_read_b128 v[152:155], v147 offset:1024
	ds_read_b128 v[156:159], v147 offset:2048
	ds_read_b128 v[160:163], v147 offset:3072
	v_add_u32_e32 v147, s54, v141
	ds_read_b128 v[164:167], v147
	ds_read_b128 v[168:171], v147 offset:1024
	ds_read_b128 v[172:175], v147 offset:2048
	ds_read_b128 v[176:179], v147 offset:3072
	s_add_u32 s28, s28, 0x40000
	s_addc_u32 s29, s29, 0
	s_mov_b32 m0, s40
	v_lshl_add_u64 v[200:201], s[28:29], 0, v[134:135]
	ds_read_b128 v[180:183], v146 offset:32768
	ds_read_b128 v[184:187], v146 offset:33792
	ds_read_b128 v[188:191], v146 offset:34816
	ds_read_b128 v[202:205], v146 offset:35840
	ds_read_b128 v[206:209], v146 offset:36864
	ds_read_b128 v[210:213], v146 offset:37888
	ds_read_b128 v[214:217], v146 offset:38912
	ds_read_b128 v[218:221], v146 offset:39936
	global_load_lds_dwordx4 v[200:201], off
	v_lshl_add_u64 v[200:201], s[28:29], 0, v[132:133]
	s_mov_b32 m0, s41
	s_nop 0
	global_load_lds_dwordx4 v[200:201], off
	s_waitcnt vmcnt(8)
	s_waitcnt lgkmcnt(0)
	s_barrier
	s_setprio 1
	s_waitcnt lgkmcnt(0)
	v_mfma_f32_16x16x32_bf16 v[126:129], v[148:151], v[180:183], v[126:129]
	v_mfma_f32_16x16x32_bf16 v[122:125], v[156:159], v[180:183], v[122:125]
	v_mfma_f32_16x16x32_bf16 v[114:117], v[148:151], v[188:191], v[114:117]
	v_mfma_f32_16x16x32_bf16 v[106:109], v[156:159], v[188:191], v[106:109]
	v_mfma_f32_16x16x32_bf16 v[98:101], v[148:151], v[206:209], v[98:101]
	v_mfma_f32_16x16x32_bf16 v[88:91], v[156:159], v[206:209], v[88:91]
	v_mfma_f32_16x16x32_bf16 v[80:83], v[148:151], v[214:217], v[80:83]
	v_mfma_f32_16x16x32_bf16 v[72:75], v[156:159], v[214:217], v[72:75]
	v_mfma_f32_16x16x32_bf16 v[126:129], v[152:155], v[184:187], v[126:129]
	v_mfma_f32_16x16x32_bf16 v[122:125], v[160:163], v[184:187], v[122:125]
	v_mfma_f32_16x16x32_bf16 v[114:117], v[152:155], v[202:205], v[114:117]
	v_mfma_f32_16x16x32_bf16 v[106:109], v[160:163], v[202:205], v[106:109]
	v_mfma_f32_16x16x32_bf16 v[98:101], v[152:155], v[210:213], v[98:101]
	v_mfma_f32_16x16x32_bf16 v[88:91], v[160:163], v[210:213], v[88:91]
	v_mfma_f32_16x16x32_bf16 v[80:83], v[152:155], v[218:221], v[80:83]
	v_mfma_f32_16x16x32_bf16 v[72:75], v[160:163], v[218:221], v[72:75]
	v_mfma_f32_16x16x32_bf16 v[118:121], v[164:167], v[180:183], v[118:121]
	v_mfma_f32_16x16x32_bf16 v[110:113], v[172:175], v[180:183], v[110:113]
	v_mfma_f32_16x16x32_bf16 v[102:105], v[164:167], v[188:191], v[102:105]
	v_mfma_f32_16x16x32_bf16 v[92:95], v[172:175], v[188:191], v[92:95]
	v_mfma_f32_16x16x32_bf16 v[84:87], v[164:167], v[206:209], v[84:87]
	v_mfma_f32_16x16x32_bf16 v[76:79], v[172:175], v[206:209], v[76:79]
	v_mfma_f32_16x16x32_bf16 v[68:71], v[164:167], v[214:217], v[68:71]
	v_mfma_f32_16x16x32_bf16 v[64:67], v[172:175], v[214:217], v[64:67]
	v_mfma_f32_16x16x32_bf16 v[118:121], v[168:171], v[184:187], v[118:121]
	v_mfma_f32_16x16x32_bf16 v[110:113], v[176:179], v[184:187], v[110:113]
	v_mfma_f32_16x16x32_bf16 v[102:105], v[168:171], v[202:205], v[102:105]
	v_mfma_f32_16x16x32_bf16 v[92:95], v[176:179], v[202:205], v[92:95]
	v_mfma_f32_16x16x32_bf16 v[84:87], v[168:171], v[210:213], v[84:87]
	v_mfma_f32_16x16x32_bf16 v[76:79], v[176:179], v[210:213], v[76:79]
	v_mfma_f32_16x16x32_bf16 v[68:71], v[168:171], v[218:221], v[68:71]
	v_mfma_f32_16x16x32_bf16 v[64:67], v[176:179], v[218:221], v[64:67]
	s_setprio 0
	s_barrier
	s_add_i32 s28, s53, s38
	v_lshl_add_u64 v[192:193], v[192:193], 0, s[64:65]
	s_mov_b32 m0, s28
	ds_read_b128 v[180:183], v146 offset:49152
	ds_read_b128 v[184:187], v146 offset:50176
	ds_read_b128 v[188:191], v146 offset:51200
	ds_read_b128 v[202:205], v146 offset:52224
	ds_read_b128 v[206:209], v146 offset:53248
	ds_read_b128 v[210:213], v146 offset:54272
	ds_read_b128 v[214:217], v146 offset:55296
	ds_read_b128 v[218:221], v146 offset:56320
	global_load_lds_dwordx4 v[192:193], off
	s_add_i32 m0, s28, 0x2000
	s_add_u32 s26, s26, 0x40080
	v_lshl_add_u64 v[192:193], v[194:195], 0, s[64:65]
	s_addc_u32 s27, s27, 0
	s_add_i32 s28, s54, s38
	global_load_lds_dwordx4 v[192:193], off
	v_lshl_add_u64 v[192:193], s[26:27], 0, v[96:97]
	s_mov_b32 m0, s28
	s_nop 0
	global_load_lds_dwordx4 v[192:193], off
	v_lshl_add_u64 v[192:193], s[26:27], 0, v[130:131]
	s_add_i32 m0, s28, 0x2000
	s_nop 0
	global_load_lds_dwordx4 v[192:193], off
	v_lshl_add_u64 v[192:193], v[196:197], 0, s[64:65]
	s_mov_b32 m0, s42
	s_nop 0
	global_load_lds_dwordx4 v[192:193], off
	v_lshl_add_u64 v[192:193], v[198:199], 0, s[64:65]
	s_mov_b32 m0, s43
	s_nop 0
	global_load_lds_dwordx4 v[192:193], off
	s_waitcnt vmcnt(8)
	s_waitcnt lgkmcnt(0)
	s_barrier
	s_setprio 1
	s_waitcnt lgkmcnt(0)
	v_mfma_f32_16x16x32_bf16 v[60:63], v[148:151], v[180:183], v[60:63]
	v_mfma_f32_16x16x32_bf16 v[56:59], v[156:159], v[180:183], v[56:59]
	v_mfma_f32_16x16x32_bf16 v[48:51], v[148:151], v[188:191], v[48:51]
	v_mfma_f32_16x16x32_bf16 v[40:43], v[156:159], v[188:191], v[40:43]
	v_mfma_f32_16x16x32_bf16 v[32:35], v[148:151], v[206:209], v[32:35]
	v_mfma_f32_16x16x32_bf16 v[24:27], v[156:159], v[206:209], v[24:27]
	v_mfma_f32_16x16x32_bf16 v[16:19], v[148:151], v[214:217], v[16:19]
	v_mfma_f32_16x16x32_bf16 v[8:11], v[156:159], v[214:217], v[8:11]
	v_mfma_f32_16x16x32_bf16 v[60:63], v[152:155], v[184:187], v[60:63]
	v_mfma_f32_16x16x32_bf16 v[56:59], v[160:163], v[184:187], v[56:59]
	v_mfma_f32_16x16x32_bf16 v[48:51], v[152:155], v[202:205], v[48:51]
	v_mfma_f32_16x16x32_bf16 v[40:43], v[160:163], v[202:205], v[40:43]
	v_mfma_f32_16x16x32_bf16 v[32:35], v[152:155], v[210:213], v[32:35]
	v_mfma_f32_16x16x32_bf16 v[24:27], v[160:163], v[210:213], v[24:27]
	v_mfma_f32_16x16x32_bf16 v[16:19], v[152:155], v[218:221], v[16:19]
	v_mfma_f32_16x16x32_bf16 v[8:11], v[160:163], v[218:221], v[8:11]
	v_mfma_f32_16x16x32_bf16 v[52:55], v[164:167], v[180:183], v[52:55]
	v_mfma_f32_16x16x32_bf16 v[44:47], v[172:175], v[180:183], v[44:47]
	v_mfma_f32_16x16x32_bf16 v[36:39], v[164:167], v[188:191], v[36:39]
	v_mfma_f32_16x16x32_bf16 v[28:31], v[172:175], v[188:191], v[28:31]
	v_mfma_f32_16x16x32_bf16 v[20:23], v[164:167], v[206:209], v[20:23]
	v_mfma_f32_16x16x32_bf16 v[12:15], v[172:175], v[206:209], v[12:15]
	v_mfma_f32_16x16x32_bf16 v[4:7], v[164:167], v[214:217], v[4:7]
	v_mfma_f32_16x16x32_bf16 v[0:3], v[172:175], v[214:217], v[0:3]
	v_mfma_f32_16x16x32_bf16 v[52:55], v[168:171], v[184:187], v[52:55]
	v_mfma_f32_16x16x32_bf16 v[44:47], v[176:179], v[184:187], v[44:47]
	v_mfma_f32_16x16x32_bf16 v[36:39], v[168:171], v[202:205], v[36:39]
	v_mfma_f32_16x16x32_bf16 v[28:31], v[176:179], v[202:205], v[28:31]
	v_mfma_f32_16x16x32_bf16 v[20:23], v[168:171], v[210:213], v[20:23]
	v_mfma_f32_16x16x32_bf16 v[12:15], v[176:179], v[210:213], v[12:15]
	v_mfma_f32_16x16x32_bf16 v[4:7], v[168:171], v[218:221], v[4:7]
	v_mfma_f32_16x16x32_bf16 v[0:3], v[176:179], v[218:221], v[0:3]
	s_setprio 0
	s_barrier
	s_add_i32 s52, s52, 2
	s_add_u32 s24, s24, 0x100
	s_addc_u32 s25, s25, 0
	s_add_u32 s50, s50, 0x100
	s_addc_u32 s51, s51, 0
	s_cmp_gt_u32 s52, 13
	s_cbranch_scc0 .LBB0_722

.LBB0_860:
	s_add_u32 s48, s20, 0x100
	s_addc_u32 s49, s21, 0
	s_mov_b32 s50, -2
	s_add_u32 s20, s18, 0x100
	s_addc_u32 s21, s19, 0
	s_add_i32 s51, 0, 0x10000
	s_cmp_eq_u32 s50, 2
	s_cselect_b32 s25, s5, s21
	s_cselect_b32 s24, s4, s20
	v_add_u32_e32 v147, s51, v141
	s_cselect_b32 s23, s17, s49
	s_cselect_b32 s22, s16, s48
	s_add_i32 s52, 0, 0x14000
	ds_read_b128 v[148:151], v147
	ds_read_b128 v[152:155], v147 offset:1024
	ds_read_b128 v[156:159], v147 offset:2048
	ds_read_b128 v[160:163], v147 offset:3072
	v_add_u32_e32 v147, s52, v141
	ds_read_b128 v[164:167], v147
	ds_read_b128 v[168:171], v147 offset:1024
	ds_read_b128 v[172:175], v147 offset:2048
	ds_read_b128 v[176:179], v147 offset:3072
	v_lshl_add_u64 v[192:193], s[18:19], 0, v[136:137]
	s_add_i32 m0, s35, 0xc000
	ds_read_b128 v[180:183], v146
	ds_read_b128 v[184:187], v146 offset:1024
	ds_read_b128 v[188:191], v146 offset:2048
	ds_read_b128 v[202:205], v146 offset:3072
	ds_read_b128 v[206:209], v146 offset:4096
	ds_read_b128 v[210:213], v146 offset:5120
	ds_read_b128 v[214:217], v146 offset:6144
	ds_read_b128 v[218:221], v146 offset:7168
	global_load_lds_dwordx4 v[192:193], off
	v_lshl_add_u64 v[192:193], s[18:19], 0, v[138:139]
	s_add_i32 m0, s35, 0xe000
	s_nop 0
	global_load_lds_dwordx4 v[192:193], off
	s_waitcnt vmcnt(8)
	s_waitcnt lgkmcnt(0)
	s_barrier
	s_setprio 1
	s_waitcnt lgkmcnt(0)
	v_mfma_f32_16x16x32_bf16 v[126:129], v[148:151], v[180:183], 0
	v_mfma_f32_16x16x32_bf16 v[122:125], v[156:159], v[180:183], 0
	v_mfma_f32_16x16x32_bf16 v[114:117], v[148:151], v[188:191], 0
	v_mfma_f32_16x16x32_bf16 v[106:109], v[156:159], v[188:191], 0
	v_mfma_f32_16x16x32_bf16 v[98:101], v[148:151], v[206:209], 0
	v_mfma_f32_16x16x32_bf16 v[88:91], v[156:159], v[206:209], 0
	v_mfma_f32_16x16x32_bf16 v[80:83], v[148:151], v[214:217], 0
	v_mfma_f32_16x16x32_bf16 v[72:75], v[156:159], v[214:217], 0
	v_mfma_f32_16x16x32_bf16 v[126:129], v[152:155], v[184:187], v[126:129]
	v_mfma_f32_16x16x32_bf16 v[122:125], v[160:163], v[184:187], v[122:125]
	v_mfma_f32_16x16x32_bf16 v[114:117], v[152:155], v[202:205], v[114:117]
	v_mfma_f32_16x16x32_bf16 v[106:109], v[160:163], v[202:205], v[106:109]
	v_mfma_f32_16x16x32_bf16 v[98:101], v[152:155], v[210:213], v[98:101]
	v_mfma_f32_16x16x32_bf16 v[88:91], v[160:163], v[210:213], v[88:91]
	v_mfma_f32_16x16x32_bf16 v[80:83], v[152:155], v[218:221], v[80:83]
	v_mfma_f32_16x16x32_bf16 v[72:75], v[160:163], v[218:221], v[72:75]
	v_mfma_f32_16x16x32_bf16 v[118:121], v[164:167], v[180:183], 0
	v_mfma_f32_16x16x32_bf16 v[110:113], v[172:175], v[180:183], 0
	v_mfma_f32_16x16x32_bf16 v[102:105], v[164:167], v[188:191], 0
	v_mfma_f32_16x16x32_bf16 v[92:95], v[172:175], v[188:191], 0
	v_mfma_f32_16x16x32_bf16 v[84:87], v[164:167], v[206:209], 0
	v_mfma_f32_16x16x32_bf16 v[76:79], v[172:175], v[206:209], 0
	v_mfma_f32_16x16x32_bf16 v[68:71], v[164:167], v[214:217], 0
	v_mfma_f32_16x16x32_bf16 v[64:67], v[172:175], v[214:217], 0
	v_mfma_f32_16x16x32_bf16 v[118:121], v[168:171], v[184:187], v[118:121]
	v_mfma_f32_16x16x32_bf16 v[110:113], v[176:179], v[184:187], v[110:113]
	v_mfma_f32_16x16x32_bf16 v[102:105], v[168:171], v[202:205], v[102:105]
	v_mfma_f32_16x16x32_bf16 v[92:95], v[176:179], v[202:205], v[92:95]
	v_mfma_f32_16x16x32_bf16 v[84:87], v[168:171], v[210:213], v[84:87]
	v_mfma_f32_16x16x32_bf16 v[76:79], v[176:179], v[210:213], v[76:79]
	v_mfma_f32_16x16x32_bf16 v[68:71], v[168:171], v[218:221], v[68:71]
	v_mfma_f32_16x16x32_bf16 v[64:67], v[176:179], v[218:221], v[64:67]
	s_setprio 0
	s_barrier
	s_add_i32 s18, s51, s34
	v_lshl_add_u64 v[192:193], s[22:23], 0, v[96:97]
	s_mov_b32 m0, s18
	ds_read_b128 v[180:183], v146 offset:16384
	ds_read_b128 v[184:187], v146 offset:17408
	ds_read_b128 v[188:191], v146 offset:18432
	ds_read_b128 v[202:205], v146 offset:19456
	ds_read_b128 v[206:209], v146 offset:20480
	ds_read_b128 v[210:213], v146 offset:21504
	ds_read_b128 v[214:217], v146 offset:22528
	ds_read_b128 v[218:221], v146 offset:23552
	global_load_lds_dwordx4 v[192:193], off
	s_add_i32 m0, s18, 0x2000
	s_add_u32 s18, s22, 0x18000
	v_lshl_add_u64 v[194:195], s[22:23], 0, v[130:131]
	s_addc_u32 s19, s23, 0
	s_add_i32 s51, s52, s34
	global_load_lds_dwordx4 v[194:195], off
	v_lshl_add_u64 v[196:197], s[18:19], 0, v[96:97]
	s_mov_b32 m0, s51
	v_lshl_add_u64 v[198:199], s[24:25], 0, v[132:133]
	global_load_lds_dwordx4 v[196:197], off
	v_lshl_add_u64 v[196:197], s[18:19], 0, v[130:131]
	s_add_i32 m0, s51, 0x2000
	s_nop 0
	global_load_lds_dwordx4 v[196:197], off
	v_lshl_add_u64 v[196:197], s[24:25], 0, v[134:135]
	s_mov_b32 m0, s35
	s_nop 0
	global_load_lds_dwordx4 v[196:197], off
	s_mov_b32 m0, s36
	s_nop 0
	global_load_lds_dwordx4 v[198:199], off
	s_waitcnt vmcnt(8)
	s_waitcnt lgkmcnt(0)
	s_barrier
	s_setprio 1
	s_waitcnt lgkmcnt(0)
	v_mfma_f32_16x16x32_bf16 v[60:63], v[148:151], v[180:183], 0
	v_mfma_f32_16x16x32_bf16 v[56:59], v[156:159], v[180:183], 0
	v_mfma_f32_16x16x32_bf16 v[48:51], v[148:151], v[188:191], 0
	v_mfma_f32_16x16x32_bf16 v[40:43], v[156:159], v[188:191], 0
	v_mfma_f32_16x16x32_bf16 v[32:35], v[148:151], v[206:209], 0
	v_mfma_f32_16x16x32_bf16 v[24:27], v[156:159], v[206:209], 0
	v_mfma_f32_16x16x32_bf16 v[16:19], v[148:151], v[214:217], 0
	v_mfma_f32_16x16x32_bf16 v[8:11], v[156:159], v[214:217], 0
	v_mfma_f32_16x16x32_bf16 v[60:63], v[152:155], v[184:187], v[60:63]
	v_mfma_f32_16x16x32_bf16 v[56:59], v[160:163], v[184:187], v[56:59]
	v_mfma_f32_16x16x32_bf16 v[48:51], v[152:155], v[202:205], v[48:51]
	v_mfma_f32_16x16x32_bf16 v[40:43], v[160:163], v[202:205], v[40:43]
	v_mfma_f32_16x16x32_bf16 v[32:35], v[152:155], v[210:213], v[32:35]
	v_mfma_f32_16x16x32_bf16 v[24:27], v[160:163], v[210:213], v[24:27]
	v_mfma_f32_16x16x32_bf16 v[16:19], v[152:155], v[218:221], v[16:19]
	v_mfma_f32_16x16x32_bf16 v[8:11], v[160:163], v[218:221], v[8:11]
	v_mfma_f32_16x16x32_bf16 v[52:55], v[164:167], v[180:183], 0
	v_mfma_f32_16x16x32_bf16 v[44:47], v[172:175], v[180:183], 0
	v_mfma_f32_16x16x32_bf16 v[36:39], v[164:167], v[188:191], 0
	v_mfma_f32_16x16x32_bf16 v[28:31], v[172:175], v[188:191], 0
	v_mfma_f32_16x16x32_bf16 v[20:23], v[164:167], v[206:209], 0
	v_mfma_f32_16x16x32_bf16 v[12:15], v[172:175], v[206:209], 0
	v_mfma_f32_16x16x32_bf16 v[4:7], v[164:167], v[214:217], 0
	v_mfma_f32_16x16x32_bf16 v[0:3], v[172:175], v[214:217], 0
	v_mfma_f32_16x16x32_bf16 v[52:55], v[168:171], v[184:187], v[52:55]
	v_mfma_f32_16x16x32_bf16 v[44:47], v[176:179], v[184:187], v[44:47]
	v_mfma_f32_16x16x32_bf16 v[36:39], v[168:171], v[202:205], v[36:39]
	v_mfma_f32_16x16x32_bf16 v[28:31], v[176:179], v[202:205], v[28:31]
	v_mfma_f32_16x16x32_bf16 v[20:23], v[168:171], v[210:213], v[20:23]
	v_mfma_f32_16x16x32_bf16 v[12:15], v[176:179], v[210:213], v[12:15]
	v_mfma_f32_16x16x32_bf16 v[4:7], v[168:171], v[218:221], v[4:7]
	v_mfma_f32_16x16x32_bf16 v[0:3], v[176:179], v[218:221], v[0:3]
	s_setprio 0
	s_barrier
	s_add_i32 s51, 0, 0x18000
	v_add_u32_e32 v147, s51, v141
	s_add_i32 s52, 0, 0x1c000
	ds_read_b128 v[148:151], v147
	ds_read_b128 v[152:155], v147 offset:1024
	ds_read_b128 v[156:159], v147 offset:2048
	ds_read_b128 v[160:163], v147 offset:3072
	v_add_u32_e32 v147, s52, v141
	ds_read_b128 v[164:167], v147
	ds_read_b128 v[168:171], v147 offset:1024
	ds_read_b128 v[172:175], v147 offset:2048
	ds_read_b128 v[176:179], v147 offset:3072
	s_add_u32 s18, s24, 0x50000
	s_addc_u32 s19, s25, 0
	s_mov_b32 m0, s37
	v_lshl_add_u64 v[200:201], s[18:19], 0, v[134:135]
	ds_read_b128 v[180:183], v146 offset:32768
	ds_read_b128 v[184:187], v146 offset:33792
	ds_read_b128 v[188:191], v146 offset:34816
	ds_read_b128 v[202:205], v146 offset:35840
	ds_read_b128 v[206:209], v146 offset:36864
	ds_read_b128 v[210:213], v146 offset:37888
	ds_read_b128 v[214:217], v146 offset:38912
	ds_read_b128 v[218:221], v146 offset:39936
	global_load_lds_dwordx4 v[200:201], off
	v_lshl_add_u64 v[200:201], s[18:19], 0, v[132:133]
	s_mov_b32 m0, s38
	s_nop 0
	global_load_lds_dwordx4 v[200:201], off
	s_waitcnt vmcnt(8)
	s_waitcnt lgkmcnt(0)
	s_barrier
	s_setprio 1
	s_waitcnt lgkmcnt(0)
	v_mfma_f32_16x16x32_bf16 v[126:129], v[148:151], v[180:183], v[126:129]
	v_mfma_f32_16x16x32_bf16 v[122:125], v[156:159], v[180:183], v[122:125]
	v_mfma_f32_16x16x32_bf16 v[114:117], v[148:151], v[188:191], v[114:117]
	v_mfma_f32_16x16x32_bf16 v[106:109], v[156:159], v[188:191], v[106:109]
	v_mfma_f32_16x16x32_bf16 v[98:101], v[148:151], v[206:209], v[98:101]
	v_mfma_f32_16x16x32_bf16 v[88:91], v[156:159], v[206:209], v[88:91]
	v_mfma_f32_16x16x32_bf16 v[80:83], v[148:151], v[214:217], v[80:83]
	v_mfma_f32_16x16x32_bf16 v[72:75], v[156:159], v[214:217], v[72:75]
	v_mfma_f32_16x16x32_bf16 v[126:129], v[152:155], v[184:187], v[126:129]
	v_mfma_f32_16x16x32_bf16 v[122:125], v[160:163], v[184:187], v[122:125]
	v_mfma_f32_16x16x32_bf16 v[114:117], v[152:155], v[202:205], v[114:117]
	v_mfma_f32_16x16x32_bf16 v[106:109], v[160:163], v[202:205], v[106:109]
	v_mfma_f32_16x16x32_bf16 v[98:101], v[152:155], v[210:213], v[98:101]
	v_mfma_f32_16x16x32_bf16 v[88:91], v[160:163], v[210:213], v[88:91]
	v_mfma_f32_16x16x32_bf16 v[80:83], v[152:155], v[218:221], v[80:83]
	v_mfma_f32_16x16x32_bf16 v[72:75], v[160:163], v[218:221], v[72:75]
	v_mfma_f32_16x16x32_bf16 v[118:121], v[164:167], v[180:183], v[118:121]
	v_mfma_f32_16x16x32_bf16 v[110:113], v[172:175], v[180:183], v[110:113]
	v_mfma_f32_16x16x32_bf16 v[102:105], v[164:167], v[188:191], v[102:105]
	v_mfma_f32_16x16x32_bf16 v[92:95], v[172:175], v[188:191], v[92:95]
	v_mfma_f32_16x16x32_bf16 v[84:87], v[164:167], v[206:209], v[84:87]
	v_mfma_f32_16x16x32_bf16 v[76:79], v[172:175], v[206:209], v[76:79]
	v_mfma_f32_16x16x32_bf16 v[68:71], v[164:167], v[214:217], v[68:71]
	v_mfma_f32_16x16x32_bf16 v[64:67], v[172:175], v[214:217], v[64:67]
	v_mfma_f32_16x16x32_bf16 v[118:121], v[168:171], v[184:187], v[118:121]
	v_mfma_f32_16x16x32_bf16 v[110:113], v[176:179], v[184:187], v[110:113]
	v_mfma_f32_16x16x32_bf16 v[102:105], v[168:171], v[202:205], v[102:105]
	v_mfma_f32_16x16x32_bf16 v[92:95], v[176:179], v[202:205], v[92:95]
	v_mfma_f32_16x16x32_bf16 v[84:87], v[168:171], v[210:213], v[84:87]
	v_mfma_f32_16x16x32_bf16 v[76:79], v[176:179], v[210:213], v[76:79]
	v_mfma_f32_16x16x32_bf16 v[68:71], v[168:171], v[218:221], v[68:71]
	v_mfma_f32_16x16x32_bf16 v[64:67], v[176:179], v[218:221], v[64:67]
	s_setprio 0
	s_barrier
	s_add_i32 s18, s51, s34
	v_lshl_add_u64 v[192:193], v[192:193], 0, s[64:65]
	s_mov_b32 m0, s18
	ds_read_b128 v[180:183], v146 offset:49152
	ds_read_b128 v[184:187], v146 offset:50176
	ds_read_b128 v[188:191], v146 offset:51200
	ds_read_b128 v[202:205], v146 offset:52224
	ds_read_b128 v[206:209], v146 offset:53248
	ds_read_b128 v[210:213], v146 offset:54272
	ds_read_b128 v[214:217], v146 offset:55296
	ds_read_b128 v[218:221], v146 offset:56320
	global_load_lds_dwordx4 v[192:193], off
	s_add_i32 m0, s18, 0x2000
	s_add_u32 s18, s22, 0x18080
	v_lshl_add_u64 v[192:193], v[194:195], 0, s[64:65]
	s_addc_u32 s19, s23, 0
	s_add_i32 s22, s52, s34
	global_load_lds_dwordx4 v[192:193], off
	v_lshl_add_u64 v[192:193], s[18:19], 0, v[96:97]
	s_mov_b32 m0, s22
	s_nop 0
	global_load_lds_dwordx4 v[192:193], off
	v_lshl_add_u64 v[192:193], s[18:19], 0, v[130:131]
	s_add_i32 m0, s22, 0x2000
	s_nop 0
	global_load_lds_dwordx4 v[192:193], off
	v_lshl_add_u64 v[192:193], v[196:197], 0, s[64:65]
	s_mov_b32 m0, s39
	s_nop 0
	global_load_lds_dwordx4 v[192:193], off
	v_lshl_add_u64 v[192:193], v[198:199], 0, s[64:65]
	s_mov_b32 m0, s40
	s_nop 0
	global_load_lds_dwordx4 v[192:193], off
	s_waitcnt vmcnt(8)
	s_waitcnt lgkmcnt(0)
	s_barrier
	s_setprio 1
	s_waitcnt lgkmcnt(0)
	v_mfma_f32_16x16x32_bf16 v[60:63], v[148:151], v[180:183], v[60:63]
	v_mfma_f32_16x16x32_bf16 v[56:59], v[156:159], v[180:183], v[56:59]
	v_mfma_f32_16x16x32_bf16 v[48:51], v[148:151], v[188:191], v[48:51]
	v_mfma_f32_16x16x32_bf16 v[40:43], v[156:159], v[188:191], v[40:43]
	v_mfma_f32_16x16x32_bf16 v[32:35], v[148:151], v[206:209], v[32:35]
	v_mfma_f32_16x16x32_bf16 v[24:27], v[156:159], v[206:209], v[24:27]
	v_mfma_f32_16x16x32_bf16 v[16:19], v[148:151], v[214:217], v[16:19]
	v_mfma_f32_16x16x32_bf16 v[8:11], v[156:159], v[214:217], v[8:11]
	v_mfma_f32_16x16x32_bf16 v[60:63], v[152:155], v[184:187], v[60:63]
	v_mfma_f32_16x16x32_bf16 v[56:59], v[160:163], v[184:187], v[56:59]
	v_mfma_f32_16x16x32_bf16 v[48:51], v[152:155], v[202:205], v[48:51]
	v_mfma_f32_16x16x32_bf16 v[40:43], v[160:163], v[202:205], v[40:43]
	v_mfma_f32_16x16x32_bf16 v[32:35], v[152:155], v[210:213], v[32:35]
	v_mfma_f32_16x16x32_bf16 v[24:27], v[160:163], v[210:213], v[24:27]
	v_mfma_f32_16x16x32_bf16 v[16:19], v[152:155], v[218:221], v[16:19]
	v_mfma_f32_16x16x32_bf16 v[8:11], v[160:163], v[218:221], v[8:11]
	v_mfma_f32_16x16x32_bf16 v[52:55], v[164:167], v[180:183], v[52:55]
	v_mfma_f32_16x16x32_bf16 v[44:47], v[172:175], v[180:183], v[44:47]
	v_mfma_f32_16x16x32_bf16 v[36:39], v[164:167], v[188:191], v[36:39]
	v_mfma_f32_16x16x32_bf16 v[28:31], v[172:175], v[188:191], v[28:31]
	v_mfma_f32_16x16x32_bf16 v[20:23], v[164:167], v[206:209], v[20:23]
	v_mfma_f32_16x16x32_bf16 v[12:15], v[172:175], v[206:209], v[12:15]
	v_mfma_f32_16x16x32_bf16 v[4:7], v[164:167], v[214:217], v[4:7]
	v_mfma_f32_16x16x32_bf16 v[0:3], v[172:175], v[214:217], v[0:3]
	v_mfma_f32_16x16x32_bf16 v[52:55], v[168:171], v[184:187], v[52:55]
	v_mfma_f32_16x16x32_bf16 v[44:47], v[176:179], v[184:187], v[44:47]
	v_mfma_f32_16x16x32_bf16 v[36:39], v[168:171], v[202:205], v[36:39]
	v_mfma_f32_16x16x32_bf16 v[28:31], v[176:179], v[202:205], v[28:31]
	v_mfma_f32_16x16x32_bf16 v[20:23], v[168:171], v[210:213], v[20:23]
	v_mfma_f32_16x16x32_bf16 v[12:15], v[176:179], v[210:213], v[12:15]
	v_mfma_f32_16x16x32_bf16 v[4:7], v[168:171], v[218:221], v[4:7]
	v_mfma_f32_16x16x32_bf16 v[0:3], v[176:179], v[218:221], v[0:3]
	s_setprio 0
	s_barrier
	s_add_i32 s50, s50, 2
	s_add_u32 s48, s48, 0x100
	s_addc_u32 s49, s49, 0
	s_cmp_gt_u32 s50, 3
	s_mov_b64 s[18:19], s[20:21]
	s_cbranch_scc1 .Lpeel_done_861
.LBB0_861:
	s_add_u32 s20, s18, 0x100
	s_addc_u32 s21, s19, 0
	s_add_i32 s51, 0, 0x10000
	s_cmp_eq_u32 s50, 2
	s_cselect_b32 s25, s5, s21
	s_cselect_b32 s24, s4, s20
	v_add_u32_e32 v147, s51, v141
	s_cselect_b32 s23, s17, s49
	s_cselect_b32 s22, s16, s48
	s_add_i32 s52, 0, 0x14000
	ds_read_b128 v[148:151], v147
	ds_read_b128 v[152:155], v147 offset:1024
	ds_read_b128 v[156:159], v147 offset:2048
	ds_read_b128 v[160:163], v147 offset:3072
	v_add_u32_e32 v147, s52, v141
	ds_read_b128 v[164:167], v147
	ds_read_b128 v[168:171], v147 offset:1024
	ds_read_b128 v[172:175], v147 offset:2048
	ds_read_b128 v[176:179], v147 offset:3072
	v_lshl_add_u64 v[192:193], s[18:19], 0, v[136:137]
	s_add_i32 m0, s35, 0xc000
	ds_read_b128 v[180:183], v146
	ds_read_b128 v[184:187], v146 offset:1024
	ds_read_b128 v[188:191], v146 offset:2048
	ds_read_b128 v[202:205], v146 offset:3072
	ds_read_b128 v[206:209], v146 offset:4096
	ds_read_b128 v[210:213], v146 offset:5120
	ds_read_b128 v[214:217], v146 offset:6144
	ds_read_b128 v[218:221], v146 offset:7168
	global_load_lds_dwordx4 v[192:193], off
	v_lshl_add_u64 v[192:193], s[18:19], 0, v[138:139]
	s_add_i32 m0, s35, 0xe000
	s_nop 0
	global_load_lds_dwordx4 v[192:193], off
	s_waitcnt vmcnt(8)
	s_waitcnt lgkmcnt(0)
	s_barrier
	s_setprio 1
	s_waitcnt lgkmcnt(0)
	v_mfma_f32_16x16x32_bf16 v[126:129], v[148:151], v[180:183], v[126:129]
	v_mfma_f32_16x16x32_bf16 v[122:125], v[156:159], v[180:183], v[122:125]
	v_mfma_f32_16x16x32_bf16 v[114:117], v[148:151], v[188:191], v[114:117]
	v_mfma_f32_16x16x32_bf16 v[106:109], v[156:159], v[188:191], v[106:109]
	v_mfma_f32_16x16x32_bf16 v[98:101], v[148:151], v[206:209], v[98:101]
	v_mfma_f32_16x16x32_bf16 v[88:91], v[156:159], v[206:209], v[88:91]
	v_mfma_f32_16x16x32_bf16 v[80:83], v[148:151], v[214:217], v[80:83]
	v_mfma_f32_16x16x32_bf16 v[72:75], v[156:159], v[214:217], v[72:75]
	v_mfma_f32_16x16x32_bf16 v[126:129], v[152:155], v[184:187], v[126:129]
	v_mfma_f32_16x16x32_bf16 v[122:125], v[160:163], v[184:187], v[122:125]
	v_mfma_f32_16x16x32_bf16 v[114:117], v[152:155], v[202:205], v[114:117]
	v_mfma_f32_16x16x32_bf16 v[106:109], v[160:163], v[202:205], v[106:109]
	v_mfma_f32_16x16x32_bf16 v[98:101], v[152:155], v[210:213], v[98:101]
	v_mfma_f32_16x16x32_bf16 v[88:91], v[160:163], v[210:213], v[88:91]
	v_mfma_f32_16x16x32_bf16 v[80:83], v[152:155], v[218:221], v[80:83]
	v_mfma_f32_16x16x32_bf16 v[72:75], v[160:163], v[218:221], v[72:75]
	v_mfma_f32_16x16x32_bf16 v[118:121], v[164:167], v[180:183], v[118:121]
	v_mfma_f32_16x16x32_bf16 v[110:113], v[172:175], v[180:183], v[110:113]
	v_mfma_f32_16x16x32_bf16 v[102:105], v[164:167], v[188:191], v[102:105]
	v_mfma_f32_16x16x32_bf16 v[92:95], v[172:175], v[188:191], v[92:95]
	v_mfma_f32_16x16x32_bf16 v[84:87], v[164:167], v[206:209], v[84:87]
	v_mfma_f32_16x16x32_bf16 v[76:79], v[172:175], v[206:209], v[76:79]
	v_mfma_f32_16x16x32_bf16 v[68:71], v[164:167], v[214:217], v[68:71]
	v_mfma_f32_16x16x32_bf16 v[64:67], v[172:175], v[214:217], v[64:67]
	v_mfma_f32_16x16x32_bf16 v[118:121], v[168:171], v[184:187], v[118:121]
	v_mfma_f32_16x16x32_bf16 v[110:113], v[176:179], v[184:187], v[110:113]
	v_mfma_f32_16x16x32_bf16 v[102:105], v[168:171], v[202:205], v[102:105]
	v_mfma_f32_16x16x32_bf16 v[92:95], v[176:179], v[202:205], v[92:95]
	v_mfma_f32_16x16x32_bf16 v[84:87], v[168:171], v[210:213], v[84:87]
	v_mfma_f32_16x16x32_bf16 v[76:79], v[176:179], v[210:213], v[76:79]
	v_mfma_f32_16x16x32_bf16 v[68:71], v[168:171], v[218:221], v[68:71]
	v_mfma_f32_16x16x32_bf16 v[64:67], v[176:179], v[218:221], v[64:67]
	s_setprio 0
	s_barrier
	s_add_i32 s18, s51, s34
	v_lshl_add_u64 v[192:193], s[22:23], 0, v[96:97]
	s_mov_b32 m0, s18
	ds_read_b128 v[180:183], v146 offset:16384
	ds_read_b128 v[184:187], v146 offset:17408
	ds_read_b128 v[188:191], v146 offset:18432
	ds_read_b128 v[202:205], v146 offset:19456
	ds_read_b128 v[206:209], v146 offset:20480
	ds_read_b128 v[210:213], v146 offset:21504
	ds_read_b128 v[214:217], v146 offset:22528
	ds_read_b128 v[218:221], v146 offset:23552
	global_load_lds_dwordx4 v[192:193], off
	s_add_i32 m0, s18, 0x2000
	s_add_u32 s18, s22, 0x18000
	v_lshl_add_u64 v[194:195], s[22:23], 0, v[130:131]
	s_addc_u32 s19, s23, 0
	s_add_i32 s51, s52, s34
	global_load_lds_dwordx4 v[194:195], off
	v_lshl_add_u64 v[196:197], s[18:19], 0, v[96:97]
	s_mov_b32 m0, s51
	v_lshl_add_u64 v[198:199], s[24:25], 0, v[132:133]
	global_load_lds_dwordx4 v[196:197], off
	v_lshl_add_u64 v[196:197], s[18:19], 0, v[130:131]
	s_add_i32 m0, s51, 0x2000
	s_nop 0
	global_load_lds_dwordx4 v[196:197], off
	v_lshl_add_u64 v[196:197], s[24:25], 0, v[134:135]
	s_mov_b32 m0, s35
	s_nop 0
	global_load_lds_dwordx4 v[196:197], off
	s_mov_b32 m0, s36
	s_nop 0
	global_load_lds_dwordx4 v[198:199], off
	s_waitcnt vmcnt(8)
	s_waitcnt lgkmcnt(0)
	s_barrier
	s_setprio 1
	s_waitcnt lgkmcnt(0)
	v_mfma_f32_16x16x32_bf16 v[60:63], v[148:151], v[180:183], v[60:63]
	v_mfma_f32_16x16x32_bf16 v[56:59], v[156:159], v[180:183], v[56:59]
	v_mfma_f32_16x16x32_bf16 v[48:51], v[148:151], v[188:191], v[48:51]
	v_mfma_f32_16x16x32_bf16 v[40:43], v[156:159], v[188:191], v[40:43]
	v_mfma_f32_16x16x32_bf16 v[32:35], v[148:151], v[206:209], v[32:35]
	v_mfma_f32_16x16x32_bf16 v[24:27], v[156:159], v[206:209], v[24:27]
	v_mfma_f32_16x16x32_bf16 v[16:19], v[148:151], v[214:217], v[16:19]
	v_mfma_f32_16x16x32_bf16 v[8:11], v[156:159], v[214:217], v[8:11]
	v_mfma_f32_16x16x32_bf16 v[60:63], v[152:155], v[184:187], v[60:63]
	v_mfma_f32_16x16x32_bf16 v[56:59], v[160:163], v[184:187], v[56:59]
	v_mfma_f32_16x16x32_bf16 v[48:51], v[152:155], v[202:205], v[48:51]
	v_mfma_f32_16x16x32_bf16 v[40:43], v[160:163], v[202:205], v[40:43]
	v_mfma_f32_16x16x32_bf16 v[32:35], v[152:155], v[210:213], v[32:35]
	v_mfma_f32_16x16x32_bf16 v[24:27], v[160:163], v[210:213], v[24:27]
	v_mfma_f32_16x16x32_bf16 v[16:19], v[152:155], v[218:221], v[16:19]
	v_mfma_f32_16x16x32_bf16 v[8:11], v[160:163], v[218:221], v[8:11]
	v_mfma_f32_16x16x32_bf16 v[52:55], v[164:167], v[180:183], v[52:55]
	v_mfma_f32_16x16x32_bf16 v[44:47], v[172:175], v[180:183], v[44:47]
	v_mfma_f32_16x16x32_bf16 v[36:39], v[164:167], v[188:191], v[36:39]
	v_mfma_f32_16x16x32_bf16 v[28:31], v[172:175], v[188:191], v[28:31]
	v_mfma_f32_16x16x32_bf16 v[20:23], v[164:167], v[206:209], v[20:23]
	v_mfma_f32_16x16x32_bf16 v[12:15], v[172:175], v[206:209], v[12:15]
	v_mfma_f32_16x16x32_bf16 v[4:7], v[164:167], v[214:217], v[4:7]
	v_mfma_f32_16x16x32_bf16 v[0:3], v[172:175], v[214:217], v[0:3]
	v_mfma_f32_16x16x32_bf16 v[52:55], v[168:171], v[184:187], v[52:55]
	v_mfma_f32_16x16x32_bf16 v[44:47], v[176:179], v[184:187], v[44:47]
	v_mfma_f32_16x16x32_bf16 v[36:39], v[168:171], v[202:205], v[36:39]
	v_mfma_f32_16x16x32_bf16 v[28:31], v[176:179], v[202:205], v[28:31]
	v_mfma_f32_16x16x32_bf16 v[20:23], v[168:171], v[210:213], v[20:23]
	v_mfma_f32_16x16x32_bf16 v[12:15], v[176:179], v[210:213], v[12:15]
	v_mfma_f32_16x16x32_bf16 v[4:7], v[168:171], v[218:221], v[4:7]
	v_mfma_f32_16x16x32_bf16 v[0:3], v[176:179], v[218:221], v[0:3]
	s_setprio 0
	s_barrier
	s_add_i32 s51, 0, 0x18000
	v_add_u32_e32 v147, s51, v141
	s_add_i32 s52, 0, 0x1c000
	ds_read_b128 v[148:151], v147
	ds_read_b128 v[152:155], v147 offset:1024
	ds_read_b128 v[156:159], v147 offset:2048
	ds_read_b128 v[160:163], v147 offset:3072
	v_add_u32_e32 v147, s52, v141
	ds_read_b128 v[164:167], v147
	ds_read_b128 v[168:171], v147 offset:1024
	ds_read_b128 v[172:175], v147 offset:2048
	ds_read_b128 v[176:179], v147 offset:3072
	s_add_u32 s18, s24, 0x50000
	s_addc_u32 s19, s25, 0
	s_mov_b32 m0, s37
	v_lshl_add_u64 v[200:201], s[18:19], 0, v[134:135]
	ds_read_b128 v[180:183], v146 offset:32768
	ds_read_b128 v[184:187], v146 offset:33792
	ds_read_b128 v[188:191], v146 offset:34816
	ds_read_b128 v[202:205], v146 offset:35840
	ds_read_b128 v[206:209], v146 offset:36864
	ds_read_b128 v[210:213], v146 offset:37888
	ds_read_b128 v[214:217], v146 offset:38912
	ds_read_b128 v[218:221], v146 offset:39936
	global_load_lds_dwordx4 v[200:201], off
	v_lshl_add_u64 v[200:201], s[18:19], 0, v[132:133]
	s_mov_b32 m0, s38
	s_nop 0
	global_load_lds_dwordx4 v[200:201], off
	s_waitcnt vmcnt(8)
	s_waitcnt lgkmcnt(0)
	s_barrier
	s_setprio 1
	s_waitcnt lgkmcnt(0)
	v_mfma_f32_16x16x32_bf16 v[126:129], v[148:151], v[180:183], v[126:129]
	v_mfma_f32_16x16x32_bf16 v[122:125], v[156:159], v[180:183], v[122:125]
	v_mfma_f32_16x16x32_bf16 v[114:117], v[148:151], v[188:191], v[114:117]
	v_mfma_f32_16x16x32_bf16 v[106:109], v[156:159], v[188:191], v[106:109]
	v_mfma_f32_16x16x32_bf16 v[98:101], v[148:151], v[206:209], v[98:101]
	v_mfma_f32_16x16x32_bf16 v[88:91], v[156:159], v[206:209], v[88:91]
	v_mfma_f32_16x16x32_bf16 v[80:83], v[148:151], v[214:217], v[80:83]
	v_mfma_f32_16x16x32_bf16 v[72:75], v[156:159], v[214:217], v[72:75]
	v_mfma_f32_16x16x32_bf16 v[126:129], v[152:155], v[184:187], v[126:129]
	v_mfma_f32_16x16x32_bf16 v[122:125], v[160:163], v[184:187], v[122:125]
	v_mfma_f32_16x16x32_bf16 v[114:117], v[152:155], v[202:205], v[114:117]
	v_mfma_f32_16x16x32_bf16 v[106:109], v[160:163], v[202:205], v[106:109]
	v_mfma_f32_16x16x32_bf16 v[98:101], v[152:155], v[210:213], v[98:101]
	v_mfma_f32_16x16x32_bf16 v[88:91], v[160:163], v[210:213], v[88:91]
	v_mfma_f32_16x16x32_bf16 v[80:83], v[152:155], v[218:221], v[80:83]
	v_mfma_f32_16x16x32_bf16 v[72:75], v[160:163], v[218:221], v[72:75]
	v_mfma_f32_16x16x32_bf16 v[118:121], v[164:167], v[180:183], v[118:121]
	v_mfma_f32_16x16x32_bf16 v[110:113], v[172:175], v[180:183], v[110:113]
	v_mfma_f32_16x16x32_bf16 v[102:105], v[164:167], v[188:191], v[102:105]
	v_mfma_f32_16x16x32_bf16 v[92:95], v[172:175], v[188:191], v[92:95]
	v_mfma_f32_16x16x32_bf16 v[84:87], v[164:167], v[206:209], v[84:87]
	v_mfma_f32_16x16x32_bf16 v[76:79], v[172:175], v[206:209], v[76:79]
	v_mfma_f32_16x16x32_bf16 v[68:71], v[164:167], v[214:217], v[68:71]
	v_mfma_f32_16x16x32_bf16 v[64:67], v[172:175], v[214:217], v[64:67]
	v_mfma_f32_16x16x32_bf16 v[118:121], v[168:171], v[184:187], v[118:121]
	v_mfma_f32_16x16x32_bf16 v[110:113], v[176:179], v[184:187], v[110:113]
	v_mfma_f32_16x16x32_bf16 v[102:105], v[168:171], v[202:205], v[102:105]
	v_mfma_f32_16x16x32_bf16 v[92:95], v[176:179], v[202:205], v[92:95]
	v_mfma_f32_16x16x32_bf16 v[84:87], v[168:171], v[210:213], v[84:87]
	v_mfma_f32_16x16x32_bf16 v[76:79], v[176:179], v[210:213], v[76:79]
	v_mfma_f32_16x16x32_bf16 v[68:71], v[168:171], v[218:221], v[68:71]
	v_mfma_f32_16x16x32_bf16 v[64:67], v[176:179], v[218:221], v[64:67]
	s_setprio 0
	s_barrier
	s_add_i32 s18, s51, s34
	v_lshl_add_u64 v[192:193], v[192:193], 0, s[64:65]
	s_mov_b32 m0, s18
	ds_read_b128 v[180:183], v146 offset:49152
	ds_read_b128 v[184:187], v146 offset:50176
	ds_read_b128 v[188:191], v146 offset:51200
	ds_read_b128 v[202:205], v146 offset:52224
	ds_read_b128 v[206:209], v146 offset:53248
	ds_read_b128 v[210:213], v146 offset:54272
	ds_read_b128 v[214:217], v146 offset:55296
	ds_read_b128 v[218:221], v146 offset:56320
	global_load_lds_dwordx4 v[192:193], off
	s_add_i32 m0, s18, 0x2000
	s_add_u32 s18, s22, 0x18080
	v_lshl_add_u64 v[192:193], v[194:195], 0, s[64:65]
	s_addc_u32 s19, s23, 0
	s_add_i32 s22, s52, s34
	global_load_lds_dwordx4 v[192:193], off
	v_lshl_add_u64 v[192:193], s[18:19], 0, v[96:97]
	s_mov_b32 m0, s22
	s_nop 0
	global_load_lds_dwordx4 v[192:193], off
	v_lshl_add_u64 v[192:193], s[18:19], 0, v[130:131]
	s_add_i32 m0, s22, 0x2000
	s_nop 0
	global_load_lds_dwordx4 v[192:193], off
	v_lshl_add_u64 v[192:193], v[196:197], 0, s[64:65]
	s_mov_b32 m0, s39
	s_nop 0
	global_load_lds_dwordx4 v[192:193], off
	v_lshl_add_u64 v[192:193], v[198:199], 0, s[64:65]
	s_mov_b32 m0, s40
	s_nop 0
	global_load_lds_dwordx4 v[192:193], off
	s_waitcnt vmcnt(8)
	s_waitcnt lgkmcnt(0)
	s_barrier
	s_setprio 1
	s_waitcnt lgkmcnt(0)
	v_mfma_f32_16x16x32_bf16 v[60:63], v[148:151], v[180:183], v[60:63]
	v_mfma_f32_16x16x32_bf16 v[56:59], v[156:159], v[180:183], v[56:59]
	v_mfma_f32_16x16x32_bf16 v[48:51], v[148:151], v[188:191], v[48:51]
	v_mfma_f32_16x16x32_bf16 v[40:43], v[156:159], v[188:191], v[40:43]
	v_mfma_f32_16x16x32_bf16 v[32:35], v[148:151], v[206:209], v[32:35]
	v_mfma_f32_16x16x32_bf16 v[24:27], v[156:159], v[206:209], v[24:27]
	v_mfma_f32_16x16x32_bf16 v[16:19], v[148:151], v[214:217], v[16:19]
	v_mfma_f32_16x16x32_bf16 v[8:11], v[156:159], v[214:217], v[8:11]
	v_mfma_f32_16x16x32_bf16 v[60:63], v[152:155], v[184:187], v[60:63]
	v_mfma_f32_16x16x32_bf16 v[56:59], v[160:163], v[184:187], v[56:59]
	v_mfma_f32_16x16x32_bf16 v[48:51], v[152:155], v[202:205], v[48:51]
	v_mfma_f32_16x16x32_bf16 v[40:43], v[160:163], v[202:205], v[40:43]
	v_mfma_f32_16x16x32_bf16 v[32:35], v[152:155], v[210:213], v[32:35]
	v_mfma_f32_16x16x32_bf16 v[24:27], v[160:163], v[210:213], v[24:27]
	v_mfma_f32_16x16x32_bf16 v[16:19], v[152:155], v[218:221], v[16:19]
	v_mfma_f32_16x16x32_bf16 v[8:11], v[160:163], v[218:221], v[8:11]
	v_mfma_f32_16x16x32_bf16 v[52:55], v[164:167], v[180:183], v[52:55]
	v_mfma_f32_16x16x32_bf16 v[44:47], v[172:175], v[180:183], v[44:47]
	v_mfma_f32_16x16x32_bf16 v[36:39], v[164:167], v[188:191], v[36:39]
	v_mfma_f32_16x16x32_bf16 v[28:31], v[172:175], v[188:191], v[28:31]
	v_mfma_f32_16x16x32_bf16 v[20:23], v[164:167], v[206:209], v[20:23]
	v_mfma_f32_16x16x32_bf16 v[12:15], v[172:175], v[206:209], v[12:15]
	v_mfma_f32_16x16x32_bf16 v[4:7], v[164:167], v[214:217], v[4:7]
	v_mfma_f32_16x16x32_bf16 v[0:3], v[172:175], v[214:217], v[0:3]
	v_mfma_f32_16x16x32_bf16 v[52:55], v[168:171], v[184:187], v[52:55]
	v_mfma_f32_16x16x32_bf16 v[44:47], v[176:179], v[184:187], v[44:47]
	v_mfma_f32_16x16x32_bf16 v[36:39], v[168:171], v[202:205], v[36:39]
	v_mfma_f32_16x16x32_bf16 v[28:31], v[176:179], v[202:205], v[28:31]
	v_mfma_f32_16x16x32_bf16 v[20:23], v[168:171], v[210:213], v[20:23]
	v_mfma_f32_16x16x32_bf16 v[12:15], v[176:179], v[210:213], v[12:15]
	v_mfma_f32_16x16x32_bf16 v[4:7], v[168:171], v[218:221], v[4:7]
	v_mfma_f32_16x16x32_bf16 v[0:3], v[176:179], v[218:221], v[0:3]
	s_setprio 0
	s_barrier
	s_add_i32 s50, s50, 2
	s_add_u32 s48, s48, 0x100
	s_addc_u32 s49, s49, 0
	s_cmp_gt_u32 s50, 3
	s_mov_b64 s[18:19], s[20:21]
	s_cbranch_scc0 .LBB0_861

.LBB0_885:
	s_add_u32 s29, s24, s28
	s_addc_u32 s36, s25, 0
	s_add_u32 s34, s29, 0x100
	s_addc_u32 s35, s36, 0
	s_and_b64 s[30:31], s[26:27], exec
	s_cselect_b32 s31, s19, s35
	s_cselect_b32 s30, s18, s34
	s_add_u32 s28, s22, s28
	s_addc_u32 s34, s23, 0
	s_add_u32 s28, s28, 0x100
	s_addc_u32 s34, s34, 0
	s_add_i32 s87, 0, 0x10000
	s_and_b64 s[26:27], s[26:27], exec
	s_cselect_b32 s35, s17, s34
	s_cselect_b32 s34, s68, s28
	s_add_i32 s27, 0, 0x14000
	s_add_u32 s38, s29, 0x50080
	s_addc_u32 s39, s36, 0
	s_add_i32 s86, s87, s46
	s_add_i32 m0, s47, 0xc000
	s_add_i32 s90, s47, 0xe000
	s_add_i32 s75, s86, 0x2000
	v_add_u32_e32 v143, s87, v137
	s_add_u32 s36, s34, 0x10000
	ds_read_b128 v[144:147], v143
	ds_read_b128 v[148:151], v143 offset:1024
	ds_read_b128 v[152:155], v143 offset:2048
	ds_read_b128 v[156:159], v143 offset:3072
	v_add_u32_e32 v143, s27, v137
	s_addc_u32 s37, s35, 0
	s_add_i32 s85, s27, s46
	ds_read_b128 v[160:163], v143
	ds_read_b128 v[164:167], v143 offset:1024
	ds_read_b128 v[168:171], v143 offset:2048
	ds_read_b128 v[172:175], v143 offset:3072
	s_add_i32 s79, s85, 0x2000
	s_add_i32 s74, 0, 0x18000
	s_add_i32 s73, 0, 0x1c000
	s_add_u32 s28, s30, 0x50000
	s_addc_u32 s29, s31, 0
	s_add_i32 s72, s74, s46
	s_add_i32 s69, s72, 0x2000
	s_add_u32 s26, s34, 0x10080
	s_addc_u32 s27, s35, 0
	s_add_i32 s88, s73, s46
	s_add_i32 s87, s88, 0x2000
	v_lshl_add_u64 v[192:193], s[38:39], 0, v[134:135]
	ds_read_b128 v[176:179], v142
	ds_read_b128 v[180:183], v142 offset:1024
	ds_read_b128 v[184:187], v142 offset:2048
	ds_read_b128 v[188:191], v142 offset:3072
	ds_read_b128 v[202:205], v142 offset:4096
	ds_read_b128 v[206:209], v142 offset:5120
	ds_read_b128 v[210:213], v142 offset:6144
	ds_read_b128 v[214:217], v142 offset:7168
	global_load_lds_dwordx4 v[192:193], off
	v_lshl_add_u64 v[192:193], s[38:39], 0, v[132:133]
	s_mov_b32 m0, s90
	s_nop 0
	global_load_lds_dwordx4 v[192:193], off
	s_waitcnt vmcnt(8)
	s_waitcnt lgkmcnt(0)
	s_barrier
	s_setprio 1
	s_waitcnt lgkmcnt(0)
	v_mfma_f32_16x16x32_bf16 v[126:129], v[144:147], v[176:179], v[126:129]
	v_mfma_f32_16x16x32_bf16 v[122:125], v[152:155], v[176:179], v[122:125]
	v_mfma_f32_16x16x32_bf16 v[110:113], v[144:147], v[184:187], v[110:113]
	v_mfma_f32_16x16x32_bf16 v[106:109], v[152:155], v[184:187], v[106:109]
	v_mfma_f32_16x16x32_bf16 v[92:95], v[144:147], v[202:205], v[92:95]
	v_mfma_f32_16x16x32_bf16 v[88:91], v[152:155], v[202:205], v[88:91]
	v_mfma_f32_16x16x32_bf16 v[76:79], v[144:147], v[210:213], v[76:79]
	v_mfma_f32_16x16x32_bf16 v[72:75], v[152:155], v[210:213], v[72:75]
	v_mfma_f32_16x16x32_bf16 v[126:129], v[148:151], v[180:183], v[126:129]
	v_mfma_f32_16x16x32_bf16 v[122:125], v[156:159], v[180:183], v[122:125]
	v_mfma_f32_16x16x32_bf16 v[110:113], v[148:151], v[188:191], v[110:113]
	v_mfma_f32_16x16x32_bf16 v[106:109], v[156:159], v[188:191], v[106:109]
	v_mfma_f32_16x16x32_bf16 v[92:95], v[148:151], v[206:209], v[92:95]
	v_mfma_f32_16x16x32_bf16 v[88:91], v[156:159], v[206:209], v[88:91]
	v_mfma_f32_16x16x32_bf16 v[76:79], v[148:151], v[214:217], v[76:79]
	v_mfma_f32_16x16x32_bf16 v[72:75], v[156:159], v[214:217], v[72:75]
	v_mfma_f32_16x16x32_bf16 v[118:121], v[160:163], v[176:179], v[118:121]
	v_mfma_f32_16x16x32_bf16 v[114:117], v[168:171], v[176:179], v[114:117]
	v_mfma_f32_16x16x32_bf16 v[102:105], v[160:163], v[184:187], v[102:105]
	v_mfma_f32_16x16x32_bf16 v[98:101], v[168:171], v[184:187], v[98:101]
	v_mfma_f32_16x16x32_bf16 v[84:87], v[160:163], v[202:205], v[84:87]
	v_mfma_f32_16x16x32_bf16 v[80:83], v[168:171], v[202:205], v[80:83]
	v_mfma_f32_16x16x32_bf16 v[68:71], v[160:163], v[210:213], v[68:71]
	v_mfma_f32_16x16x32_bf16 v[64:67], v[168:171], v[210:213], v[64:67]
	v_mfma_f32_16x16x32_bf16 v[118:121], v[164:167], v[180:183], v[118:121]
	v_mfma_f32_16x16x32_bf16 v[114:117], v[172:175], v[180:183], v[114:117]
	v_mfma_f32_16x16x32_bf16 v[102:105], v[164:167], v[188:191], v[102:105]
	v_mfma_f32_16x16x32_bf16 v[98:101], v[172:175], v[188:191], v[98:101]
	v_mfma_f32_16x16x32_bf16 v[84:87], v[164:167], v[206:209], v[84:87]
	v_mfma_f32_16x16x32_bf16 v[80:83], v[172:175], v[206:209], v[80:83]
	v_mfma_f32_16x16x32_bf16 v[68:71], v[164:167], v[214:217], v[68:71]
	v_mfma_f32_16x16x32_bf16 v[64:67], v[172:175], v[214:217], v[64:67]
	s_setprio 0
	s_barrier
	s_mov_b32 m0, s86
	v_lshl_add_u64 v[192:193], s[34:35], 0, v[96:97]
	ds_read_b128 v[176:179], v142 offset:16384
	ds_read_b128 v[180:183], v142 offset:17408
	ds_read_b128 v[184:187], v142 offset:18432
	ds_read_b128 v[188:191], v142 offset:19456
	ds_read_b128 v[202:205], v142 offset:20480
	ds_read_b128 v[206:209], v142 offset:21504
	ds_read_b128 v[210:213], v142 offset:22528
	ds_read_b128 v[214:217], v142 offset:23552
	global_load_lds_dwordx4 v[192:193], off
	v_lshl_add_u64 v[194:195], s[34:35], 0, v[130:131]
	s_mov_b32 m0, s75
	v_lshl_add_u64 v[196:197], s[36:37], 0, v[96:97]
	global_load_lds_dwordx4 v[194:195], off
	s_mov_b32 m0, s85
	v_lshl_add_u64 v[198:199], s[30:31], 0, v[132:133]
	global_load_lds_dwordx4 v[196:197], off
	v_lshl_add_u64 v[196:197], s[36:37], 0, v[130:131]
	s_mov_b32 m0, s79
	s_nop 0
	global_load_lds_dwordx4 v[196:197], off
	v_lshl_add_u64 v[196:197], s[30:31], 0, v[134:135]
	s_mov_b32 m0, s47
	s_nop 0
	global_load_lds_dwordx4 v[196:197], off
	s_mov_b32 m0, s48
	s_nop 0
	global_load_lds_dwordx4 v[198:199], off
	s_waitcnt vmcnt(8)
	s_waitcnt lgkmcnt(0)
	s_barrier
	s_setprio 1
	s_waitcnt lgkmcnt(0)
	v_mfma_f32_16x16x32_bf16 v[60:63], v[144:147], v[176:179], v[60:63]
	v_mfma_f32_16x16x32_bf16 v[56:59], v[152:155], v[176:179], v[56:59]
	v_mfma_f32_16x16x32_bf16 v[48:51], v[144:147], v[184:187], v[48:51]
	v_mfma_f32_16x16x32_bf16 v[40:43], v[152:155], v[184:187], v[40:43]
	v_mfma_f32_16x16x32_bf16 v[32:35], v[144:147], v[202:205], v[32:35]
	v_mfma_f32_16x16x32_bf16 v[24:27], v[152:155], v[202:205], v[24:27]
	v_mfma_f32_16x16x32_bf16 v[16:19], v[144:147], v[210:213], v[16:19]
	v_mfma_f32_16x16x32_bf16 v[8:11], v[152:155], v[210:213], v[8:11]
	v_mfma_f32_16x16x32_bf16 v[60:63], v[148:151], v[180:183], v[60:63]
	v_mfma_f32_16x16x32_bf16 v[56:59], v[156:159], v[180:183], v[56:59]
	v_mfma_f32_16x16x32_bf16 v[48:51], v[148:151], v[188:191], v[48:51]
	v_mfma_f32_16x16x32_bf16 v[40:43], v[156:159], v[188:191], v[40:43]
	v_mfma_f32_16x16x32_bf16 v[32:35], v[148:151], v[206:209], v[32:35]
	v_mfma_f32_16x16x32_bf16 v[24:27], v[156:159], v[206:209], v[24:27]
	v_mfma_f32_16x16x32_bf16 v[16:19], v[148:151], v[214:217], v[16:19]
	v_mfma_f32_16x16x32_bf16 v[8:11], v[156:159], v[214:217], v[8:11]
	v_mfma_f32_16x16x32_bf16 v[52:55], v[160:163], v[176:179], v[52:55]
	v_mfma_f32_16x16x32_bf16 v[44:47], v[168:171], v[176:179], v[44:47]
	v_mfma_f32_16x16x32_bf16 v[36:39], v[160:163], v[184:187], v[36:39]
	v_mfma_f32_16x16x32_bf16 v[28:31], v[168:171], v[184:187], v[28:31]
	v_mfma_f32_16x16x32_bf16 v[20:23], v[160:163], v[202:205], v[20:23]
	v_mfma_f32_16x16x32_bf16 v[12:15], v[168:171], v[202:205], v[12:15]
	v_mfma_f32_16x16x32_bf16 v[4:7], v[160:163], v[210:213], v[4:7]
	v_mfma_f32_16x16x32_bf16 v[0:3], v[168:171], v[210:213], v[0:3]
	v_mfma_f32_16x16x32_bf16 v[52:55], v[164:167], v[180:183], v[52:55]
	v_mfma_f32_16x16x32_bf16 v[44:47], v[172:175], v[180:183], v[44:47]
	v_mfma_f32_16x16x32_bf16 v[36:39], v[164:167], v[188:191], v[36:39]
	v_mfma_f32_16x16x32_bf16 v[28:31], v[172:175], v[188:191], v[28:31]
	v_mfma_f32_16x16x32_bf16 v[20:23], v[164:167], v[206:209], v[20:23]
	v_mfma_f32_16x16x32_bf16 v[12:15], v[172:175], v[206:209], v[12:15]
	v_mfma_f32_16x16x32_bf16 v[4:7], v[164:167], v[214:217], v[4:7]
	v_mfma_f32_16x16x32_bf16 v[0:3], v[172:175], v[214:217], v[0:3]
	s_setprio 0
	s_barrier
	v_add_u32_e32 v143, s74, v137
	ds_read_b128 v[144:147], v143
	ds_read_b128 v[148:151], v143 offset:1024
	ds_read_b128 v[152:155], v143 offset:2048
	ds_read_b128 v[156:159], v143 offset:3072
	v_add_u32_e32 v143, s73, v137
	ds_read_b128 v[160:163], v143
	ds_read_b128 v[164:167], v143 offset:1024
	ds_read_b128 v[168:171], v143 offset:2048
	ds_read_b128 v[172:175], v143 offset:3072
	s_mov_b32 m0, s49
	v_lshl_add_u64 v[200:201], s[28:29], 0, v[134:135]
	ds_read_b128 v[176:179], v142 offset:32768
	ds_read_b128 v[180:183], v142 offset:33792
	ds_read_b128 v[184:187], v142 offset:34816
	ds_read_b128 v[188:191], v142 offset:35840
	ds_read_b128 v[202:205], v142 offset:36864
	ds_read_b128 v[206:209], v142 offset:37888
	ds_read_b128 v[210:213], v142 offset:38912
	ds_read_b128 v[214:217], v142 offset:39936
	global_load_lds_dwordx4 v[200:201], off
	v_lshl_add_u64 v[200:201], s[28:29], 0, v[132:133]
	s_mov_b32 m0, s50
	s_nop 0
	global_load_lds_dwordx4 v[200:201], off
	s_waitcnt vmcnt(8)
	s_waitcnt lgkmcnt(0)
	s_barrier
	s_setprio 1
	s_waitcnt lgkmcnt(0)
	v_mfma_f32_16x16x32_bf16 v[126:129], v[144:147], v[176:179], v[126:129]
	v_mfma_f32_16x16x32_bf16 v[122:125], v[152:155], v[176:179], v[122:125]
	v_mfma_f32_16x16x32_bf16 v[110:113], v[144:147], v[184:187], v[110:113]
	v_mfma_f32_16x16x32_bf16 v[106:109], v[152:155], v[184:187], v[106:109]
	v_mfma_f32_16x16x32_bf16 v[92:95], v[144:147], v[202:205], v[92:95]
	v_mfma_f32_16x16x32_bf16 v[88:91], v[152:155], v[202:205], v[88:91]
	v_mfma_f32_16x16x32_bf16 v[76:79], v[144:147], v[210:213], v[76:79]
	v_mfma_f32_16x16x32_bf16 v[72:75], v[152:155], v[210:213], v[72:75]
	v_mfma_f32_16x16x32_bf16 v[126:129], v[148:151], v[180:183], v[126:129]
	v_mfma_f32_16x16x32_bf16 v[122:125], v[156:159], v[180:183], v[122:125]
	v_mfma_f32_16x16x32_bf16 v[110:113], v[148:151], v[188:191], v[110:113]
	v_mfma_f32_16x16x32_bf16 v[106:109], v[156:159], v[188:191], v[106:109]
	v_mfma_f32_16x16x32_bf16 v[92:95], v[148:151], v[206:209], v[92:95]
	v_mfma_f32_16x16x32_bf16 v[88:91], v[156:159], v[206:209], v[88:91]
	v_mfma_f32_16x16x32_bf16 v[76:79], v[148:151], v[214:217], v[76:79]
	v_mfma_f32_16x16x32_bf16 v[72:75], v[156:159], v[214:217], v[72:75]
	v_mfma_f32_16x16x32_bf16 v[118:121], v[160:163], v[176:179], v[118:121]
	v_mfma_f32_16x16x32_bf16 v[114:117], v[168:171], v[176:179], v[114:117]
	v_mfma_f32_16x16x32_bf16 v[102:105], v[160:163], v[184:187], v[102:105]
	v_mfma_f32_16x16x32_bf16 v[98:101], v[168:171], v[184:187], v[98:101]
	v_mfma_f32_16x16x32_bf16 v[84:87], v[160:163], v[202:205], v[84:87]
	v_mfma_f32_16x16x32_bf16 v[80:83], v[168:171], v[202:205], v[80:83]
	v_mfma_f32_16x16x32_bf16 v[68:71], v[160:163], v[210:213], v[68:71]
	v_mfma_f32_16x16x32_bf16 v[64:67], v[168:171], v[210:213], v[64:67]
	v_mfma_f32_16x16x32_bf16 v[118:121], v[164:167], v[180:183], v[118:121]
	v_mfma_f32_16x16x32_bf16 v[114:117], v[172:175], v[180:183], v[114:117]
	v_mfma_f32_16x16x32_bf16 v[102:105], v[164:167], v[188:191], v[102:105]
	v_mfma_f32_16x16x32_bf16 v[98:101], v[172:175], v[188:191], v[98:101]
	v_mfma_f32_16x16x32_bf16 v[84:87], v[164:167], v[206:209], v[84:87]
	v_mfma_f32_16x16x32_bf16 v[80:83], v[172:175], v[206:209], v[80:83]
	v_mfma_f32_16x16x32_bf16 v[68:71], v[164:167], v[214:217], v[68:71]
	v_mfma_f32_16x16x32_bf16 v[64:67], v[172:175], v[214:217], v[64:67]
	s_setprio 0
	s_barrier
	s_mov_b32 m0, s72
	v_lshl_add_u64 v[192:193], v[192:193], 0, s[64:65]
	ds_read_b128 v[176:179], v142 offset:49152
	ds_read_b128 v[180:183], v142 offset:50176
	ds_read_b128 v[184:187], v142 offset:51200
	ds_read_b128 v[188:191], v142 offset:52224
	ds_read_b128 v[202:205], v142 offset:53248
	ds_read_b128 v[206:209], v142 offset:54272
	ds_read_b128 v[210:213], v142 offset:55296
	ds_read_b128 v[214:217], v142 offset:56320
	global_load_lds_dwordx4 v[192:193], off
	v_lshl_add_u64 v[192:193], v[194:195], 0, s[64:65]
	s_mov_b32 m0, s69
	s_nop 0
	global_load_lds_dwordx4 v[192:193], off
	v_lshl_add_u64 v[192:193], s[26:27], 0, v[96:97]
	s_mov_b32 m0, s88
	s_nop 0
	global_load_lds_dwordx4 v[192:193], off
	v_lshl_add_u64 v[192:193], s[26:27], 0, v[130:131]
	s_mov_b32 m0, s87
	s_nop 0
	global_load_lds_dwordx4 v[192:193], off
	v_lshl_add_u64 v[192:193], v[196:197], 0, s[64:65]
	s_mov_b32 m0, s51
	s_nop 0
	global_load_lds_dwordx4 v[192:193], off
	v_lshl_add_u64 v[192:193], v[198:199], 0, s[64:65]
	s_mov_b32 m0, s52
	s_nop 0
	global_load_lds_dwordx4 v[192:193], off
	s_waitcnt vmcnt(8)
	s_waitcnt lgkmcnt(0)
	s_barrier
	s_setprio 1
	s_waitcnt lgkmcnt(0)
	v_mfma_f32_16x16x32_bf16 v[60:63], v[144:147], v[176:179], v[60:63]
	v_mfma_f32_16x16x32_bf16 v[56:59], v[152:155], v[176:179], v[56:59]
	v_mfma_f32_16x16x32_bf16 v[48:51], v[144:147], v[184:187], v[48:51]
	v_mfma_f32_16x16x32_bf16 v[40:43], v[152:155], v[184:187], v[40:43]
	v_mfma_f32_16x16x32_bf16 v[32:35], v[144:147], v[202:205], v[32:35]
	v_mfma_f32_16x16x32_bf16 v[24:27], v[152:155], v[202:205], v[24:27]
	v_mfma_f32_16x16x32_bf16 v[16:19], v[144:147], v[210:213], v[16:19]
	v_mfma_f32_16x16x32_bf16 v[8:11], v[152:155], v[210:213], v[8:11]
	v_mfma_f32_16x16x32_bf16 v[60:63], v[148:151], v[180:183], v[60:63]
	v_mfma_f32_16x16x32_bf16 v[56:59], v[156:159], v[180:183], v[56:59]
	v_mfma_f32_16x16x32_bf16 v[48:51], v[148:151], v[188:191], v[48:51]
	v_mfma_f32_16x16x32_bf16 v[40:43], v[156:159], v[188:191], v[40:43]
	v_mfma_f32_16x16x32_bf16 v[32:35], v[148:151], v[206:209], v[32:35]
	v_mfma_f32_16x16x32_bf16 v[24:27], v[156:159], v[206:209], v[24:27]
	v_mfma_f32_16x16x32_bf16 v[16:19], v[148:151], v[214:217], v[16:19]
	v_mfma_f32_16x16x32_bf16 v[8:11], v[156:159], v[214:217], v[8:11]
	v_mfma_f32_16x16x32_bf16 v[52:55], v[160:163], v[176:179], v[52:55]
	v_mfma_f32_16x16x32_bf16 v[44:47], v[168:171], v[176:179], v[44:47]
	v_mfma_f32_16x16x32_bf16 v[36:39], v[160:163], v[184:187], v[36:39]
	v_mfma_f32_16x16x32_bf16 v[28:31], v[168:171], v[184:187], v[28:31]
	v_mfma_f32_16x16x32_bf16 v[20:23], v[160:163], v[202:205], v[20:23]
	v_mfma_f32_16x16x32_bf16 v[12:15], v[168:171], v[202:205], v[12:15]
	v_mfma_f32_16x16x32_bf16 v[4:7], v[160:163], v[210:213], v[4:7]
	v_mfma_f32_16x16x32_bf16 v[0:3], v[168:171], v[210:213], v[0:3]
	v_mfma_f32_16x16x32_bf16 v[52:55], v[164:167], v[180:183], v[52:55]
	v_mfma_f32_16x16x32_bf16 v[44:47], v[172:175], v[180:183], v[44:47]
	v_mfma_f32_16x16x32_bf16 v[36:39], v[164:167], v[188:191], v[36:39]
	v_mfma_f32_16x16x32_bf16 v[28:31], v[172:175], v[188:191], v[28:31]
	v_mfma_f32_16x16x32_bf16 v[20:23], v[164:167], v[206:209], v[20:23]
	v_mfma_f32_16x16x32_bf16 v[12:15], v[172:175], v[206:209], v[12:15]
	v_mfma_f32_16x16x32_bf16 v[4:7], v[164:167], v[214:217], v[4:7]
	v_mfma_f32_16x16x32_bf16 v[0:3], v[172:175], v[214:217], v[0:3]
	s_setprio 0
	s_barrier
	s_movk_i32 s28, 0x100
	s_andn2_b64 vcc, exec, s[4:5]
	s_mov_b64 s[26:27], -1
	s_mov_b64 s[4:5], 0
	s_cbranch_vccz .LBB0_885
	s_and_b64 vcc, exec, s[12:13]
	s_cbranch_vccz .LBB0_888
	s_barrier

.LBB0_908:
	s_ashr_i32 s17, s16, 31
	s_lshl_b64 s[20:21], s[16:17], 17
	s_add_u32 s20, s28, s20
	s_addc_u32 s21, s29, s21
	s_and_b64 s[4:5], s[4:5], exec
	s_cselect_b32 s5, s21, s25
	s_cselect_b32 s4, s20, s24
	s_add_i32 s45, 0, 0x10000
	s_add_i32 s44, 0, 0x14000
	v_add_u32_e32 v214, s45, v141
	v_add_u32_e32 v215, s44, v141
	ds_read_b128 v[0:3], v214
	ds_read_b128 v[4:7], v214 offset:1024
	ds_read_b128 v[8:11], v214 offset:2048
	ds_read_b128 v[12:15], v214 offset:3072
	ds_read_b128 v[16:19], v215
	ds_read_b128 v[20:23], v215 offset:1024
	ds_read_b128 v[24:27], v215 offset:2048
	ds_read_b128 v[28:31], v215 offset:3072
	s_add_u32 s42, s24, 0x10080
	s_addc_u32 s43, s25, 0
	s_add_i32 s47, s23, 0xc000
	v_lshl_add_u64 v[64:65], s[42:43], 0, v[134:135]
	s_mov_b32 m0, s47
	s_add_i32 s17, s23, 0xe000
	ds_read_b128 v[32:35], v143
	ds_read_b128 v[36:39], v143 offset:1024
	ds_read_b128 v[40:43], v143 offset:2048
	ds_read_b128 v[44:47], v143 offset:3072
	ds_read_b128 v[48:51], v143 offset:4096
	ds_read_b128 v[52:55], v143 offset:5120
	ds_read_b128 v[56:59], v143 offset:6144
	ds_read_b128 v[60:63], v143 offset:7168
	global_load_lds_dwordx4 v[64:65], off
	v_lshl_add_u64 v[64:65], s[42:43], 0, v[132:133]
	s_mov_b32 m0, s17
	s_nop 0
	global_load_lds_dwordx4 v[64:65], off
	s_waitcnt vmcnt(8)
	s_waitcnt lgkmcnt(0)
	s_barrier
	s_setprio 1
	s_waitcnt lgkmcnt(0)
	v_mfma_f32_16x16x32_bf16 v[64:67], v[0:3], v[32:35], 0
	v_mfma_f32_16x16x32_bf16 v[68:71], v[8:11], v[32:35], 0
	v_mfma_f32_16x16x32_bf16 v[72:75], v[0:3], v[40:43], 0
	v_mfma_f32_16x16x32_bf16 v[76:79], v[8:11], v[40:43], 0
	v_mfma_f32_16x16x32_bf16 v[80:83], v[0:3], v[48:51], 0
	v_mfma_f32_16x16x32_bf16 v[84:87], v[8:11], v[48:51], 0
	v_mfma_f32_16x16x32_bf16 v[88:91], v[0:3], v[56:59], 0
	v_mfma_f32_16x16x32_bf16 v[92:95], v[8:11], v[56:59], 0
	v_mfma_f32_16x16x32_bf16 v[64:67], v[4:7], v[36:39], v[64:67]
	v_mfma_f32_16x16x32_bf16 v[68:71], v[12:15], v[36:39], v[68:71]
	v_mfma_f32_16x16x32_bf16 v[72:75], v[4:7], v[44:47], v[72:75]
	v_mfma_f32_16x16x32_bf16 v[76:79], v[12:15], v[44:47], v[76:79]
	v_mfma_f32_16x16x32_bf16 v[80:83], v[4:7], v[52:55], v[80:83]
	v_mfma_f32_16x16x32_bf16 v[84:87], v[12:15], v[52:55], v[84:87]
	v_mfma_f32_16x16x32_bf16 v[88:91], v[4:7], v[60:63], v[88:91]
	v_mfma_f32_16x16x32_bf16 v[92:95], v[12:15], v[60:63], v[92:95]
	v_mfma_f32_16x16x32_bf16 v[98:101], v[16:19], v[32:35], 0
	v_mfma_f32_16x16x32_bf16 v[32:35], v[24:27], v[32:35], 0
	v_mfma_f32_16x16x32_bf16 v[98:101], v[20:23], v[36:39], v[98:101]
	v_mfma_f32_16x16x32_bf16 v[32:35], v[28:31], v[36:39], v[32:35]
	v_mfma_f32_16x16x32_bf16 v[36:39], v[16:19], v[40:43], 0
	v_mfma_f32_16x16x32_bf16 v[40:43], v[24:27], v[40:43], 0
	v_mfma_f32_16x16x32_bf16 v[36:39], v[20:23], v[44:47], v[36:39]
	v_mfma_f32_16x16x32_bf16 v[40:43], v[28:31], v[44:47], v[40:43]
	v_mfma_f32_16x16x32_bf16 v[44:47], v[16:19], v[48:51], 0
	v_mfma_f32_16x16x32_bf16 v[48:51], v[24:27], v[48:51], 0
	v_mfma_f32_16x16x32_bf16 v[44:47], v[20:23], v[52:55], v[44:47]
	v_mfma_f32_16x16x32_bf16 v[48:51], v[28:31], v[52:55], v[48:51]
	v_mfma_f32_16x16x32_bf16 v[52:55], v[16:19], v[56:59], 0
	v_mfma_f32_16x16x32_bf16 v[56:59], v[24:27], v[56:59], 0
	v_mfma_f32_16x16x32_bf16 v[52:55], v[20:23], v[60:63], v[52:55]
	v_mfma_f32_16x16x32_bf16 v[56:59], v[28:31], v[60:63], v[56:59]
	s_setprio 0
	s_barrier
	s_add_i32 s45, s45, s34
	v_lshl_add_u64 v[192:193], s[26:27], 0, v[96:97]
	s_add_i32 s42, s45, 0x2000
	v_lshl_add_u64 v[136:137], v[192:193], 0, s[66:67]
	s_mov_b32 m0, s45
	v_lshl_add_u64 v[194:195], s[26:27], 0, v[130:131]
	s_add_u32 s48, s26, 0x50100
	ds_read_b128 v[60:63], v143 offset:16384
	ds_read_b128 v[102:105], v143 offset:17408
	ds_read_b128 v[106:109], v143 offset:18432
	ds_read_b128 v[110:113], v143 offset:19456
	ds_read_b128 v[114:117], v143 offset:20480
	ds_read_b128 v[118:121], v143 offset:21504
	ds_read_b128 v[122:125], v143 offset:22528
	ds_read_b128 v[126:129], v143 offset:23552
	global_load_lds_dwordx4 v[136:137], off
	v_lshl_add_u64 v[136:137], v[194:195], 0, s[66:67]
	s_mov_b32 m0, s42
	s_addc_u32 s49, s27, 0
	s_add_i32 s43, s44, s34
	global_load_lds_dwordx4 v[136:137], off
	v_lshl_add_u64 v[136:137], s[48:49], 0, v[96:97]
	s_mov_b32 m0, s43
	s_add_i32 s44, s43, 0x2000
	global_load_lds_dwordx4 v[136:137], off
	v_lshl_add_u64 v[136:137], s[48:49], 0, v[130:131]
	s_mov_b32 m0, s44
	v_lshl_add_u64 v[196:197], s[24:25], 0, v[134:135]
	global_load_lds_dwordx4 v[136:137], off
	v_lshl_add_u64 v[136:137], v[196:197], 0, s[66:67]
	s_mov_b32 m0, s23
	v_lshl_add_u64 v[198:199], s[24:25], 0, v[132:133]
	global_load_lds_dwordx4 v[136:137], off
	v_lshl_add_u64 v[136:137], v[198:199], 0, s[66:67]
	s_mov_b32 m0, s35
	s_nop 0
	global_load_lds_dwordx4 v[136:137], off
	s_waitcnt vmcnt(8)
	s_waitcnt lgkmcnt(0)
	s_barrier
	s_setprio 1
	s_waitcnt lgkmcnt(0)
	v_mfma_f32_16x16x32_bf16 v[136:139], v[0:3], v[60:63], 0
	v_mfma_f32_16x16x32_bf16 v[148:151], v[0:3], v[106:109], 0
	v_mfma_f32_16x16x32_bf16 v[156:159], v[0:3], v[114:117], 0
	v_mfma_f32_16x16x32_bf16 v[0:3], v[0:3], v[122:125], 0
	v_mfma_f32_16x16x32_bf16 v[136:139], v[4:7], v[102:105], v[136:139]
	v_mfma_f32_16x16x32_bf16 v[148:151], v[4:7], v[110:113], v[148:151]
	v_mfma_f32_16x16x32_bf16 v[156:159], v[4:7], v[118:121], v[156:159]
	v_mfma_f32_16x16x32_bf16 v[0:3], v[4:7], v[126:129], v[0:3]
	v_mfma_f32_16x16x32_bf16 v[4:7], v[8:11], v[122:125], 0
	v_mfma_f32_16x16x32_bf16 v[144:147], v[8:11], v[60:63], 0
	v_mfma_f32_16x16x32_bf16 v[152:155], v[8:11], v[106:109], 0
	v_mfma_f32_16x16x32_bf16 v[160:163], v[8:11], v[114:117], 0
	v_mfma_f32_16x16x32_bf16 v[4:7], v[12:15], v[126:129], v[4:7]
	v_mfma_f32_16x16x32_bf16 v[144:147], v[12:15], v[102:105], v[144:147]
	v_mfma_f32_16x16x32_bf16 v[152:155], v[12:15], v[110:113], v[152:155]
	v_mfma_f32_16x16x32_bf16 v[160:163], v[12:15], v[118:121], v[160:163]
	v_mfma_f32_16x16x32_bf16 v[8:11], v[16:19], v[60:63], 0
	v_mfma_f32_16x16x32_bf16 v[12:15], v[24:27], v[60:63], 0
	v_mfma_f32_16x16x32_bf16 v[8:11], v[20:23], v[102:105], v[8:11]
	v_mfma_f32_16x16x32_bf16 v[12:15], v[28:31], v[102:105], v[12:15]
	v_mfma_f32_16x16x32_bf16 v[60:63], v[16:19], v[106:109], 0
	v_mfma_f32_16x16x32_bf16 v[102:105], v[24:27], v[106:109], 0
	v_mfma_f32_16x16x32_bf16 v[106:109], v[16:19], v[114:117], 0
	v_mfma_f32_16x16x32_bf16 v[16:19], v[16:19], v[122:125], 0
	v_mfma_f32_16x16x32_bf16 v[60:63], v[20:23], v[110:113], v[60:63]
	v_mfma_f32_16x16x32_bf16 v[102:105], v[28:31], v[110:113], v[102:105]
	v_mfma_f32_16x16x32_bf16 v[106:109], v[20:23], v[118:121], v[106:109]
	v_mfma_f32_16x16x32_bf16 v[110:113], v[24:27], v[114:117], 0
	v_mfma_f32_16x16x32_bf16 v[16:19], v[20:23], v[126:129], v[16:19]
	v_mfma_f32_16x16x32_bf16 v[20:23], v[24:27], v[122:125], 0
	v_mfma_f32_16x16x32_bf16 v[110:113], v[28:31], v[118:121], v[110:113]
	v_mfma_f32_16x16x32_bf16 v[20:23], v[28:31], v[126:129], v[20:23]
	s_setprio 0
	s_barrier
	s_add_i32 s46, 0, 0x18000
	s_add_i32 s52, 0, 0x1c000
	v_add_u32_e32 v234, s46, v141
	v_add_u32_e32 v242, s52, v141
	ds_read_b128 v[24:27], v234
	ds_read_b128 v[28:31], v234 offset:1024
	ds_read_b128 v[114:117], v234 offset:2048
	ds_read_b128 v[118:121], v234 offset:3072
	ds_read_b128 v[122:125], v242
	ds_read_b128 v[126:129], v242 offset:1024
	ds_read_b128 v[164:167], v242 offset:2048
	ds_read_b128 v[168:171], v242 offset:3072
	s_add_u32 s48, s24, 0x10100
	s_addc_u32 s49, s25, 0
	s_mov_b32 m0, s36
	v_lshl_add_u64 v[200:201], s[48:49], 0, v[134:135]
	ds_read_b128 v[172:175], v143 offset:32768
	ds_read_b128 v[176:179], v143 offset:33792
	ds_read_b128 v[180:183], v143 offset:34816
	ds_read_b128 v[184:187], v143 offset:35840
	ds_read_b128 v[188:191], v143 offset:36864
	ds_read_b128 v[202:205], v143 offset:37888
	ds_read_b128 v[206:209], v143 offset:38912
	ds_read_b128 v[210:213], v143 offset:39936
	global_load_lds_dwordx4 v[200:201], off
	v_lshl_add_u64 v[200:201], s[48:49], 0, v[132:133]
	s_mov_b32 m0, s37
	s_nop 0
	global_load_lds_dwordx4 v[200:201], off
	s_waitcnt vmcnt(8)
	s_waitcnt lgkmcnt(0)
	s_barrier
	s_setprio 1
	s_waitcnt lgkmcnt(0)
	v_mfma_f32_16x16x32_bf16 v[64:67], v[24:27], v[172:175], v[64:67]
	v_mfma_f32_16x16x32_bf16 v[68:71], v[114:117], v[172:175], v[68:71]
	v_mfma_f32_16x16x32_bf16 v[72:75], v[24:27], v[180:183], v[72:75]
	v_mfma_f32_16x16x32_bf16 v[76:79], v[114:117], v[180:183], v[76:79]
	v_mfma_f32_16x16x32_bf16 v[80:83], v[24:27], v[188:191], v[80:83]
	v_mfma_f32_16x16x32_bf16 v[84:87], v[114:117], v[188:191], v[84:87]
	v_mfma_f32_16x16x32_bf16 v[88:91], v[24:27], v[206:209], v[88:91]
	v_mfma_f32_16x16x32_bf16 v[92:95], v[114:117], v[206:209], v[92:95]
	v_mfma_f32_16x16x32_bf16 v[64:67], v[28:31], v[176:179], v[64:67]
	v_mfma_f32_16x16x32_bf16 v[68:71], v[118:121], v[176:179], v[68:71]
	v_mfma_f32_16x16x32_bf16 v[72:75], v[28:31], v[184:187], v[72:75]
	v_mfma_f32_16x16x32_bf16 v[76:79], v[118:121], v[184:187], v[76:79]
	v_mfma_f32_16x16x32_bf16 v[80:83], v[28:31], v[202:205], v[80:83]
	v_mfma_f32_16x16x32_bf16 v[84:87], v[118:121], v[202:205], v[84:87]
	v_mfma_f32_16x16x32_bf16 v[88:91], v[28:31], v[210:213], v[88:91]
	v_mfma_f32_16x16x32_bf16 v[92:95], v[118:121], v[210:213], v[92:95]
	v_mfma_f32_16x16x32_bf16 v[98:101], v[122:125], v[172:175], v[98:101]
	v_mfma_f32_16x16x32_bf16 v[32:35], v[164:167], v[172:175], v[32:35]
	v_mfma_f32_16x16x32_bf16 v[36:39], v[122:125], v[180:183], v[36:39]
	v_mfma_f32_16x16x32_bf16 v[40:43], v[164:167], v[180:183], v[40:43]
	v_mfma_f32_16x16x32_bf16 v[44:47], v[122:125], v[188:191], v[44:47]
	v_mfma_f32_16x16x32_bf16 v[48:51], v[164:167], v[188:191], v[48:51]
	v_mfma_f32_16x16x32_bf16 v[52:55], v[122:125], v[206:209], v[52:55]
	v_mfma_f32_16x16x32_bf16 v[56:59], v[164:167], v[206:209], v[56:59]
	v_mfma_f32_16x16x32_bf16 v[98:101], v[126:129], v[176:179], v[98:101]
	v_mfma_f32_16x16x32_bf16 v[32:35], v[168:171], v[176:179], v[32:35]
	v_mfma_f32_16x16x32_bf16 v[36:39], v[126:129], v[184:187], v[36:39]
	v_mfma_f32_16x16x32_bf16 v[40:43], v[168:171], v[184:187], v[40:43]
	v_mfma_f32_16x16x32_bf16 v[44:47], v[126:129], v[202:205], v[44:47]
	v_mfma_f32_16x16x32_bf16 v[48:51], v[168:171], v[202:205], v[48:51]
	v_mfma_f32_16x16x32_bf16 v[52:55], v[126:129], v[210:213], v[52:55]
	v_mfma_f32_16x16x32_bf16 v[56:59], v[168:171], v[210:213], v[56:59]
	s_setprio 0
	s_barrier
	s_add_i32 s48, s46, s34
	s_add_i32 s46, s48, 0x2000
	v_lshl_add_u64 v[192:193], v[192:193], 0, s[80:81]
	s_mov_b32 m0, s48
	s_add_u32 s50, s26, 0x50180
	ds_read_b128 v[172:175], v143 offset:49152
	ds_read_b128 v[176:179], v143 offset:50176
	ds_read_b128 v[180:183], v143 offset:51200
	ds_read_b128 v[184:187], v143 offset:52224
	ds_read_b128 v[188:191], v143 offset:53248
	ds_read_b128 v[202:205], v143 offset:54272
	ds_read_b128 v[206:209], v143 offset:55296
	ds_read_b128 v[210:213], v143 offset:56320
	global_load_lds_dwordx4 v[192:193], off
	v_lshl_add_u64 v[192:193], v[194:195], 0, s[80:81]
	s_mov_b32 m0, s46
	s_addc_u32 s51, s27, 0
	s_add_i32 s26, s52, s34
	global_load_lds_dwordx4 v[192:193], off
	v_lshl_add_u64 v[192:193], s[50:51], 0, v[96:97]
	s_mov_b32 m0, s26
	s_add_i32 s27, s26, 0x2000
	global_load_lds_dwordx4 v[192:193], off
	v_lshl_add_u64 v[192:193], s[50:51], 0, v[130:131]
	s_mov_b32 m0, s27
	s_nop 0
	global_load_lds_dwordx4 v[192:193], off
	v_lshl_add_u64 v[192:193], v[196:197], 0, s[80:81]
	s_mov_b32 m0, s38
	s_nop 0
	global_load_lds_dwordx4 v[192:193], off
	v_lshl_add_u64 v[192:193], v[198:199], 0, s[80:81]
	s_mov_b32 m0, s39
	s_nop 0
	global_load_lds_dwordx4 v[192:193], off
	s_waitcnt vmcnt(8)
	s_waitcnt lgkmcnt(0)
	s_barrier
	s_setprio 1
	s_waitcnt lgkmcnt(0)
	v_mfma_f32_16x16x32_bf16 v[0:3], v[24:27], v[206:209], v[0:3]
	v_mfma_f32_16x16x32_bf16 v[4:7], v[114:117], v[206:209], v[4:7]
	v_mfma_f32_16x16x32_bf16 v[136:139], v[24:27], v[172:175], v[136:139]
	v_mfma_f32_16x16x32_bf16 v[144:147], v[114:117], v[172:175], v[144:147]
	v_mfma_f32_16x16x32_bf16 v[148:151], v[24:27], v[180:183], v[148:151]
	v_mfma_f32_16x16x32_bf16 v[152:155], v[114:117], v[180:183], v[152:155]
	v_mfma_f32_16x16x32_bf16 v[156:159], v[24:27], v[188:191], v[156:159]
	v_mfma_f32_16x16x32_bf16 v[160:163], v[114:117], v[188:191], v[160:163]
	v_mfma_f32_16x16x32_bf16 v[0:3], v[28:31], v[210:213], v[0:3]
	v_mfma_f32_16x16x32_bf16 v[4:7], v[118:121], v[210:213], v[4:7]
	v_mfma_f32_16x16x32_bf16 v[136:139], v[28:31], v[176:179], v[136:139]
	v_mfma_f32_16x16x32_bf16 v[144:147], v[118:121], v[176:179], v[144:147]
	v_mfma_f32_16x16x32_bf16 v[148:151], v[28:31], v[184:187], v[148:151]
	v_mfma_f32_16x16x32_bf16 v[152:155], v[118:121], v[184:187], v[152:155]
	v_mfma_f32_16x16x32_bf16 v[156:159], v[28:31], v[202:205], v[156:159]
	v_mfma_f32_16x16x32_bf16 v[160:163], v[118:121], v[202:205], v[160:163]
	v_mfma_f32_16x16x32_bf16 v[8:11], v[122:125], v[172:175], v[8:11]
	v_mfma_f32_16x16x32_bf16 v[12:15], v[164:167], v[172:175], v[12:15]
	v_mfma_f32_16x16x32_bf16 v[24:27], v[122:125], v[180:183], v[60:63]
	v_mfma_f32_16x16x32_bf16 v[28:31], v[164:167], v[180:183], v[102:105]
	v_mfma_f32_16x16x32_bf16 v[60:63], v[122:125], v[188:191], v[106:109]
	v_mfma_f32_16x16x32_bf16 v[102:105], v[164:167], v[188:191], v[110:113]
	v_mfma_f32_16x16x32_bf16 v[16:19], v[122:125], v[206:209], v[16:19]
	v_mfma_f32_16x16x32_bf16 v[20:23], v[164:167], v[206:209], v[20:23]
	v_mfma_f32_16x16x32_bf16 v[8:11], v[126:129], v[176:179], v[8:11]
	v_mfma_f32_16x16x32_bf16 v[12:15], v[168:171], v[176:179], v[12:15]
	v_mfma_f32_16x16x32_bf16 v[24:27], v[126:129], v[184:187], v[24:27]
	v_mfma_f32_16x16x32_bf16 v[28:31], v[168:171], v[184:187], v[28:31]
	v_mfma_f32_16x16x32_bf16 v[60:63], v[126:129], v[202:205], v[60:63]
	v_mfma_f32_16x16x32_bf16 v[102:105], v[168:171], v[202:205], v[102:105]
	v_mfma_f32_16x16x32_bf16 v[16:19], v[126:129], v[210:213], v[16:19]
	v_mfma_f32_16x16x32_bf16 v[20:23], v[168:171], v[210:213], v[20:23]
	s_setprio 0
	s_barrier
	ds_read_b128 v[106:109], v214
	ds_read_b128 v[110:113], v214 offset:1024
	ds_read_b128 v[114:117], v214 offset:2048
	ds_read_b128 v[118:121], v214 offset:3072
	ds_read_b128 v[122:125], v215
	ds_read_b128 v[126:129], v215 offset:1024
	ds_read_b128 v[164:167], v215 offset:2048
	ds_read_b128 v[168:171], v215 offset:3072
	s_add_u32 s24, s24, 0x10180
	s_addc_u32 s25, s25, 0
	s_mov_b32 m0, s47
	v_lshl_add_u64 v[192:193], s[24:25], 0, v[134:135]
	ds_read_b128 v[172:175], v143
	ds_read_b128 v[176:179], v143 offset:1024
	ds_read_b128 v[180:183], v143 offset:2048
	ds_read_b128 v[184:187], v143 offset:3072
	ds_read_b128 v[188:191], v143 offset:4096
	ds_read_b128 v[202:205], v143 offset:5120
	ds_read_b128 v[206:209], v143 offset:6144
	ds_read_b128 v[210:213], v143 offset:7168
	global_load_lds_dwordx4 v[192:193], off
	v_lshl_add_u64 v[192:193], s[24:25], 0, v[132:133]
	s_mov_b32 m0, s17
	s_nop 0
	global_load_lds_dwordx4 v[192:193], off
	s_waitcnt vmcnt(8)
	s_waitcnt lgkmcnt(0)
	s_barrier
	s_setprio 1
	s_waitcnt lgkmcnt(0)
	v_mfma_f32_16x16x32_bf16 v[88:91], v[106:109], v[206:209], v[88:91]
	v_mfma_f32_16x16x32_bf16 v[64:67], v[106:109], v[172:175], v[64:67]
	v_mfma_f32_16x16x32_bf16 v[68:71], v[114:117], v[172:175], v[68:71]
	v_mfma_f32_16x16x32_bf16 v[72:75], v[106:109], v[180:183], v[72:75]
	v_mfma_f32_16x16x32_bf16 v[76:79], v[114:117], v[180:183], v[76:79]
	v_mfma_f32_16x16x32_bf16 v[80:83], v[106:109], v[188:191], v[80:83]
	v_mfma_f32_16x16x32_bf16 v[84:87], v[114:117], v[188:191], v[84:87]
	v_mfma_f32_16x16x32_bf16 v[214:217], v[110:113], v[210:213], v[88:91]
	v_mfma_f32_16x16x32_bf16 v[88:91], v[114:117], v[206:209], v[92:95]
	v_mfma_f32_16x16x32_bf16 v[64:67], v[110:113], v[176:179], v[64:67]
	v_mfma_f32_16x16x32_bf16 v[68:71], v[118:121], v[176:179], v[68:71]
	v_mfma_f32_16x16x32_bf16 v[72:75], v[110:113], v[184:187], v[72:75]
	v_mfma_f32_16x16x32_bf16 v[76:79], v[118:121], v[184:187], v[76:79]
	v_mfma_f32_16x16x32_bf16 v[80:83], v[110:113], v[202:205], v[80:83]
	v_mfma_f32_16x16x32_bf16 v[84:87], v[118:121], v[202:205], v[84:87]
	v_mfma_f32_16x16x32_bf16 v[92:95], v[118:121], v[210:213], v[88:91]
	v_mfma_f32_16x16x32_bf16 v[44:47], v[122:125], v[188:191], v[44:47]
	v_mfma_f32_16x16x32_bf16 v[88:91], v[122:125], v[172:175], v[98:101]
	v_mfma_f32_16x16x32_bf16 v[32:35], v[164:167], v[172:175], v[32:35]
	v_mfma_f32_16x16x32_bf16 v[172:175], v[126:129], v[202:205], v[44:47]
	v_mfma_f32_16x16x32_bf16 v[44:47], v[164:167], v[188:191], v[48:51]
	v_mfma_f32_16x16x32_bf16 v[218:221], v[126:129], v[176:179], v[88:91]
	v_mfma_f32_16x16x32_bf16 v[32:35], v[168:171], v[176:179], v[32:35]
	v_mfma_f32_16x16x32_bf16 v[36:39], v[122:125], v[180:183], v[36:39]
	v_mfma_f32_16x16x32_bf16 v[40:43], v[164:167], v[180:183], v[40:43]
	v_mfma_f32_16x16x32_bf16 v[176:179], v[168:171], v[202:205], v[44:47]
	v_mfma_f32_16x16x32_bf16 v[44:47], v[122:125], v[206:209], v[52:55]
	v_mfma_f32_16x16x32_bf16 v[36:39], v[126:129], v[184:187], v[36:39]
	v_mfma_f32_16x16x32_bf16 v[40:43], v[168:171], v[184:187], v[40:43]
	v_mfma_f32_16x16x32_bf16 v[52:55], v[126:129], v[210:213], v[44:47]
	v_mfma_f32_16x16x32_bf16 v[44:47], v[164:167], v[206:209], v[56:59]
	v_mfma_f32_16x16x32_bf16 v[180:183], v[168:171], v[210:213], v[44:47]
	s_setprio 0
	s_barrier
	s_mov_b32 m0, s45
	v_lshl_add_u64 v[192:193], s[18:19], 0, v[96:97]
	s_add_u32 s24, s18, 0x50000
	s_nop 1
	ds_read_b128 v[44:47], v143 offset:16384
	ds_read_b128 v[48:51], v143 offset:17408
	ds_read_b128 v[56:59], v143 offset:18432
	ds_read_b128 v[88:91], v143 offset:19456
	ds_read_b128 v[98:101], v143 offset:20480
	ds_read_b128 v[184:187], v143 offset:21504
	ds_read_b128 v[188:191], v143 offset:22528
	ds_read_b128 v[202:205], v143 offset:23552
	global_load_lds_dwordx4 v[192:193], off
	v_lshl_add_u64 v[194:195], s[18:19], 0, v[130:131]
	s_mov_b32 m0, s42
	s_addc_u32 s25, s19, 0
	global_load_lds_dwordx4 v[194:195], off
	v_lshl_add_u64 v[196:197], s[24:25], 0, v[96:97]
	s_mov_b32 m0, s43
	v_lshl_add_u64 v[246:247], s[4:5], 0, v[132:133]
	global_load_lds_dwordx4 v[196:197], off
	v_lshl_add_u64 v[196:197], s[24:25], 0, v[130:131]
	s_mov_b32 m0, s44
	s_nop 0
	global_load_lds_dwordx4 v[196:197], off
	v_lshl_add_u64 v[196:197], s[4:5], 0, v[134:135]
	s_mov_b32 m0, s23
	s_nop 0
	global_load_lds_dwordx4 v[196:197], off
	s_mov_b32 m0, s35
	s_nop 0
	global_load_lds_dwordx4 v[246:247], off
	s_waitcnt vmcnt(8)
	s_waitcnt lgkmcnt(0)
	s_barrier
	s_setprio 1
	s_waitcnt lgkmcnt(0)
	v_mfma_f32_16x16x32_bf16 v[0:3], v[106:109], v[188:191], v[0:3]
	v_mfma_f32_16x16x32_bf16 v[136:139], v[106:109], v[44:47], v[136:139]
	v_mfma_f32_16x16x32_bf16 v[144:147], v[114:117], v[44:47], v[144:147]
	v_mfma_f32_16x16x32_bf16 v[148:151], v[106:109], v[56:59], v[148:151]
	v_mfma_f32_16x16x32_bf16 v[152:155], v[114:117], v[56:59], v[152:155]
	v_mfma_f32_16x16x32_bf16 v[156:159], v[106:109], v[98:101], v[156:159]
	v_mfma_f32_16x16x32_bf16 v[160:163], v[114:117], v[98:101], v[160:163]
	v_mfma_f32_16x16x32_bf16 v[0:3], v[110:113], v[202:205], v[0:3]
	v_mfma_f32_16x16x32_bf16 v[4:7], v[114:117], v[188:191], v[4:7]
	v_mfma_f32_16x16x32_bf16 v[136:139], v[110:113], v[48:51], v[136:139]
	v_mfma_f32_16x16x32_bf16 v[144:147], v[118:121], v[48:51], v[144:147]
	v_mfma_f32_16x16x32_bf16 v[148:151], v[110:113], v[88:91], v[148:151]
	v_mfma_f32_16x16x32_bf16 v[152:155], v[118:121], v[88:91], v[152:155]
	v_mfma_f32_16x16x32_bf16 v[156:159], v[110:113], v[184:187], v[156:159]
	v_mfma_f32_16x16x32_bf16 v[160:163], v[118:121], v[184:187], v[160:163]
	v_mfma_f32_16x16x32_bf16 v[206:209], v[118:121], v[202:205], v[4:7]
	v_mfma_f32_16x16x32_bf16 v[4:7], v[122:125], v[44:47], v[8:11]
	v_mfma_f32_16x16x32_bf16 v[8:11], v[126:129], v[48:51], v[4:7]
	v_mfma_f32_16x16x32_bf16 v[4:7], v[164:167], v[44:47], v[12:15]
	v_mfma_f32_16x16x32_bf16 v[210:213], v[168:171], v[48:51], v[4:7]
	v_mfma_f32_16x16x32_bf16 v[4:7], v[122:125], v[56:59], v[24:27]
	v_mfma_f32_16x16x32_bf16 v[24:27], v[126:129], v[88:91], v[4:7]
	v_mfma_f32_16x16x32_bf16 v[4:7], v[164:167], v[56:59], v[28:31]
	v_mfma_f32_16x16x32_bf16 v[222:225], v[168:171], v[88:91], v[4:7]
	v_mfma_f32_16x16x32_bf16 v[4:7], v[122:125], v[98:101], v[60:63]
	v_mfma_f32_16x16x32_bf16 v[226:229], v[126:129], v[184:187], v[4:7]
	v_mfma_f32_16x16x32_bf16 v[4:7], v[164:167], v[98:101], v[102:105]
	v_mfma_f32_16x16x32_bf16 v[184:187], v[168:171], v[184:187], v[4:7]
	v_mfma_f32_16x16x32_bf16 v[4:7], v[122:125], v[188:191], v[16:19]
	v_mfma_f32_16x16x32_bf16 v[230:233], v[126:129], v[202:205], v[4:7]
	v_mfma_f32_16x16x32_bf16 v[4:7], v[164:167], v[188:191], v[20:23]
	v_mfma_f32_16x16x32_bf16 v[164:167], v[168:171], v[202:205], v[4:7]
	s_setprio 0
	s_barrier
	ds_read_b128 v[16:19], v234
	ds_read_b128 v[60:63], v234 offset:1024
	ds_read_b128 v[168:171], v234 offset:2048
	ds_read_b128 v[188:191], v234 offset:3072
	ds_read_b128 v[202:205], v242
	ds_read_b128 v[234:237], v242 offset:1024
	ds_read_b128 v[238:241], v242 offset:2048
	ds_read_b128 v[242:245], v242 offset:3072
	s_add_u32 s4, s4, 0x10000
	s_addc_u32 s5, s5, 0
	s_mov_b32 m0, s36
	v_lshl_add_u64 v[44:45], s[4:5], 0, v[134:135]
	ds_read_b128 v[4:7], v143 offset:32768
	ds_read_b128 v[12:15], v143 offset:33792
	ds_read_b128 v[20:23], v143 offset:34816
	ds_read_b128 v[28:31], v143 offset:35840
	ds_read_b128 v[102:105], v143 offset:36864
	ds_read_b128 v[106:109], v143 offset:37888
	ds_read_b128 v[114:117], v143 offset:38912
	ds_read_b128 v[198:201], v143 offset:39936
	global_load_lds_dwordx4 v[44:45], off
	v_lshl_add_u64 v[44:45], s[4:5], 0, v[132:133]
	s_mov_b32 m0, s37
	s_nop 0
	global_load_lds_dwordx4 v[44:45], off
	s_waitcnt vmcnt(8)
	s_waitcnt lgkmcnt(0)
	s_barrier
	s_setprio 1
	s_waitcnt lgkmcnt(0)
	v_mfma_f32_16x16x32_bf16 v[44:47], v[16:19], v[4:7], v[64:67]
	v_mfma_f32_16x16x32_bf16 v[126:129], v[60:63], v[12:15], v[44:47]
	v_mfma_f32_16x16x32_bf16 v[44:47], v[168:171], v[4:7], v[68:71]
	v_mfma_f32_16x16x32_bf16 v[122:125], v[188:191], v[12:15], v[44:47]
	v_mfma_f32_16x16x32_bf16 v[44:47], v[16:19], v[20:23], v[72:75]
	v_mfma_f32_16x16x32_bf16 v[118:121], v[60:63], v[28:31], v[44:47]
	v_mfma_f32_16x16x32_bf16 v[44:47], v[168:171], v[20:23], v[76:79]
	v_mfma_f32_16x16x32_bf16 v[110:113], v[188:191], v[28:31], v[44:47]
	v_mfma_f32_16x16x32_bf16 v[44:47], v[16:19], v[102:105], v[80:83]
	v_mfma_f32_16x16x32_bf16 v[98:101], v[60:63], v[106:109], v[44:47]
	v_mfma_f32_16x16x32_bf16 v[44:47], v[168:171], v[102:105], v[84:87]
	v_mfma_f32_16x16x32_bf16 v[88:91], v[188:191], v[106:109], v[44:47]
	v_mfma_f32_16x16x32_bf16 v[44:47], v[16:19], v[114:117], v[214:217]
	v_mfma_f32_16x16x32_bf16 v[76:79], v[60:63], v[198:201], v[44:47]
	v_mfma_f32_16x16x32_bf16 v[44:47], v[168:171], v[114:117], v[92:95]
	v_mfma_f32_16x16x32_bf16 v[72:75], v[188:191], v[198:201], v[44:47]
	v_mfma_f32_16x16x32_bf16 v[44:47], v[202:205], v[4:7], v[218:221]
	v_mfma_f32_16x16x32_bf16 v[4:7], v[238:241], v[4:7], v[32:35]
	v_mfma_f32_16x16x32_bf16 v[48:51], v[242:245], v[12:15], v[4:7]
	v_mfma_f32_16x16x32_bf16 v[4:7], v[202:205], v[20:23], v[36:39]
	v_mfma_f32_16x16x32_bf16 v[56:59], v[234:237], v[12:15], v[44:47]
	v_mfma_f32_16x16x32_bf16 v[44:47], v[234:237], v[28:31], v[4:7]
	v_mfma_f32_16x16x32_bf16 v[4:7], v[238:241], v[20:23], v[40:43]
	v_mfma_f32_16x16x32_bf16 v[36:39], v[242:245], v[28:31], v[4:7]
	v_mfma_f32_16x16x32_bf16 v[4:7], v[202:205], v[102:105], v[172:175]
	v_mfma_f32_16x16x32_bf16 v[28:31], v[234:237], v[106:109], v[4:7]
	v_mfma_f32_16x16x32_bf16 v[4:7], v[238:241], v[102:105], v[176:179]
	v_mfma_f32_16x16x32_bf16 v[20:23], v[242:245], v[106:109], v[4:7]
	v_mfma_f32_16x16x32_bf16 v[4:7], v[202:205], v[114:117], v[52:55]
	v_mfma_f32_16x16x32_bf16 v[12:15], v[234:237], v[198:201], v[4:7]
	v_mfma_f32_16x16x32_bf16 v[4:7], v[238:241], v[114:117], v[180:183]
	v_mfma_f32_16x16x32_bf16 v[4:7], v[242:245], v[198:201], v[4:7]
	s_setprio 0
	s_barrier
	s_mov_b32 m0, s48
	v_lshl_add_u64 v[52:53], v[192:193], 0, s[64:65]
	s_add_u32 s4, s18, 0x50080
	ds_read_b128 v[32:35], v143 offset:49152
	ds_read_b128 v[40:43], v143 offset:50176
	ds_read_b128 v[172:175], v143 offset:51200
	ds_read_b128 v[176:179], v143 offset:52224
	ds_read_b128 v[180:183], v143 offset:53248
	ds_read_b128 v[198:201], v143 offset:54272
	ds_read_b128 v[214:217], v143 offset:55296
	ds_read_b128 v[218:221], v143 offset:56320
	global_load_lds_dwordx4 v[52:53], off
	v_lshl_add_u64 v[52:53], v[194:195], 0, s[64:65]
	s_mov_b32 m0, s46
	s_addc_u32 s5, s19, 0
	global_load_lds_dwordx4 v[52:53], off
	v_lshl_add_u64 v[52:53], s[4:5], 0, v[96:97]
	s_mov_b32 m0, s26
	s_nop 0
	global_load_lds_dwordx4 v[52:53], off
	v_lshl_add_u64 v[52:53], s[4:5], 0, v[130:131]
	s_mov_b32 m0, s27
	s_nop 0
	global_load_lds_dwordx4 v[52:53], off
	v_lshl_add_u64 v[52:53], v[196:197], 0, s[64:65]
	s_mov_b32 m0, s38
	s_nop 0
	global_load_lds_dwordx4 v[52:53], off
	v_lshl_add_u64 v[52:53], v[246:247], 0, s[64:65]
	s_mov_b32 m0, s39
	s_nop 0
	global_load_lds_dwordx4 v[52:53], off
	s_waitcnt vmcnt(8)
	s_waitcnt lgkmcnt(0)
	s_barrier
	s_setprio 1
	s_waitcnt lgkmcnt(0)
	v_mfma_f32_16x16x32_bf16 v[52:55], v[16:19], v[32:35], v[136:139]
	v_mfma_f32_16x16x32_bf16 v[114:117], v[60:63], v[40:43], v[52:55]
	v_mfma_f32_16x16x32_bf16 v[52:55], v[168:171], v[32:35], v[144:147]
	v_mfma_f32_16x16x32_bf16 v[106:109], v[188:191], v[40:43], v[52:55]
	v_mfma_f32_16x16x32_bf16 v[52:55], v[16:19], v[172:175], v[148:151]
	v_mfma_f32_16x16x32_bf16 v[102:105], v[60:63], v[176:179], v[52:55]
	v_mfma_f32_16x16x32_bf16 v[52:55], v[168:171], v[172:175], v[152:155]
	v_mfma_f32_16x16x32_bf16 v[92:95], v[188:191], v[176:179], v[52:55]
	v_mfma_f32_16x16x32_bf16 v[52:55], v[16:19], v[180:183], v[156:159]
	v_mfma_f32_16x16x32_bf16 v[0:3], v[16:19], v[214:217], v[0:3]
	v_mfma_f32_16x16x32_bf16 v[84:87], v[60:63], v[198:201], v[52:55]
	v_mfma_f32_16x16x32_bf16 v[52:55], v[168:171], v[180:183], v[160:163]
	v_mfma_f32_16x16x32_bf16 v[68:71], v[60:63], v[218:221], v[0:3]
	v_mfma_f32_16x16x32_bf16 v[0:3], v[168:171], v[214:217], v[206:209]
	v_mfma_f32_16x16x32_bf16 v[80:83], v[188:191], v[198:201], v[52:55]
	v_mfma_f32_16x16x32_bf16 v[64:67], v[188:191], v[218:221], v[0:3]
	v_mfma_f32_16x16x32_bf16 v[0:3], v[202:205], v[32:35], v[8:11]
	v_mfma_f32_16x16x32_bf16 v[60:63], v[234:237], v[40:43], v[0:3]
	v_mfma_f32_16x16x32_bf16 v[0:3], v[238:241], v[32:35], v[210:213]
	v_mfma_f32_16x16x32_bf16 v[52:55], v[242:245], v[40:43], v[0:3]
	v_mfma_f32_16x16x32_bf16 v[0:3], v[202:205], v[172:175], v[24:27]
	v_mfma_f32_16x16x32_bf16 v[40:43], v[234:237], v[176:179], v[0:3]
	v_mfma_f32_16x16x32_bf16 v[0:3], v[238:241], v[172:175], v[222:225]
	v_mfma_f32_16x16x32_bf16 v[32:35], v[242:245], v[176:179], v[0:3]
	v_mfma_f32_16x16x32_bf16 v[0:3], v[202:205], v[180:183], v[226:229]
	v_mfma_f32_16x16x32_bf16 v[24:27], v[234:237], v[198:201], v[0:3]
	v_mfma_f32_16x16x32_bf16 v[0:3], v[238:241], v[180:183], v[184:187]
	v_mfma_f32_16x16x32_bf16 v[16:19], v[242:245], v[198:201], v[0:3]
	v_mfma_f32_16x16x32_bf16 v[0:3], v[202:205], v[214:217], v[230:233]
	v_mfma_f32_16x16x32_bf16 v[8:11], v[234:237], v[218:221], v[0:3]
	v_mfma_f32_16x16x32_bf16 v[0:3], v[238:241], v[214:217], v[164:167]
	v_mfma_f32_16x16x32_bf16 v[0:3], v[242:245], v[218:221], v[0:3]
	s_setprio 0
	s_barrier
	s_andn2_b64 vcc, exec, s[12:13]
	s_cbranch_vccnz .LBB0_910
	s_barrier

.LBB0_1236:
	s_ashr_i32 s17, s16, 31
	s_lshl_b64 s[18:19], s[16:17], 19
	s_add_u32 s18, s35, s18
	s_addc_u32 s19, s36, s19
	s_and_b64 s[20:21], s[4:5], exec
	s_cselect_b32 s17, s19, s27
	s_cselect_b32 s23, s18, s26
	s_ashr_i32 s15, s14, 31
	s_lshl_b64 s[20:21], s[14:15], 19
	s_add_u32 s20, s37, s20
	s_addc_u32 s21, s38, s21
	s_and_b64 s[30:31], s[4:5], exec
	s_cselect_b32 s15, s21, s29
	s_cselect_b32 s25, s20, s28
	s_add_u32 s26, s26, 0x40080
	s_addc_u32 s27, s27, 0
	s_add_u32 s49, s28, 0x100
	s_addc_u32 s50, s29, 0
	s_mov_b32 s51, -2
	s_waitcnt vmcnt(0)
	s_add_u32 s28, s26, 0xfffc0080
	s_addc_u32 s29, s27, -1
	s_add_i32 s52, 0, 0x10000
	s_cmp_eq_u32 s51, 12
	s_cselect_b32 s31, s17, s29
	s_cselect_b32 s30, s23, s28
	s_cselect_b32 s29, s15, s50
	s_cselect_b32 s28, s25, s49
	s_add_i32 s54, 0, 0x14000
	v_add_u32_e32 v134, s52, v245
	v_add_u32_e32 v150, s54, v245
	ds_read_b128 v[122:125], v134
	ds_read_b128 v[126:129], v134 offset:1024
	ds_read_b128 v[130:133], v134 offset:2048
	ds_read_b128 v[134:137], v134 offset:3072
	ds_read_b128 v[138:141], v150
	ds_read_b128 v[142:145], v150 offset:1024
	ds_read_b128 v[146:149], v150 offset:2048
	ds_read_b128 v[150:153], v150 offset:3072
	v_lshl_add_u64 v[194:195], s[26:27], 0, v[204:205]
	s_add_i32 m0, s40, 0xc000
	ds_read_b128 v[162:165], v199
	ds_read_b128 v[166:169], v199 offset:1024
	ds_read_b128 v[170:173], v199 offset:2048
	ds_read_b128 v[174:177], v199 offset:3072
	ds_read_b128 v[178:181], v199 offset:4096
	ds_read_b128 v[182:185], v199 offset:5120
	ds_read_b128 v[186:189], v199 offset:6144
	ds_read_b128 v[208:211], v199 offset:7168
	global_load_lds_dwordx4 v[194:195], off
	v_lshl_add_u64 v[194:195], s[26:27], 0, v[206:207]
	s_add_i32 m0, s40, 0xe000
	s_nop 0
	global_load_lds_dwordx4 v[194:195], off
	s_waitcnt vmcnt(8)
	s_waitcnt lgkmcnt(0)
	s_barrier
	s_setprio 1
	s_waitcnt lgkmcnt(0)
	v_mfma_f32_16x16x32_bf16 v[158:161], v[122:125], v[162:165], 0
	v_mfma_f32_16x16x32_bf16 v[154:157], v[130:133], v[162:165], 0
	v_mfma_f32_16x16x32_bf16 v[110:113], v[122:125], v[170:173], 0
	v_mfma_f32_16x16x32_bf16 v[106:109], v[130:133], v[170:173], 0
	v_mfma_f32_16x16x32_bf16 v[92:95], v[122:125], v[178:181], 0
	v_mfma_f32_16x16x32_bf16 v[88:91], v[130:133], v[178:181], 0
	v_mfma_f32_16x16x32_bf16 v[76:79], v[122:125], v[186:189], 0
	v_mfma_f32_16x16x32_bf16 v[72:75], v[130:133], v[186:189], 0
	v_mfma_f32_16x16x32_bf16 v[158:161], v[126:129], v[166:169], v[158:161]
	v_mfma_f32_16x16x32_bf16 v[154:157], v[134:137], v[166:169], v[154:157]
	v_mfma_f32_16x16x32_bf16 v[110:113], v[126:129], v[174:177], v[110:113]
	v_mfma_f32_16x16x32_bf16 v[106:109], v[134:137], v[174:177], v[106:109]
	v_mfma_f32_16x16x32_bf16 v[92:95], v[126:129], v[182:185], v[92:95]
	v_mfma_f32_16x16x32_bf16 v[88:91], v[134:137], v[182:185], v[88:91]
	v_mfma_f32_16x16x32_bf16 v[76:79], v[126:129], v[208:211], v[76:79]
	v_mfma_f32_16x16x32_bf16 v[72:75], v[134:137], v[208:211], v[72:75]
	v_mfma_f32_16x16x32_bf16 v[118:121], v[138:141], v[162:165], 0
	v_mfma_f32_16x16x32_bf16 v[114:117], v[146:149], v[162:165], 0
	v_mfma_f32_16x16x32_bf16 v[102:105], v[138:141], v[170:173], 0
	v_mfma_f32_16x16x32_bf16 v[98:101], v[146:149], v[170:173], 0
	v_mfma_f32_16x16x32_bf16 v[84:87], v[138:141], v[178:181], 0
	v_mfma_f32_16x16x32_bf16 v[80:83], v[146:149], v[178:181], 0
	v_mfma_f32_16x16x32_bf16 v[68:71], v[138:141], v[186:189], 0
	v_mfma_f32_16x16x32_bf16 v[64:67], v[146:149], v[186:189], 0
	v_mfma_f32_16x16x32_bf16 v[118:121], v[142:145], v[166:169], v[118:121]
	v_mfma_f32_16x16x32_bf16 v[114:117], v[150:153], v[166:169], v[114:117]
	v_mfma_f32_16x16x32_bf16 v[102:105], v[142:145], v[174:177], v[102:105]
	v_mfma_f32_16x16x32_bf16 v[98:101], v[150:153], v[174:177], v[98:101]
	v_mfma_f32_16x16x32_bf16 v[84:87], v[142:145], v[182:185], v[84:87]
	v_mfma_f32_16x16x32_bf16 v[80:83], v[150:153], v[182:185], v[80:83]
	v_mfma_f32_16x16x32_bf16 v[68:71], v[142:145], v[208:211], v[68:71]
	v_mfma_f32_16x16x32_bf16 v[64:67], v[150:153], v[208:211], v[64:67]
	s_setprio 0
	s_barrier
	s_add_i32 s52, s52, s39
	v_lshl_add_u64 v[194:195], s[28:29], 0, v[96:97]
	s_mov_b32 m0, s52
	ds_read_b128 v[162:165], v199 offset:16384
	ds_read_b128 v[166:169], v199 offset:17408
	ds_read_b128 v[170:173], v199 offset:18432
	ds_read_b128 v[174:177], v199 offset:19456
	ds_read_b128 v[178:181], v199 offset:20480
	ds_read_b128 v[182:185], v199 offset:21504
	ds_read_b128 v[186:189], v199 offset:22528
	ds_read_b128 v[208:211], v199 offset:23552
	global_load_lds_dwordx4 v[194:195], off
	s_add_i32 m0, s52, 0x2000
	s_add_u32 s52, s28, 0x40000
	v_lshl_add_u64 v[196:197], s[28:29], 0, v[202:203]
	s_addc_u32 s53, s29, 0
	s_add_i32 s54, s54, s39
	global_load_lds_dwordx4 v[196:197], off
	v_lshl_add_u64 v[200:201], s[52:53], 0, v[96:97]
	s_mov_b32 m0, s54
	v_lshl_add_u64 v[212:213], s[30:31], 0, v[192:193]
	global_load_lds_dwordx4 v[200:201], off
	v_lshl_add_u64 v[200:201], s[52:53], 0, v[202:203]
	s_add_i32 m0, s54, 0x2000
	s_nop 0
	global_load_lds_dwordx4 v[200:201], off
	v_lshl_add_u64 v[200:201], s[30:31], 0, v[190:191]
	s_mov_b32 m0, s40
	s_nop 0
	global_load_lds_dwordx4 v[200:201], off
	s_mov_b32 m0, s41
	s_nop 0
	global_load_lds_dwordx4 v[212:213], off
	s_waitcnt vmcnt(8)
	s_waitcnt lgkmcnt(0)
	s_barrier
	s_setprio 1
	s_waitcnt lgkmcnt(0)
	v_mfma_f32_16x16x32_bf16 v[60:63], v[122:125], v[162:165], 0
	v_mfma_f32_16x16x32_bf16 v[56:59], v[130:133], v[162:165], 0
	v_mfma_f32_16x16x32_bf16 v[44:47], v[122:125], v[170:173], 0
	v_mfma_f32_16x16x32_bf16 v[40:43], v[130:133], v[170:173], 0
	v_mfma_f32_16x16x32_bf16 v[28:31], v[122:125], v[178:181], 0
	v_mfma_f32_16x16x32_bf16 v[24:27], v[130:133], v[178:181], 0
	v_mfma_f32_16x16x32_bf16 v[12:15], v[122:125], v[186:189], 0
	v_mfma_f32_16x16x32_bf16 v[8:11], v[130:133], v[186:189], 0
	v_mfma_f32_16x16x32_bf16 v[60:63], v[126:129], v[166:169], v[60:63]
	v_mfma_f32_16x16x32_bf16 v[56:59], v[134:137], v[166:169], v[56:59]
	v_mfma_f32_16x16x32_bf16 v[44:47], v[126:129], v[174:177], v[44:47]
	v_mfma_f32_16x16x32_bf16 v[40:43], v[134:137], v[174:177], v[40:43]
	v_mfma_f32_16x16x32_bf16 v[28:31], v[126:129], v[182:185], v[28:31]
	v_mfma_f32_16x16x32_bf16 v[24:27], v[134:137], v[182:185], v[24:27]
	v_mfma_f32_16x16x32_bf16 v[12:15], v[126:129], v[208:211], v[12:15]
	v_mfma_f32_16x16x32_bf16 v[8:11], v[134:137], v[208:211], v[8:11]
	v_mfma_f32_16x16x32_bf16 v[52:55], v[138:141], v[162:165], 0
	v_mfma_f32_16x16x32_bf16 v[48:51], v[146:149], v[162:165], 0
	v_mfma_f32_16x16x32_bf16 v[36:39], v[138:141], v[170:173], 0
	v_mfma_f32_16x16x32_bf16 v[32:35], v[146:149], v[170:173], 0
	v_mfma_f32_16x16x32_bf16 v[20:23], v[138:141], v[178:181], 0
	v_mfma_f32_16x16x32_bf16 v[16:19], v[146:149], v[178:181], 0
	v_mfma_f32_16x16x32_bf16 v[4:7], v[138:141], v[186:189], 0
	v_mfma_f32_16x16x32_bf16 v[0:3], v[146:149], v[186:189], 0
	v_mfma_f32_16x16x32_bf16 v[52:55], v[142:145], v[166:169], v[52:55]
	v_mfma_f32_16x16x32_bf16 v[48:51], v[150:153], v[166:169], v[48:51]
	v_mfma_f32_16x16x32_bf16 v[36:39], v[142:145], v[174:177], v[36:39]
	v_mfma_f32_16x16x32_bf16 v[32:35], v[150:153], v[174:177], v[32:35]
	v_mfma_f32_16x16x32_bf16 v[20:23], v[142:145], v[182:185], v[20:23]
	v_mfma_f32_16x16x32_bf16 v[16:19], v[150:153], v[182:185], v[16:19]
	v_mfma_f32_16x16x32_bf16 v[4:7], v[142:145], v[208:211], v[4:7]
	v_mfma_f32_16x16x32_bf16 v[0:3], v[150:153], v[208:211], v[0:3]
	s_setprio 0
	s_barrier
	s_add_i32 s52, 0, 0x18000
	s_add_i32 s53, 0, 0x1c000
	v_add_u32_e32 v134, s52, v245
	v_add_u32_e32 v150, s53, v245
	ds_read_b128 v[122:125], v134
	ds_read_b128 v[126:129], v134 offset:1024
	ds_read_b128 v[130:133], v134 offset:2048
	ds_read_b128 v[134:137], v134 offset:3072
	ds_read_b128 v[138:141], v150
	ds_read_b128 v[142:145], v150 offset:1024
	ds_read_b128 v[146:149], v150 offset:2048
	ds_read_b128 v[150:153], v150 offset:3072
	s_add_u32 s30, s30, 0x40000
	s_addc_u32 s31, s31, 0
	s_mov_b32 m0, s42
	v_lshl_add_u64 v[214:215], s[30:31], 0, v[190:191]
	ds_read_b128 v[162:165], v199 offset:32768
	ds_read_b128 v[166:169], v199 offset:33792
	ds_read_b128 v[170:173], v199 offset:34816
	ds_read_b128 v[174:177], v199 offset:35840
	ds_read_b128 v[178:181], v199 offset:36864
	ds_read_b128 v[182:185], v199 offset:37888
	ds_read_b128 v[186:189], v199 offset:38912
	ds_read_b128 v[208:211], v199 offset:39936
	global_load_lds_dwordx4 v[214:215], off
	v_lshl_add_u64 v[214:215], s[30:31], 0, v[192:193]
	s_mov_b32 m0, s43
	s_nop 0
	global_load_lds_dwordx4 v[214:215], off
	s_waitcnt vmcnt(8)
	s_waitcnt lgkmcnt(0)
	s_barrier
	s_setprio 1
	s_waitcnt lgkmcnt(0)
	v_mfma_f32_16x16x32_bf16 v[158:161], v[122:125], v[162:165], v[158:161]
	v_mfma_f32_16x16x32_bf16 v[154:157], v[130:133], v[162:165], v[154:157]
	v_mfma_f32_16x16x32_bf16 v[110:113], v[122:125], v[170:173], v[110:113]
	v_mfma_f32_16x16x32_bf16 v[106:109], v[130:133], v[170:173], v[106:109]
	v_mfma_f32_16x16x32_bf16 v[92:95], v[122:125], v[178:181], v[92:95]
	v_mfma_f32_16x16x32_bf16 v[88:91], v[130:133], v[178:181], v[88:91]
	v_mfma_f32_16x16x32_bf16 v[76:79], v[122:125], v[186:189], v[76:79]
	v_mfma_f32_16x16x32_bf16 v[72:75], v[130:133], v[186:189], v[72:75]
	v_mfma_f32_16x16x32_bf16 v[158:161], v[126:129], v[166:169], v[158:161]
	v_mfma_f32_16x16x32_bf16 v[154:157], v[134:137], v[166:169], v[154:157]
	v_mfma_f32_16x16x32_bf16 v[110:113], v[126:129], v[174:177], v[110:113]
	v_mfma_f32_16x16x32_bf16 v[106:109], v[134:137], v[174:177], v[106:109]
	v_mfma_f32_16x16x32_bf16 v[92:95], v[126:129], v[182:185], v[92:95]
	v_mfma_f32_16x16x32_bf16 v[88:91], v[134:137], v[182:185], v[88:91]
	v_mfma_f32_16x16x32_bf16 v[76:79], v[126:129], v[208:211], v[76:79]
	v_mfma_f32_16x16x32_bf16 v[72:75], v[134:137], v[208:211], v[72:75]
	v_mfma_f32_16x16x32_bf16 v[118:121], v[138:141], v[162:165], v[118:121]
	v_mfma_f32_16x16x32_bf16 v[114:117], v[146:149], v[162:165], v[114:117]
	v_mfma_f32_16x16x32_bf16 v[102:105], v[138:141], v[170:173], v[102:105]
	v_mfma_f32_16x16x32_bf16 v[98:101], v[146:149], v[170:173], v[98:101]
	v_mfma_f32_16x16x32_bf16 v[84:87], v[138:141], v[178:181], v[84:87]
	v_mfma_f32_16x16x32_bf16 v[80:83], v[146:149], v[178:181], v[80:83]
	v_mfma_f32_16x16x32_bf16 v[68:71], v[138:141], v[186:189], v[68:71]
	v_mfma_f32_16x16x32_bf16 v[64:67], v[146:149], v[186:189], v[64:67]
	v_mfma_f32_16x16x32_bf16 v[118:121], v[142:145], v[166:169], v[118:121]
	v_mfma_f32_16x16x32_bf16 v[114:117], v[150:153], v[166:169], v[114:117]
	v_mfma_f32_16x16x32_bf16 v[102:105], v[142:145], v[174:177], v[102:105]
	v_mfma_f32_16x16x32_bf16 v[98:101], v[150:153], v[174:177], v[98:101]
	v_mfma_f32_16x16x32_bf16 v[84:87], v[142:145], v[182:185], v[84:87]
	v_mfma_f32_16x16x32_bf16 v[80:83], v[150:153], v[182:185], v[80:83]
	v_mfma_f32_16x16x32_bf16 v[68:71], v[142:145], v[208:211], v[68:71]
	v_mfma_f32_16x16x32_bf16 v[64:67], v[150:153], v[208:211], v[64:67]
	s_setprio 0
	s_barrier
	s_add_i32 s30, s52, s39
	v_lshl_add_u64 v[194:195], v[194:195], 0, s[64:65]
	s_mov_b32 m0, s30
	ds_read_b128 v[162:165], v199 offset:49152
	ds_read_b128 v[166:169], v199 offset:50176
	ds_read_b128 v[170:173], v199 offset:51200
	ds_read_b128 v[174:177], v199 offset:52224
	ds_read_b128 v[178:181], v199 offset:53248
	ds_read_b128 v[182:185], v199 offset:54272
	ds_read_b128 v[186:189], v199 offset:55296
	ds_read_b128 v[208:211], v199 offset:56320
	global_load_lds_dwordx4 v[194:195], off
	s_add_i32 m0, s30, 0x2000
	s_add_u32 s28, s28, 0x40080
	v_lshl_add_u64 v[194:195], v[196:197], 0, s[64:65]
	s_addc_u32 s29, s29, 0
	s_add_i32 s30, s53, s39
	global_load_lds_dwordx4 v[194:195], off
	v_lshl_add_u64 v[194:195], s[28:29], 0, v[96:97]
	s_mov_b32 m0, s30
	s_nop 0
	global_load_lds_dwordx4 v[194:195], off
	v_lshl_add_u64 v[194:195], s[28:29], 0, v[202:203]
	s_add_i32 m0, s30, 0x2000
	s_nop 0
	global_load_lds_dwordx4 v[194:195], off
	v_lshl_add_u64 v[194:195], v[200:201], 0, s[64:65]
	s_mov_b32 m0, s45
	s_nop 0
	global_load_lds_dwordx4 v[194:195], off
	v_lshl_add_u64 v[194:195], v[212:213], 0, s[64:65]
	s_mov_b32 m0, s46
	s_nop 0
	global_load_lds_dwordx4 v[194:195], off
	s_waitcnt vmcnt(8)
	s_waitcnt lgkmcnt(0)
	s_barrier
	s_setprio 1
	s_waitcnt lgkmcnt(0)
	v_mfma_f32_16x16x32_bf16 v[60:63], v[122:125], v[162:165], v[60:63]
	v_mfma_f32_16x16x32_bf16 v[56:59], v[130:133], v[162:165], v[56:59]
	v_mfma_f32_16x16x32_bf16 v[44:47], v[122:125], v[170:173], v[44:47]
	v_mfma_f32_16x16x32_bf16 v[40:43], v[130:133], v[170:173], v[40:43]
	v_mfma_f32_16x16x32_bf16 v[28:31], v[122:125], v[178:181], v[28:31]
	v_mfma_f32_16x16x32_bf16 v[24:27], v[130:133], v[178:181], v[24:27]
	v_mfma_f32_16x16x32_bf16 v[12:15], v[122:125], v[186:189], v[12:15]
	v_mfma_f32_16x16x32_bf16 v[8:11], v[130:133], v[186:189], v[8:11]
	v_mfma_f32_16x16x32_bf16 v[60:63], v[126:129], v[166:169], v[60:63]
	v_mfma_f32_16x16x32_bf16 v[56:59], v[134:137], v[166:169], v[56:59]
	v_mfma_f32_16x16x32_bf16 v[44:47], v[126:129], v[174:177], v[44:47]
	v_mfma_f32_16x16x32_bf16 v[40:43], v[134:137], v[174:177], v[40:43]
	v_mfma_f32_16x16x32_bf16 v[28:31], v[126:129], v[182:185], v[28:31]
	v_mfma_f32_16x16x32_bf16 v[24:27], v[134:137], v[182:185], v[24:27]
	v_mfma_f32_16x16x32_bf16 v[12:15], v[126:129], v[208:211], v[12:15]
	v_mfma_f32_16x16x32_bf16 v[8:11], v[134:137], v[208:211], v[8:11]
	v_mfma_f32_16x16x32_bf16 v[52:55], v[138:141], v[162:165], v[52:55]
	v_mfma_f32_16x16x32_bf16 v[48:51], v[146:149], v[162:165], v[48:51]
	v_mfma_f32_16x16x32_bf16 v[36:39], v[138:141], v[170:173], v[36:39]
	v_mfma_f32_16x16x32_bf16 v[32:35], v[146:149], v[170:173], v[32:35]
	v_mfma_f32_16x16x32_bf16 v[20:23], v[138:141], v[178:181], v[20:23]
	v_mfma_f32_16x16x32_bf16 v[16:19], v[146:149], v[178:181], v[16:19]
	v_mfma_f32_16x16x32_bf16 v[4:7], v[138:141], v[186:189], v[4:7]
	v_mfma_f32_16x16x32_bf16 v[0:3], v[146:149], v[186:189], v[0:3]
	v_mfma_f32_16x16x32_bf16 v[52:55], v[142:145], v[166:169], v[52:55]
	v_mfma_f32_16x16x32_bf16 v[48:51], v[150:153], v[166:169], v[48:51]
	v_mfma_f32_16x16x32_bf16 v[36:39], v[142:145], v[174:177], v[36:39]
	v_mfma_f32_16x16x32_bf16 v[32:35], v[150:153], v[174:177], v[32:35]
	v_mfma_f32_16x16x32_bf16 v[20:23], v[142:145], v[182:185], v[20:23]
	v_mfma_f32_16x16x32_bf16 v[16:19], v[150:153], v[182:185], v[16:19]
	v_mfma_f32_16x16x32_bf16 v[4:7], v[142:145], v[208:211], v[4:7]
	v_mfma_f32_16x16x32_bf16 v[0:3], v[150:153], v[208:211], v[0:3]
	s_setprio 0
	s_barrier
	s_add_i32 s51, s51, 2
	s_add_u32 s26, s26, 0x100
	s_addc_u32 s27, s27, 0
	s_add_u32 s49, s49, 0x100
	s_addc_u32 s50, s50, 0
	s_cmp_gt_u32 s51, 13
	s_cbranch_scc1 .Lpeel_done_1237
.LBB0_1237:
	s_add_u32 s28, s26, 0xfffc0080
	s_addc_u32 s29, s27, -1
	s_add_i32 s52, 0, 0x10000
	s_cmp_eq_u32 s51, 12
	s_cselect_b32 s31, s17, s29
	s_cselect_b32 s30, s23, s28
	s_cselect_b32 s29, s15, s50
	s_cselect_b32 s28, s25, s49
	s_add_i32 s54, 0, 0x14000
	v_add_u32_e32 v134, s52, v245
	v_add_u32_e32 v150, s54, v245
	ds_read_b128 v[122:125], v134
	ds_read_b128 v[126:129], v134 offset:1024
	ds_read_b128 v[130:133], v134 offset:2048
	ds_read_b128 v[134:137], v134 offset:3072
	ds_read_b128 v[138:141], v150
	ds_read_b128 v[142:145], v150 offset:1024
	ds_read_b128 v[146:149], v150 offset:2048
	ds_read_b128 v[150:153], v150 offset:3072
	v_lshl_add_u64 v[194:195], s[26:27], 0, v[204:205]
	s_add_i32 m0, s40, 0xc000
	ds_read_b128 v[162:165], v199
	ds_read_b128 v[166:169], v199 offset:1024
	ds_read_b128 v[170:173], v199 offset:2048
	ds_read_b128 v[174:177], v199 offset:3072
	ds_read_b128 v[178:181], v199 offset:4096
	ds_read_b128 v[182:185], v199 offset:5120
	ds_read_b128 v[186:189], v199 offset:6144
	ds_read_b128 v[208:211], v199 offset:7168
	global_load_lds_dwordx4 v[194:195], off
	v_lshl_add_u64 v[194:195], s[26:27], 0, v[206:207]
	s_add_i32 m0, s40, 0xe000
	s_nop 0
	global_load_lds_dwordx4 v[194:195], off
	s_waitcnt vmcnt(8)
	s_waitcnt lgkmcnt(0)
	s_barrier
	s_setprio 1
	s_waitcnt lgkmcnt(0)
	v_mfma_f32_16x16x32_bf16 v[158:161], v[122:125], v[162:165], v[158:161]
	v_mfma_f32_16x16x32_bf16 v[154:157], v[130:133], v[162:165], v[154:157]
	v_mfma_f32_16x16x32_bf16 v[110:113], v[122:125], v[170:173], v[110:113]
	v_mfma_f32_16x16x32_bf16 v[106:109], v[130:133], v[170:173], v[106:109]
	v_mfma_f32_16x16x32_bf16 v[92:95], v[122:125], v[178:181], v[92:95]
	v_mfma_f32_16x16x32_bf16 v[88:91], v[130:133], v[178:181], v[88:91]
	v_mfma_f32_16x16x32_bf16 v[76:79], v[122:125], v[186:189], v[76:79]
	v_mfma_f32_16x16x32_bf16 v[72:75], v[130:133], v[186:189], v[72:75]
	v_mfma_f32_16x16x32_bf16 v[158:161], v[126:129], v[166:169], v[158:161]
	v_mfma_f32_16x16x32_bf16 v[154:157], v[134:137], v[166:169], v[154:157]
	v_mfma_f32_16x16x32_bf16 v[110:113], v[126:129], v[174:177], v[110:113]
	v_mfma_f32_16x16x32_bf16 v[106:109], v[134:137], v[174:177], v[106:109]
	v_mfma_f32_16x16x32_bf16 v[92:95], v[126:129], v[182:185], v[92:95]
	v_mfma_f32_16x16x32_bf16 v[88:91], v[134:137], v[182:185], v[88:91]
	v_mfma_f32_16x16x32_bf16 v[76:79], v[126:129], v[208:211], v[76:79]
	v_mfma_f32_16x16x32_bf16 v[72:75], v[134:137], v[208:211], v[72:75]
	v_mfma_f32_16x16x32_bf16 v[118:121], v[138:141], v[162:165], v[118:121]
	v_mfma_f32_16x16x32_bf16 v[114:117], v[146:149], v[162:165], v[114:117]
	v_mfma_f32_16x16x32_bf16 v[102:105], v[138:141], v[170:173], v[102:105]
	v_mfma_f32_16x16x32_bf16 v[98:101], v[146:149], v[170:173], v[98:101]
	v_mfma_f32_16x16x32_bf16 v[84:87], v[138:141], v[178:181], v[84:87]
	v_mfma_f32_16x16x32_bf16 v[80:83], v[146:149], v[178:181], v[80:83]
	v_mfma_f32_16x16x32_bf16 v[68:71], v[138:141], v[186:189], v[68:71]
	v_mfma_f32_16x16x32_bf16 v[64:67], v[146:149], v[186:189], v[64:67]
	v_mfma_f32_16x16x32_bf16 v[118:121], v[142:145], v[166:169], v[118:121]
	v_mfma_f32_16x16x32_bf16 v[114:117], v[150:153], v[166:169], v[114:117]
	v_mfma_f32_16x16x32_bf16 v[102:105], v[142:145], v[174:177], v[102:105]
	v_mfma_f32_16x16x32_bf16 v[98:101], v[150:153], v[174:177], v[98:101]
	v_mfma_f32_16x16x32_bf16 v[84:87], v[142:145], v[182:185], v[84:87]
	v_mfma_f32_16x16x32_bf16 v[80:83], v[150:153], v[182:185], v[80:83]
	v_mfma_f32_16x16x32_bf16 v[68:71], v[142:145], v[208:211], v[68:71]
	v_mfma_f32_16x16x32_bf16 v[64:67], v[150:153], v[208:211], v[64:67]
	s_setprio 0
	s_barrier
	s_add_i32 s52, s52, s39
	v_lshl_add_u64 v[194:195], s[28:29], 0, v[96:97]
	s_mov_b32 m0, s52
	ds_read_b128 v[162:165], v199 offset:16384
	ds_read_b128 v[166:169], v199 offset:17408
	ds_read_b128 v[170:173], v199 offset:18432
	ds_read_b128 v[174:177], v199 offset:19456
	ds_read_b128 v[178:181], v199 offset:20480
	ds_read_b128 v[182:185], v199 offset:21504
	ds_read_b128 v[186:189], v199 offset:22528
	ds_read_b128 v[208:211], v199 offset:23552
	global_load_lds_dwordx4 v[194:195], off
	s_add_i32 m0, s52, 0x2000
	s_add_u32 s52, s28, 0x40000
	v_lshl_add_u64 v[196:197], s[28:29], 0, v[202:203]
	s_addc_u32 s53, s29, 0
	s_add_i32 s54, s54, s39
	global_load_lds_dwordx4 v[196:197], off
	v_lshl_add_u64 v[200:201], s[52:53], 0, v[96:97]
	s_mov_b32 m0, s54
	v_lshl_add_u64 v[212:213], s[30:31], 0, v[192:193]
	global_load_lds_dwordx4 v[200:201], off
	v_lshl_add_u64 v[200:201], s[52:53], 0, v[202:203]
	s_add_i32 m0, s54, 0x2000
	s_nop 0
	global_load_lds_dwordx4 v[200:201], off
	v_lshl_add_u64 v[200:201], s[30:31], 0, v[190:191]
	s_mov_b32 m0, s40
	s_nop 0
	global_load_lds_dwordx4 v[200:201], off
	s_mov_b32 m0, s41
	s_nop 0
	global_load_lds_dwordx4 v[212:213], off
	s_waitcnt vmcnt(8)
	s_waitcnt lgkmcnt(0)
	s_barrier
	s_setprio 1
	s_waitcnt lgkmcnt(0)
	v_mfma_f32_16x16x32_bf16 v[60:63], v[122:125], v[162:165], v[60:63]
	v_mfma_f32_16x16x32_bf16 v[56:59], v[130:133], v[162:165], v[56:59]
	v_mfma_f32_16x16x32_bf16 v[44:47], v[122:125], v[170:173], v[44:47]
	v_mfma_f32_16x16x32_bf16 v[40:43], v[130:133], v[170:173], v[40:43]
	v_mfma_f32_16x16x32_bf16 v[28:31], v[122:125], v[178:181], v[28:31]
	v_mfma_f32_16x16x32_bf16 v[24:27], v[130:133], v[178:181], v[24:27]
	v_mfma_f32_16x16x32_bf16 v[12:15], v[122:125], v[186:189], v[12:15]
	v_mfma_f32_16x16x32_bf16 v[8:11], v[130:133], v[186:189], v[8:11]
	v_mfma_f32_16x16x32_bf16 v[60:63], v[126:129], v[166:169], v[60:63]
	v_mfma_f32_16x16x32_bf16 v[56:59], v[134:137], v[166:169], v[56:59]
	v_mfma_f32_16x16x32_bf16 v[44:47], v[126:129], v[174:177], v[44:47]
	v_mfma_f32_16x16x32_bf16 v[40:43], v[134:137], v[174:177], v[40:43]
	v_mfma_f32_16x16x32_bf16 v[28:31], v[126:129], v[182:185], v[28:31]
	v_mfma_f32_16x16x32_bf16 v[24:27], v[134:137], v[182:185], v[24:27]
	v_mfma_f32_16x16x32_bf16 v[12:15], v[126:129], v[208:211], v[12:15]
	v_mfma_f32_16x16x32_bf16 v[8:11], v[134:137], v[208:211], v[8:11]
	v_mfma_f32_16x16x32_bf16 v[52:55], v[138:141], v[162:165], v[52:55]
	v_mfma_f32_16x16x32_bf16 v[48:51], v[146:149], v[162:165], v[48:51]
	v_mfma_f32_16x16x32_bf16 v[36:39], v[138:141], v[170:173], v[36:39]
	v_mfma_f32_16x16x32_bf16 v[32:35], v[146:149], v[170:173], v[32:35]
	v_mfma_f32_16x16x32_bf16 v[20:23], v[138:141], v[178:181], v[20:23]
	v_mfma_f32_16x16x32_bf16 v[16:19], v[146:149], v[178:181], v[16:19]
	v_mfma_f32_16x16x32_bf16 v[4:7], v[138:141], v[186:189], v[4:7]
	v_mfma_f32_16x16x32_bf16 v[0:3], v[146:149], v[186:189], v[0:3]
	v_mfma_f32_16x16x32_bf16 v[52:55], v[142:145], v[166:169], v[52:55]
	v_mfma_f32_16x16x32_bf16 v[48:51], v[150:153], v[166:169], v[48:51]
	v_mfma_f32_16x16x32_bf16 v[36:39], v[142:145], v[174:177], v[36:39]
	v_mfma_f32_16x16x32_bf16 v[32:35], v[150:153], v[174:177], v[32:35]
	v_mfma_f32_16x16x32_bf16 v[20:23], v[142:145], v[182:185], v[20:23]
	v_mfma_f32_16x16x32_bf16 v[16:19], v[150:153], v[182:185], v[16:19]
	v_mfma_f32_16x16x32_bf16 v[4:7], v[142:145], v[208:211], v[4:7]
	v_mfma_f32_16x16x32_bf16 v[0:3], v[150:153], v[208:211], v[0:3]
	s_setprio 0
	s_barrier
	s_add_i32 s52, 0, 0x18000
	s_add_i32 s53, 0, 0x1c000
	v_add_u32_e32 v134, s52, v245
	v_add_u32_e32 v150, s53, v245
	ds_read_b128 v[122:125], v134
	ds_read_b128 v[126:129], v134 offset:1024
	ds_read_b128 v[130:133], v134 offset:2048
	ds_read_b128 v[134:137], v134 offset:3072
	ds_read_b128 v[138:141], v150
	ds_read_b128 v[142:145], v150 offset:1024
	ds_read_b128 v[146:149], v150 offset:2048
	ds_read_b128 v[150:153], v150 offset:3072
	s_add_u32 s30, s30, 0x40000
	s_addc_u32 s31, s31, 0
	s_mov_b32 m0, s42
	v_lshl_add_u64 v[214:215], s[30:31], 0, v[190:191]
	ds_read_b128 v[162:165], v199 offset:32768
	ds_read_b128 v[166:169], v199 offset:33792
	ds_read_b128 v[170:173], v199 offset:34816
	ds_read_b128 v[174:177], v199 offset:35840
	ds_read_b128 v[178:181], v199 offset:36864
	ds_read_b128 v[182:185], v199 offset:37888
	ds_read_b128 v[186:189], v199 offset:38912
	ds_read_b128 v[208:211], v199 offset:39936
	global_load_lds_dwordx4 v[214:215], off
	v_lshl_add_u64 v[214:215], s[30:31], 0, v[192:193]
	s_mov_b32 m0, s43
	s_nop 0
	global_load_lds_dwordx4 v[214:215], off
	s_waitcnt vmcnt(8)
	s_waitcnt lgkmcnt(0)
	s_barrier
	s_setprio 1
	s_waitcnt lgkmcnt(0)
	v_mfma_f32_16x16x32_bf16 v[158:161], v[122:125], v[162:165], v[158:161]
	v_mfma_f32_16x16x32_bf16 v[154:157], v[130:133], v[162:165], v[154:157]
	v_mfma_f32_16x16x32_bf16 v[110:113], v[122:125], v[170:173], v[110:113]
	v_mfma_f32_16x16x32_bf16 v[106:109], v[130:133], v[170:173], v[106:109]
	v_mfma_f32_16x16x32_bf16 v[92:95], v[122:125], v[178:181], v[92:95]
	v_mfma_f32_16x16x32_bf16 v[88:91], v[130:133], v[178:181], v[88:91]
	v_mfma_f32_16x16x32_bf16 v[76:79], v[122:125], v[186:189], v[76:79]
	v_mfma_f32_16x16x32_bf16 v[72:75], v[130:133], v[186:189], v[72:75]
	v_mfma_f32_16x16x32_bf16 v[158:161], v[126:129], v[166:169], v[158:161]
	v_mfma_f32_16x16x32_bf16 v[154:157], v[134:137], v[166:169], v[154:157]
	v_mfma_f32_16x16x32_bf16 v[110:113], v[126:129], v[174:177], v[110:113]
	v_mfma_f32_16x16x32_bf16 v[106:109], v[134:137], v[174:177], v[106:109]
	v_mfma_f32_16x16x32_bf16 v[92:95], v[126:129], v[182:185], v[92:95]
	v_mfma_f32_16x16x32_bf16 v[88:91], v[134:137], v[182:185], v[88:91]
	v_mfma_f32_16x16x32_bf16 v[76:79], v[126:129], v[208:211], v[76:79]
	v_mfma_f32_16x16x32_bf16 v[72:75], v[134:137], v[208:211], v[72:75]
	v_mfma_f32_16x16x32_bf16 v[118:121], v[138:141], v[162:165], v[118:121]
	v_mfma_f32_16x16x32_bf16 v[114:117], v[146:149], v[162:165], v[114:117]
	v_mfma_f32_16x16x32_bf16 v[102:105], v[138:141], v[170:173], v[102:105]
	v_mfma_f32_16x16x32_bf16 v[98:101], v[146:149], v[170:173], v[98:101]
	v_mfma_f32_16x16x32_bf16 v[84:87], v[138:141], v[178:181], v[84:87]
	v_mfma_f32_16x16x32_bf16 v[80:83], v[146:149], v[178:181], v[80:83]
	v_mfma_f32_16x16x32_bf16 v[68:71], v[138:141], v[186:189], v[68:71]
	v_mfma_f32_16x16x32_bf16 v[64:67], v[146:149], v[186:189], v[64:67]
	v_mfma_f32_16x16x32_bf16 v[118:121], v[142:145], v[166:169], v[118:121]
	v_mfma_f32_16x16x32_bf16 v[114:117], v[150:153], v[166:169], v[114:117]
	v_mfma_f32_16x16x32_bf16 v[102:105], v[142:145], v[174:177], v[102:105]
	v_mfma_f32_16x16x32_bf16 v[98:101], v[150:153], v[174:177], v[98:101]
	v_mfma_f32_16x16x32_bf16 v[84:87], v[142:145], v[182:185], v[84:87]
	v_mfma_f32_16x16x32_bf16 v[80:83], v[150:153], v[182:185], v[80:83]
	v_mfma_f32_16x16x32_bf16 v[68:71], v[142:145], v[208:211], v[68:71]
	v_mfma_f32_16x16x32_bf16 v[64:67], v[150:153], v[208:211], v[64:67]
	s_setprio 0
	s_barrier
	s_add_i32 s30, s52, s39
	v_lshl_add_u64 v[194:195], v[194:195], 0, s[64:65]
	s_mov_b32 m0, s30
	ds_read_b128 v[162:165], v199 offset:49152
	ds_read_b128 v[166:169], v199 offset:50176
	ds_read_b128 v[170:173], v199 offset:51200
	ds_read_b128 v[174:177], v199 offset:52224
	ds_read_b128 v[178:181], v199 offset:53248
	ds_read_b128 v[182:185], v199 offset:54272
	ds_read_b128 v[186:189], v199 offset:55296
	ds_read_b128 v[208:211], v199 offset:56320
	global_load_lds_dwordx4 v[194:195], off
	s_add_i32 m0, s30, 0x2000
	s_add_u32 s28, s28, 0x40080
	v_lshl_add_u64 v[194:195], v[196:197], 0, s[64:65]
	s_addc_u32 s29, s29, 0
	s_add_i32 s30, s53, s39
	global_load_lds_dwordx4 v[194:195], off
	v_lshl_add_u64 v[194:195], s[28:29], 0, v[96:97]
	s_mov_b32 m0, s30
	s_nop 0
	global_load_lds_dwordx4 v[194:195], off
	v_lshl_add_u64 v[194:195], s[28:29], 0, v[202:203]
	s_add_i32 m0, s30, 0x2000
	s_nop 0
	global_load_lds_dwordx4 v[194:195], off
	v_lshl_add_u64 v[194:195], v[200:201], 0, s[64:65]
	s_mov_b32 m0, s45
	s_nop 0
	global_load_lds_dwordx4 v[194:195], off
	v_lshl_add_u64 v[194:195], v[212:213], 0, s[64:65]
	s_mov_b32 m0, s46
	s_nop 0
	global_load_lds_dwordx4 v[194:195], off
	s_waitcnt vmcnt(8)
	s_waitcnt lgkmcnt(0)
	s_barrier
	s_setprio 1
	s_waitcnt lgkmcnt(0)
	v_mfma_f32_16x16x32_bf16 v[60:63], v[122:125], v[162:165], v[60:63]
	v_mfma_f32_16x16x32_bf16 v[56:59], v[130:133], v[162:165], v[56:59]
	v_mfma_f32_16x16x32_bf16 v[44:47], v[122:125], v[170:173], v[44:47]
	v_mfma_f32_16x16x32_bf16 v[40:43], v[130:133], v[170:173], v[40:43]
	v_mfma_f32_16x16x32_bf16 v[28:31], v[122:125], v[178:181], v[28:31]
	v_mfma_f32_16x16x32_bf16 v[24:27], v[130:133], v[178:181], v[24:27]
	v_mfma_f32_16x16x32_bf16 v[12:15], v[122:125], v[186:189], v[12:15]
	v_mfma_f32_16x16x32_bf16 v[8:11], v[130:133], v[186:189], v[8:11]
	v_mfma_f32_16x16x32_bf16 v[60:63], v[126:129], v[166:169], v[60:63]
	v_mfma_f32_16x16x32_bf16 v[56:59], v[134:137], v[166:169], v[56:59]
	v_mfma_f32_16x16x32_bf16 v[44:47], v[126:129], v[174:177], v[44:47]
	v_mfma_f32_16x16x32_bf16 v[40:43], v[134:137], v[174:177], v[40:43]
	v_mfma_f32_16x16x32_bf16 v[28:31], v[126:129], v[182:185], v[28:31]
	v_mfma_f32_16x16x32_bf16 v[24:27], v[134:137], v[182:185], v[24:27]
	v_mfma_f32_16x16x32_bf16 v[12:15], v[126:129], v[208:211], v[12:15]
	v_mfma_f32_16x16x32_bf16 v[8:11], v[134:137], v[208:211], v[8:11]
	v_mfma_f32_16x16x32_bf16 v[52:55], v[138:141], v[162:165], v[52:55]
	v_mfma_f32_16x16x32_bf16 v[48:51], v[146:149], v[162:165], v[48:51]
	v_mfma_f32_16x16x32_bf16 v[36:39], v[138:141], v[170:173], v[36:39]
	v_mfma_f32_16x16x32_bf16 v[32:35], v[146:149], v[170:173], v[32:35]
	v_mfma_f32_16x16x32_bf16 v[20:23], v[138:141], v[178:181], v[20:23]
	v_mfma_f32_16x16x32_bf16 v[16:19], v[146:149], v[178:181], v[16:19]
	v_mfma_f32_16x16x32_bf16 v[4:7], v[138:141], v[186:189], v[4:7]
	v_mfma_f32_16x16x32_bf16 v[0:3], v[146:149], v[186:189], v[0:3]
	v_mfma_f32_16x16x32_bf16 v[52:55], v[142:145], v[166:169], v[52:55]
	v_mfma_f32_16x16x32_bf16 v[48:51], v[150:153], v[166:169], v[48:51]
	v_mfma_f32_16x16x32_bf16 v[36:39], v[142:145], v[174:177], v[36:39]
	v_mfma_f32_16x16x32_bf16 v[32:35], v[150:153], v[174:177], v[32:35]
	v_mfma_f32_16x16x32_bf16 v[20:23], v[142:145], v[182:185], v[20:23]
	v_mfma_f32_16x16x32_bf16 v[16:19], v[150:153], v[182:185], v[16:19]
	v_mfma_f32_16x16x32_bf16 v[4:7], v[142:145], v[208:211], v[4:7]
	v_mfma_f32_16x16x32_bf16 v[0:3], v[150:153], v[208:211], v[0:3]
	s_setprio 0
	s_barrier
	s_add_i32 s51, s51, 2
	s_add_u32 s26, s26, 0x100
	s_addc_u32 s27, s27, 0
	s_add_u32 s49, s49, 0x100
	s_addc_u32 s50, s50, 0
	s_cmp_gt_u32 s51, 13
	s_cbranch_scc0 .LBB0_1237
